# gdb solve hand-scheduled (LDS prefetch, readlane rhs scaling), rwa quotas 5/10/16, rwc scanner hand-scheduled 32-step blocks with vv b128
# speedup vs baseline: 1.0468x; 1.0468x over previous
; __device__ __forceinline__ void phase_gdb(const int wvs, const Params& p, LAS unsigned char* lds, int nwg) {
;     ...
;     { float x[64]; const bool isw = t >= 64;
; #pragma unroll
;       for (int i = 0; i < 64; ++i) { const float v = (float)R[i * RP + t]; x[i] = v * bs[i] * (isw ? __expf(gcs[i]) : 1.0f); asm volatile("" : "+v"(x[i])); if ((i & 7) == 7) __builtin_amdgcn_sched_barrier(0); }
.LBB0_899:
	s_waitcnt lgkmcnt(0)
	s_barrier
	v_and_b32_e32 v252, 63, v224
	v_lshl_add_u32 v252, v252, 2, v228
	ds_read_b32 v242, v252 offset:34048
	ds_read_b32 v243, v252 offset:34304
	ds_read_u16 v64, v232 offset:16384
	ds_read_u16 v65, v232 offset:16656
	ds_read_u16 v66, v232 offset:16928
	ds_read_u16 v67, v232 offset:17200
	ds_read_u16 v68, v232 offset:17472
	ds_read_u16 v69, v232 offset:17744
	ds_read_u16 v70, v232 offset:18016
	ds_read_u16 v71, v232 offset:18288
	ds_read_u16 v72, v232 offset:18560
	ds_read_u16 v73, v232 offset:18832
	ds_read_u16 v74, v232 offset:19104
	ds_read_u16 v75, v232 offset:19376
	s_waitcnt lgkmcnt(12)
	v_mul_f32_e32 v243, 0x3fb8aa3b, v243
	v_exp_f32_e32 v243, v243
	s_nop 0
	v_cndmask_b32_e64 v243, 1.0, v243, s[4:5]
	v_readlane_b32 s8, v242, 0
	v_readlane_b32 s9, v243, 0
	v_readlane_b32 s18, v242, 1
	v_readlane_b32 s19, v243, 1
	v_readlane_b32 s20, v242, 2
	v_readlane_b32 s21, v243, 2
	v_readlane_b32 s22, v242, 3
	v_readlane_b32 s23, v243, 3
	s_waitcnt lgkmcnt(11)
	v_cvt_f32_f16_e32 v64, v64
	s_waitcnt lgkmcnt(10)
	v_cvt_f32_f16_e32 v65, v65
	s_waitcnt lgkmcnt(9)
	v_cvt_f32_f16_e32 v66, v66
	s_waitcnt lgkmcnt(8)
	v_cvt_f32_f16_e32 v67, v67
	v_mul_f32_e32 v64, s8, v64
	v_mul_f32_e32 v64, s9, v64
	v_mul_f32_e32 v65, s18, v65
	v_mul_f32_e32 v65, s19, v65
	v_mul_f32_e32 v66, s20, v66
	v_mul_f32_e32 v66, s21, v66
	v_mul_f32_e32 v67, s22, v67
	v_mul_f32_e32 v67, s23, v67
	ds_read_u16 v76, v232 offset:19648
	ds_read_u16 v77, v232 offset:19920
	ds_read_u16 v78, v232 offset:20192
	ds_read_u16 v79, v232 offset:20464
	v_readlane_b32 s8, v242, 4
	v_readlane_b32 s9, v243, 4
	v_readlane_b32 s18, v242, 5
	v_readlane_b32 s19, v243, 5
	v_readlane_b32 s20, v242, 6
	v_readlane_b32 s21, v243, 6
	v_readlane_b32 s22, v242, 7
	v_readlane_b32 s23, v243, 7
	s_waitcnt lgkmcnt(11)
	v_cvt_f32_f16_e32 v68, v68
	s_waitcnt lgkmcnt(10)
	v_cvt_f32_f16_e32 v69, v69
	s_waitcnt lgkmcnt(9)
	v_cvt_f32_f16_e32 v70, v70
	s_waitcnt lgkmcnt(8)
	v_cvt_f32_f16_e32 v71, v71
	v_mul_f32_e32 v68, s8, v68
	v_mul_f32_e32 v68, s9, v68
	v_mul_f32_e32 v69, s18, v69
	v_mul_f32_e32 v69, s19, v69
	v_mul_f32_e32 v70, s20, v70
	v_mul_f32_e32 v70, s21, v70
	v_mul_f32_e32 v71, s22, v71
	v_mul_f32_e32 v71, s23, v71
	ds_read_u16 v80, v232 offset:20736
	ds_read_u16 v81, v232 offset:21008
	ds_read_u16 v82, v232 offset:21280
	ds_read_u16 v83, v232 offset:21552
	v_readlane_b32 s8, v242, 8
	v_readlane_b32 s9, v243, 8
	v_readlane_b32 s18, v242, 9
	v_readlane_b32 s19, v243, 9
	v_readlane_b32 s20, v242, 10
	v_readlane_b32 s21, v243, 10
	v_readlane_b32 s22, v242, 11
	v_readlane_b32 s23, v243, 11
	s_waitcnt lgkmcnt(11)
	v_cvt_f32_f16_e32 v72, v72
	s_waitcnt lgkmcnt(10)
	v_cvt_f32_f16_e32 v73, v73
	s_waitcnt lgkmcnt(9)
	v_cvt_f32_f16_e32 v74, v74
	s_waitcnt lgkmcnt(8)
	v_cvt_f32_f16_e32 v75, v75
	v_mul_f32_e32 v72, s8, v72
	v_mul_f32_e32 v72, s9, v72
	v_mul_f32_e32 v73, s18, v73
	v_mul_f32_e32 v73, s19, v73
	v_mul_f32_e32 v74, s20, v74
	v_mul_f32_e32 v74, s21, v74
	v_mul_f32_e32 v75, s22, v75
	v_mul_f32_e32 v75, s23, v75
	ds_read_u16 v84, v232 offset:21824
	ds_read_u16 v85, v232 offset:22096
	ds_read_u16 v86, v232 offset:22368
	ds_read_u16 v87, v232 offset:22640
	v_readlane_b32 s8, v242, 12
	v_readlane_b32 s9, v243, 12
	v_readlane_b32 s18, v242, 13
	v_readlane_b32 s19, v243, 13
	v_readlane_b32 s20, v242, 14
	v_readlane_b32 s21, v243, 14
	v_readlane_b32 s22, v242, 15
	v_readlane_b32 s23, v243, 15
	s_waitcnt lgkmcnt(11)
	v_cvt_f32_f16_e32 v76, v76
	s_waitcnt lgkmcnt(10)
	v_cvt_f32_f16_e32 v77, v77
	s_waitcnt lgkmcnt(9)
	v_cvt_f32_f16_e32 v78, v78
	s_waitcnt lgkmcnt(8)
	v_cvt_f32_f16_e32 v79, v79
	v_mul_f32_e32 v76, s8, v76
	v_mul_f32_e32 v76, s9, v76
	v_mul_f32_e32 v77, s18, v77
	v_mul_f32_e32 v77, s19, v77
	v_mul_f32_e32 v78, s20, v78
	v_mul_f32_e32 v78, s21, v78
	v_mul_f32_e32 v79, s22, v79
	v_mul_f32_e32 v79, s23, v79
	ds_read_u16 v88, v232 offset:22912
	ds_read_u16 v89, v232 offset:23184
	ds_read_u16 v90, v232 offset:23456
	ds_read_u16 v91, v232 offset:23728
	v_readlane_b32 s8, v242, 16
	v_readlane_b32 s9, v243, 16
	v_readlane_b32 s18, v242, 17
	v_readlane_b32 s19, v243, 17
	v_readlane_b32 s20, v242, 18
	v_readlane_b32 s21, v243, 18
	v_readlane_b32 s22, v242, 19
	v_readlane_b32 s23, v243, 19
	s_waitcnt lgkmcnt(11)
	v_cvt_f32_f16_e32 v80, v80
	s_waitcnt lgkmcnt(10)
	v_cvt_f32_f16_e32 v81, v81
	s_waitcnt lgkmcnt(9)
	v_cvt_f32_f16_e32 v82, v82
	s_waitcnt lgkmcnt(8)
	v_cvt_f32_f16_e32 v83, v83
	v_mul_f32_e32 v80, s8, v80
	v_mul_f32_e32 v80, s9, v80
	v_mul_f32_e32 v81, s18, v81
	v_mul_f32_e32 v81, s19, v81
	v_mul_f32_e32 v82, s20, v82
	v_mul_f32_e32 v82, s21, v82
	v_mul_f32_e32 v83, s22, v83
	v_mul_f32_e32 v83, s23, v83
	ds_read_u16 v92, v232 offset:24000
	ds_read_u16 v93, v232 offset:24272
	ds_read_u16 v94, v232 offset:24544
	ds_read_u16 v95, v232 offset:24816
	v_readlane_b32 s8, v242, 20
	v_readlane_b32 s9, v243, 20
	v_readlane_b32 s18, v242, 21
	v_readlane_b32 s19, v243, 21
	v_readlane_b32 s20, v242, 22
	v_readlane_b32 s21, v243, 22
	v_readlane_b32 s22, v242, 23
	v_readlane_b32 s23, v243, 23
	s_waitcnt lgkmcnt(11)
	v_cvt_f32_f16_e32 v84, v84
	s_waitcnt lgkmcnt(10)
	v_cvt_f32_f16_e32 v85, v85
	s_waitcnt lgkmcnt(9)
	v_cvt_f32_f16_e32 v86, v86
	s_waitcnt lgkmcnt(8)
	v_cvt_f32_f16_e32 v87, v87
	v_mul_f32_e32 v84, s8, v84
	v_mul_f32_e32 v84, s9, v84
	v_mul_f32_e32 v85, s18, v85
	v_mul_f32_e32 v85, s19, v85
	v_mul_f32_e32 v86, s20, v86
	v_mul_f32_e32 v86, s21, v86
	v_mul_f32_e32 v87, s22, v87
	v_mul_f32_e32 v87, s23, v87
	ds_read_u16 v96, v232 offset:25088
	ds_read_u16 v97, v232 offset:25360
	ds_read_u16 v98, v232 offset:25632
	ds_read_u16 v99, v232 offset:25904
	v_readlane_b32 s8, v242, 24
	v_readlane_b32 s9, v243, 24
	v_readlane_b32 s18, v242, 25
	v_readlane_b32 s19, v243, 25
	v_readlane_b32 s20, v242, 26
	v_readlane_b32 s21, v243, 26
	v_readlane_b32 s22, v242, 27
	v_readlane_b32 s23, v243, 27
	s_waitcnt lgkmcnt(11)
; __device__ __forceinline__ void phase_gdb(const int wvs, const Params& p, LAS unsigned char* lds, int nwg) {
;     ...
;     { float x[64]; const bool isw = t >= 64;
; #pragma unroll
;       for (int i = 0; i < 64; ++i) { const float v = (float)R[i * RP + t]; x[i] = v * bs[i] * (isw ? __expf(gcs[i]) : 1.0f); asm volatile("" : "+v"(x[i])); if ((i & 7) == 7) __builtin_amdgcn_sched_barrier(0); }
	v_cvt_f32_f16_e32 v88, v88
	s_waitcnt lgkmcnt(10)
	v_cvt_f32_f16_e32 v89, v89
	s_waitcnt lgkmcnt(9)
	v_cvt_f32_f16_e32 v90, v90
	s_waitcnt lgkmcnt(8)
	v_cvt_f32_f16_e32 v91, v91
	v_mul_f32_e32 v88, s8, v88
	v_mul_f32_e32 v88, s9, v88
	v_mul_f32_e32 v89, s18, v89
	v_mul_f32_e32 v89, s19, v89
	v_mul_f32_e32 v90, s20, v90
	v_mul_f32_e32 v90, s21, v90
	v_mul_f32_e32 v91, s22, v91
	v_mul_f32_e32 v91, s23, v91
	ds_read_u16 v100, v232 offset:26176
	ds_read_u16 v101, v232 offset:26448
	ds_read_u16 v102, v232 offset:26720
	ds_read_u16 v103, v232 offset:26992
	v_readlane_b32 s8, v242, 28
	v_readlane_b32 s9, v243, 28
	v_readlane_b32 s18, v242, 29
	v_readlane_b32 s19, v243, 29
	v_readlane_b32 s20, v242, 30
	v_readlane_b32 s21, v243, 30
	v_readlane_b32 s22, v242, 31
	v_readlane_b32 s23, v243, 31
	s_waitcnt lgkmcnt(11)
	v_cvt_f32_f16_e32 v92, v92
	s_waitcnt lgkmcnt(10)
	v_cvt_f32_f16_e32 v93, v93
	s_waitcnt lgkmcnt(9)
	v_cvt_f32_f16_e32 v94, v94
	s_waitcnt lgkmcnt(8)
	v_cvt_f32_f16_e32 v95, v95
	v_mul_f32_e32 v92, s8, v92
	v_mul_f32_e32 v92, s9, v92
	v_mul_f32_e32 v93, s18, v93
	v_mul_f32_e32 v93, s19, v93
	v_mul_f32_e32 v94, s20, v94
	v_mul_f32_e32 v94, s21, v94
	v_mul_f32_e32 v95, s22, v95
	v_mul_f32_e32 v95, s23, v95
	ds_read_u16 v104, v232 offset:27264
	ds_read_u16 v105, v232 offset:27536
	ds_read_u16 v106, v232 offset:27808
	ds_read_u16 v107, v232 offset:28080
	v_readlane_b32 s8, v242, 32
	v_readlane_b32 s9, v243, 32
	v_readlane_b32 s18, v242, 33
	v_readlane_b32 s19, v243, 33
	v_readlane_b32 s20, v242, 34
	v_readlane_b32 s21, v243, 34
	v_readlane_b32 s22, v242, 35
	v_readlane_b32 s23, v243, 35
	s_waitcnt lgkmcnt(11)
	v_cvt_f32_f16_e32 v96, v96
	s_waitcnt lgkmcnt(10)
	v_cvt_f32_f16_e32 v97, v97
	s_waitcnt lgkmcnt(9)
	v_cvt_f32_f16_e32 v98, v98
	s_waitcnt lgkmcnt(8)
	v_cvt_f32_f16_e32 v99, v99
	v_mul_f32_e32 v96, s8, v96
	v_mul_f32_e32 v96, s9, v96
	v_mul_f32_e32 v97, s18, v97
	v_mul_f32_e32 v97, s19, v97
	v_mul_f32_e32 v98, s20, v98
	v_mul_f32_e32 v98, s21, v98
	v_mul_f32_e32 v99, s22, v99
	v_mul_f32_e32 v99, s23, v99
	ds_read_u16 v108, v232 offset:28352
	ds_read_u16 v109, v232 offset:28624
	ds_read_u16 v110, v232 offset:28896
	ds_read_u16 v111, v232 offset:29168
	v_readlane_b32 s8, v242, 36
	v_readlane_b32 s9, v243, 36
	v_readlane_b32 s18, v242, 37
	v_readlane_b32 s19, v243, 37
	v_readlane_b32 s20, v242, 38
	v_readlane_b32 s21, v243, 38
	v_readlane_b32 s22, v242, 39
	v_readlane_b32 s23, v243, 39
	s_waitcnt lgkmcnt(11)
	v_cvt_f32_f16_e32 v100, v100
	s_waitcnt lgkmcnt(10)
	v_cvt_f32_f16_e32 v101, v101
	s_waitcnt lgkmcnt(9)
	v_cvt_f32_f16_e32 v102, v102
	s_waitcnt lgkmcnt(8)
	v_cvt_f32_f16_e32 v103, v103
	v_mul_f32_e32 v100, s8, v100
	v_mul_f32_e32 v100, s9, v100
	v_mul_f32_e32 v101, s18, v101
	v_mul_f32_e32 v101, s19, v101
	v_mul_f32_e32 v102, s20, v102
	v_mul_f32_e32 v102, s21, v102
	v_mul_f32_e32 v103, s22, v103
	v_mul_f32_e32 v103, s23, v103
	ds_read_u16 v112, v232 offset:29440
	ds_read_u16 v113, v232 offset:29712
	ds_read_u16 v114, v232 offset:29984
	ds_read_u16 v115, v232 offset:30256
	v_readlane_b32 s8, v242, 40
	v_readlane_b32 s9, v243, 40
	v_readlane_b32 s18, v242, 41
	v_readlane_b32 s19, v243, 41
	v_readlane_b32 s20, v242, 42
	v_readlane_b32 s21, v243, 42
	v_readlane_b32 s22, v242, 43
	v_readlane_b32 s23, v243, 43
	s_waitcnt lgkmcnt(11)
	v_cvt_f32_f16_e32 v104, v104
	s_waitcnt lgkmcnt(10)
	v_cvt_f32_f16_e32 v105, v105
	s_waitcnt lgkmcnt(9)
	v_cvt_f32_f16_e32 v106, v106
	s_waitcnt lgkmcnt(8)
	v_cvt_f32_f16_e32 v107, v107
	v_mul_f32_e32 v104, s8, v104
	v_mul_f32_e32 v104, s9, v104
	v_mul_f32_e32 v105, s18, v105
	v_mul_f32_e32 v105, s19, v105
	v_mul_f32_e32 v106, s20, v106
	v_mul_f32_e32 v106, s21, v106
	v_mul_f32_e32 v107, s22, v107
	v_mul_f32_e32 v107, s23, v107
	ds_read_u16 v116, v232 offset:30528
	ds_read_u16 v117, v232 offset:30800
	ds_read_u16 v118, v232 offset:31072
	ds_read_u16 v119, v232 offset:31344
	v_readlane_b32 s8, v242, 44
	v_readlane_b32 s9, v243, 44
	v_readlane_b32 s18, v242, 45
	v_readlane_b32 s19, v243, 45
	v_readlane_b32 s20, v242, 46
	v_readlane_b32 s21, v243, 46
	v_readlane_b32 s22, v242, 47
	v_readlane_b32 s23, v243, 47
	s_waitcnt lgkmcnt(11)
	v_cvt_f32_f16_e32 v108, v108
	s_waitcnt lgkmcnt(10)
	v_cvt_f32_f16_e32 v109, v109
	s_waitcnt lgkmcnt(9)
	v_cvt_f32_f16_e32 v110, v110
	s_waitcnt lgkmcnt(8)
	v_cvt_f32_f16_e32 v111, v111
	v_mul_f32_e32 v108, s8, v108
	v_mul_f32_e32 v108, s9, v108
	v_mul_f32_e32 v109, s18, v109
	v_mul_f32_e32 v109, s19, v109
	v_mul_f32_e32 v110, s20, v110
	v_mul_f32_e32 v110, s21, v110
	v_mul_f32_e32 v111, s22, v111
	v_mul_f32_e32 v111, s23, v111
	ds_read_u16 v120, v232 offset:31616
	ds_read_u16 v121, v232 offset:31888
	ds_read_u16 v122, v232 offset:32160
	ds_read_u16 v123, v232 offset:32432
	v_readlane_b32 s8, v242, 48
	v_readlane_b32 s9, v243, 48
	v_readlane_b32 s18, v242, 49
	v_readlane_b32 s19, v243, 49
	v_readlane_b32 s20, v242, 50
	v_readlane_b32 s21, v243, 50
	v_readlane_b32 s22, v242, 51
	v_readlane_b32 s23, v243, 51
	s_waitcnt lgkmcnt(11)
	v_cvt_f32_f16_e32 v112, v112
	s_waitcnt lgkmcnt(10)
	v_cvt_f32_f16_e32 v113, v113
	s_waitcnt lgkmcnt(9)
	v_cvt_f32_f16_e32 v114, v114
	s_waitcnt lgkmcnt(8)
	v_cvt_f32_f16_e32 v115, v115
	v_mul_f32_e32 v112, s8, v112
	v_mul_f32_e32 v112, s9, v112
	v_mul_f32_e32 v113, s18, v113
	v_mul_f32_e32 v113, s19, v113
	v_mul_f32_e32 v114, s20, v114
	v_mul_f32_e32 v114, s21, v114
	v_mul_f32_e32 v115, s22, v115
	v_mul_f32_e32 v115, s23, v115
	ds_read_u16 v124, v232 offset:32704
	ds_read_u16 v125, v232 offset:32976
	ds_read_u16 v126, v232 offset:33248
	ds_read_u16 v127, v232 offset:33520
	ds_read_b128 v[4:7], v228 offset:256
	ds_read_b128 v[8:11], v228 offset:512
	ds_read_b128 v[12:15], v228 offset:768
	s_waitcnt lgkmcnt(14)
; #define LAS __attribute__((address_space(3)))
; __device__ __forceinline__ void phase_gdb(const int wvs, const Params& p, LAS unsigned char* lds, int nwg) {
;     ...
;     { float x[64]; const bool isw = t >= 64;
; #pragma unroll
;       for (int i = 0; i < 64; ++i) { const float v = (float)R[i * RP + t]; x[i] = v * bs[i] * (isw ? __expf(gcs[i]) : 1.0f); asm volatile("" : "+v"(x[i])); if ((i & 7) == 7) __builtin_amdgcn_sched_barrier(0); }
; #pragma unroll
;       for (int i = 1; i < 64; ++i) {
; #pragma unroll
;         for (int j4 = 0; j4 < (i + 3) / 4; ++j4) { const f32x4 m4 = *(const LAS f32x4*)(M + i * 64 + j4 * 4);
; #pragma unroll
;           for (int jj = 0; jj < 4; ++jj) if (j4 * 4 + jj < i) x[i] -= m4[jj] * x[j4 * 4 + jj]; }
;         __builtin_amdgcn_sched_barrier(0); }
; #pragma unroll
;       for (int i = 0; i < 64; ++i) R[i * RP + t] = (hf)x[i]; }
	ds_read_b128 v[16:19], v228 offset:1024
	s_waitcnt lgkmcnt(14)
	ds_read_b128 v[20:23], v228 offset:1280
	s_waitcnt lgkmcnt(14)
	ds_read_b128 v[24:27], v228 offset:1296
	v_readlane_b32 s8, v242, 52
	v_readlane_b32 s9, v243, 52
	v_readlane_b32 s18, v242, 53
	v_readlane_b32 s19, v243, 53
	v_readlane_b32 s20, v242, 54
	v_readlane_b32 s21, v243, 54
	v_readlane_b32 s22, v242, 55
	v_readlane_b32 s23, v243, 55
	v_cvt_f32_f16_e32 v116, v116
	v_cvt_f32_f16_e32 v117, v117
	v_cvt_f32_f16_e32 v118, v118
	s_waitcnt lgkmcnt(14)
	v_cvt_f32_f16_e32 v119, v119
	v_mul_f32_e32 v116, s8, v116
	v_mul_f32_e32 v116, s9, v116
	v_mul_f32_e32 v117, s18, v117
	v_mul_f32_e32 v117, s19, v117
	v_mul_f32_e32 v118, s20, v118
	v_mul_f32_e32 v118, s21, v118
	v_mul_f32_e32 v119, s22, v119
	v_mul_f32_e32 v119, s23, v119
	v_readlane_b32 s8, v242, 56
	v_readlane_b32 s9, v243, 56
	v_readlane_b32 s18, v242, 57
	v_readlane_b32 s19, v243, 57
	v_readlane_b32 s20, v242, 58
	v_readlane_b32 s21, v243, 58
	v_readlane_b32 s22, v242, 59
	v_readlane_b32 s23, v243, 59
	s_waitcnt lgkmcnt(13)
	v_cvt_f32_f16_e32 v120, v120
	s_waitcnt lgkmcnt(12)
	v_cvt_f32_f16_e32 v121, v121
	s_waitcnt lgkmcnt(11)
	v_cvt_f32_f16_e32 v122, v122
	s_waitcnt lgkmcnt(10)
	v_cvt_f32_f16_e32 v123, v123
	v_mul_f32_e32 v120, s8, v120
	v_mul_f32_e32 v120, s9, v120
	v_mul_f32_e32 v121, s18, v121
	v_mul_f32_e32 v121, s19, v121
	v_mul_f32_e32 v122, s20, v122
	v_mul_f32_e32 v122, s21, v122
	v_mul_f32_e32 v123, s22, v123
	v_mul_f32_e32 v123, s23, v123
	v_readlane_b32 s8, v242, 60
	v_readlane_b32 s9, v243, 60
	v_readlane_b32 s18, v242, 61
	v_readlane_b32 s19, v243, 61
	v_readlane_b32 s20, v242, 62
	v_readlane_b32 s21, v243, 62
	v_readlane_b32 s22, v242, 63
	v_readlane_b32 s23, v243, 63
	s_waitcnt lgkmcnt(9)
	v_cvt_f32_f16_e32 v124, v124
	s_waitcnt lgkmcnt(8)
	v_cvt_f32_f16_e32 v125, v125
	s_waitcnt lgkmcnt(7)
	v_cvt_f32_f16_e32 v126, v126
	s_waitcnt lgkmcnt(6)
	v_cvt_f32_f16_e32 v127, v127
	v_mul_f32_e32 v124, s8, v124
	v_mul_f32_e32 v124, s9, v124
	v_mul_f32_e32 v125, s18, v125
	v_mul_f32_e32 v125, s19, v125
	v_mul_f32_e32 v126, s20, v126
	v_mul_f32_e32 v126, s21, v126
	v_mul_f32_e32 v127, s22, v127
	v_mul_f32_e32 v127, s23, v127
	v_cvt_f16_f32_e32 v0, v64
	ds_write_b16 v232, v0 offset:16384
	s_waitcnt lgkmcnt(6)
	v_fma_mixlo_f16 v2, -v64, v4, v65
	v_fma_f32 v65, -v64, v4, v65
	ds_write_b16 v232, v2 offset:16656
	ds_read_b128 v[28:31], v228 offset:1536
	ds_read_b128 v[32:35], v228 offset:1552
	s_waitcnt lgkmcnt(8)
	v_fma_f32 v66, -v64, v8, v66
	v_fma_mixlo_f16 v3, -v65, v9, v66
	v_fma_f32 v66, -v65, v9, v66
	ds_write_b16 v232, v3 offset:16928
	ds_read_b128 v[36:39], v228 offset:1792
	ds_read_b128 v[40:43], v228 offset:1808
	s_waitcnt lgkmcnt(10)
	v_fma_f32 v67, -v64, v12, v67
	v_fma_f32 v67, -v65, v13, v67
	v_fma_mixlo_f16 v238, -v66, v14, v67
	v_fma_f32 v67, -v66, v14, v67
	ds_write_b16 v232, v238 offset:17200
	ds_read_b128 v[44:47], v228 offset:2048
	ds_read_b128 v[48:51], v228 offset:2064
	s_waitcnt lgkmcnt(12)
	v_fma_f32 v68, -v64, v16, v68
	v_fma_f32 v68, -v65, v17, v68
	v_fma_f32 v68, -v66, v18, v68
	v_fma_mixlo_f16 v239, -v67, v19, v68
	v_fma_f32 v68, -v67, v19, v68
	ds_write_b16 v232, v239 offset:17472
	ds_read_b128 v[52:55], v228 offset:2304
	ds_read_b128 v[56:59], v228 offset:2320
	s_waitcnt lgkmcnt(14)
	ds_read_b128 v[60:63], v228 offset:2336
	s_waitcnt lgkmcnt(14)
	v_fma_f32 v69, -v64, v20, v69
	v_fma_f32 v69, -v65, v21, v69
	v_fma_f32 v69, -v66, v22, v69
	v_fma_f32 v69, -v67, v23, v69
	v_fma_mixlo_f16 v240, -v68, v24, v69
	v_fma_f32 v69, -v68, v24, v69
	ds_write_b16 v232, v240 offset:17744
	s_waitcnt lgkmcnt(14)
	ds_read_b128 v[128:131], v228 offset:2560
	s_waitcnt lgkmcnt(14)
	ds_read_b128 v[132:135], v228 offset:2576
	s_waitcnt lgkmcnt(14)
	ds_read_b128 v[136:139], v228 offset:2592
	s_waitcnt lgkmcnt(14)
	v_fma_f32 v70, -v64, v28, v70
	v_fma_f32 v70, -v65, v29, v70
	v_fma_f32 v70, -v66, v30, v70
	v_fma_f32 v70, -v67, v31, v70
	v_fma_f32 v70, -v68, v32, v70
	v_fma_mixlo_f16 v0, -v69, v33, v70
	v_fma_f32 v70, -v69, v33, v70
	ds_write_b16 v232, v0 offset:18016
	s_waitcnt lgkmcnt(14)
	ds_read_b128 v[140:143], v228 offset:2816
	s_waitcnt lgkmcnt(14)
	ds_read_b128 v[144:147], v228 offset:2832
	s_waitcnt lgkmcnt(14)
	ds_read_b128 v[148:151], v228 offset:2848
	v_fma_f32 v71, -v64, v36, v71
	v_fma_f32 v71, -v65, v37, v71
	v_fma_f32 v71, -v66, v38, v71
	v_fma_f32 v71, -v67, v39, v71
	v_fma_f32 v71, -v68, v40, v71
	v_fma_f32 v71, -v69, v41, v71
	v_fma_mixlo_f16 v2, -v70, v42, v71
	v_fma_f32 v71, -v70, v42, v71
	s_waitcnt lgkmcnt(14)
	ds_write_b16 v232, v2 offset:18288
	s_waitcnt lgkmcnt(14)
	ds_read_b128 v[152:155], v228 offset:3072
	s_waitcnt lgkmcnt(14)
	ds_read_b128 v[156:159], v228 offset:3088
	s_waitcnt lgkmcnt(14)
	ds_read_b128 v[160:163], v228 offset:3104
	v_fma_f32 v72, -v64, v44, v72
	v_fma_f32 v72, -v65, v45, v72
	v_fma_f32 v72, -v66, v46, v72
	v_fma_f32 v72, -v67, v47, v72
	v_fma_f32 v72, -v68, v48, v72
	v_fma_f32 v72, -v69, v49, v72
	v_fma_f32 v72, -v70, v50, v72
	v_fma_mixlo_f16 v3, -v71, v51, v72
	v_fma_f32 v72, -v71, v51, v72
	s_waitcnt lgkmcnt(14)
	ds_write_b16 v232, v3 offset:18560
	s_waitcnt lgkmcnt(14)
	ds_read_b128 v[164:167], v228 offset:3328
	s_waitcnt lgkmcnt(14)
	ds_read_b128 v[168:171], v228 offset:3344
	s_waitcnt lgkmcnt(14)
	ds_read_b128 v[172:175], v228 offset:3360
	s_waitcnt lgkmcnt(14)
	ds_read_b128 v[176:179], v228 offset:3376
	v_fma_f32 v73, -v64, v52, v73
	v_fma_f32 v73, -v65, v53, v73
	v_fma_f32 v73, -v66, v54, v73
	v_fma_f32 v73, -v67, v55, v73
	v_fma_f32 v73, -v68, v56, v73
	v_fma_f32 v73, -v69, v57, v73
	v_fma_f32 v73, -v70, v58, v73
	v_fma_f32 v73, -v71, v59, v73
	v_fma_mixlo_f16 v238, -v72, v60, v73
	v_fma_f32 v73, -v72, v60, v73
	s_waitcnt lgkmcnt(14)
; #define LAS __attribute__((address_space(3)))
; __device__ __forceinline__ void phase_gdb(const int wvs, const Params& p, LAS unsigned char* lds, int nwg) {
;     ...
;       for (int i = 1; i < 64; ++i) {
; #pragma unroll
;         for (int j4 = 0; j4 < (i + 3) / 4; ++j4) { const f32x4 m4 = *(const LAS f32x4*)(M + i * 64 + j4 * 4);
; #pragma unroll
;           for (int jj = 0; jj < 4; ++jj) if (j4 * 4 + jj < i) x[i] -= m4[jj] * x[j4 * 4 + jj]; }
;         __builtin_amdgcn_sched_barrier(0); }
; #pragma unroll
;       for (int i = 0; i < 64; ++i) R[i * RP + t] = (hf)x[i]; }
	ds_write_b16 v232, v238 offset:18832
	s_waitcnt lgkmcnt(14)
	ds_read_b128 v[180:183], v228 offset:3584
	s_waitcnt lgkmcnt(14)
	ds_read_b128 v[184:187], v228 offset:3600
	s_waitcnt lgkmcnt(14)
	ds_read_b128 v[188:191], v228 offset:3616
	s_waitcnt lgkmcnt(14)
	ds_read_b128 v[244:247], v228 offset:3632
	v_fma_f32 v74, -v64, v128, v74
	v_fma_f32 v74, -v65, v129, v74
	v_fma_f32 v74, -v66, v130, v74
	v_fma_f32 v74, -v67, v131, v74
	v_fma_f32 v74, -v68, v132, v74
	v_fma_f32 v74, -v69, v133, v74
	v_fma_f32 v74, -v70, v134, v74
	v_fma_f32 v74, -v71, v135, v74
	v_fma_f32 v74, -v72, v136, v74
	v_fma_mixlo_f16 v239, -v73, v137, v74
	v_fma_f32 v74, -v73, v137, v74
	s_waitcnt lgkmcnt(14)
	ds_write_b16 v232, v239 offset:19104
	s_waitcnt lgkmcnt(14)
	ds_read_b128 v[248:251], v228 offset:3840
	s_waitcnt lgkmcnt(14)
	ds_read_b128 v[4:7], v228 offset:3856
	s_waitcnt lgkmcnt(14)
	ds_read_b128 v[8:11], v228 offset:3872
	s_waitcnt lgkmcnt(14)
	ds_read_b128 v[12:15], v228 offset:3888
	v_fma_f32 v75, -v64, v140, v75
	v_fma_f32 v75, -v65, v141, v75
	v_fma_f32 v75, -v66, v142, v75
	v_fma_f32 v75, -v67, v143, v75
	v_fma_f32 v75, -v68, v144, v75
	v_fma_f32 v75, -v69, v145, v75
	v_fma_f32 v75, -v70, v146, v75
	v_fma_f32 v75, -v71, v147, v75
	v_fma_f32 v75, -v72, v148, v75
	v_fma_f32 v75, -v73, v149, v75
	v_fma_mixlo_f16 v240, -v74, v150, v75
	v_fma_f32 v75, -v74, v150, v75
	s_waitcnt lgkmcnt(14)
	ds_write_b16 v232, v240 offset:19376
	v_fma_f32 v76, -v64, v152, v76
	v_fma_f32 v76, -v65, v153, v76
	v_fma_f32 v76, -v66, v154, v76
	v_fma_f32 v76, -v67, v155, v76
	v_fma_f32 v76, -v68, v156, v76
	v_fma_f32 v76, -v69, v157, v76
	v_fma_f32 v76, -v70, v158, v76
	v_fma_f32 v76, -v71, v159, v76
	v_fma_f32 v76, -v72, v160, v76
	v_fma_f32 v76, -v73, v161, v76
	v_fma_f32 v76, -v74, v162, v76
	v_fma_mixlo_f16 v0, -v75, v163, v76
	v_fma_f32 v76, -v75, v163, v76
	s_waitcnt lgkmcnt(14)
	ds_write_b16 v232, v0 offset:19648
	s_waitcnt lgkmcnt(12)
	v_fma_f32 v77, -v64, v164, v77
	v_fma_f32 v77, -v65, v165, v77
	v_fma_f32 v77, -v66, v166, v77
	v_fma_f32 v77, -v67, v167, v77
	v_fma_f32 v77, -v68, v168, v77
	v_fma_f32 v77, -v69, v169, v77
	v_fma_f32 v77, -v70, v170, v77
	v_fma_f32 v77, -v71, v171, v77
	v_fma_f32 v77, -v72, v172, v77
	v_fma_f32 v77, -v73, v173, v77
	v_fma_f32 v77, -v74, v174, v77
	v_fma_f32 v77, -v75, v175, v77
	v_fma_mixlo_f16 v2, -v76, v176, v77
	v_fma_f32 v77, -v76, v176, v77
	ds_write_b16 v232, v2 offset:19920
	ds_read_b128 v[16:19], v228 offset:4096
	ds_read_b128 v[20:23], v228 offset:4112
	s_waitcnt lgkmcnt(14)
	ds_read_b128 v[24:27], v228 offset:4128
	s_waitcnt lgkmcnt(14)
	ds_read_b128 v[28:31], v228 offset:4144
	s_waitcnt lgkmcnt(12)
	v_fma_f32 v78, -v64, v180, v78
	v_fma_f32 v78, -v65, v181, v78
	v_fma_f32 v78, -v66, v182, v78
	v_fma_f32 v78, -v67, v183, v78
	v_fma_f32 v78, -v68, v184, v78
	v_fma_f32 v78, -v69, v185, v78
	v_fma_f32 v78, -v70, v186, v78
	v_fma_f32 v78, -v71, v187, v78
	v_fma_f32 v78, -v72, v188, v78
	v_fma_f32 v78, -v73, v189, v78
	v_fma_f32 v78, -v74, v190, v78
	v_fma_f32 v78, -v75, v191, v78
	v_fma_f32 v78, -v76, v244, v78
	v_fma_mixlo_f16 v3, -v77, v245, v78
	v_fma_f32 v78, -v77, v245, v78
	ds_write_b16 v232, v3 offset:20192
	ds_read_b128 v[32:35], v228 offset:4352
	ds_read_b128 v[36:39], v228 offset:4368
	s_waitcnt lgkmcnt(14)
	ds_read_b128 v[40:43], v228 offset:4384
	s_waitcnt lgkmcnt(14)
	ds_read_b128 v[44:47], v228 offset:4400
	s_waitcnt lgkmcnt(14)
	ds_read_b128 v[48:51], v228 offset:4416
	s_waitcnt lgkmcnt(13)
	v_fma_f32 v79, -v64, v248, v79
	v_fma_f32 v79, -v65, v249, v79
	v_fma_f32 v79, -v66, v250, v79
	v_fma_f32 v79, -v67, v251, v79
	v_fma_f32 v79, -v68, v4, v79
	v_fma_f32 v79, -v69, v5, v79
	v_fma_f32 v79, -v70, v6, v79
	v_fma_f32 v79, -v71, v7, v79
	v_fma_f32 v79, -v72, v8, v79
	v_fma_f32 v79, -v73, v9, v79
	v_fma_f32 v79, -v74, v10, v79
	v_fma_f32 v79, -v75, v11, v79
	v_fma_f32 v79, -v76, v12, v79
	v_fma_f32 v79, -v77, v13, v79
	v_fma_mixlo_f16 v238, -v78, v14, v79
	v_fma_f32 v79, -v78, v14, v79
	ds_write_b16 v232, v238 offset:20464
	ds_read_b128 v[52:55], v228 offset:4608
	s_waitcnt lgkmcnt(14)
	ds_read_b128 v[56:59], v228 offset:4624
	s_waitcnt lgkmcnt(14)
	ds_read_b128 v[60:63], v228 offset:4640
	s_waitcnt lgkmcnt(14)
	ds_read_b128 v[128:131], v228 offset:4656
	s_waitcnt lgkmcnt(14)
	ds_read_b128 v[132:135], v228 offset:4672
	s_waitcnt lgkmcnt(12)
	v_fma_f32 v80, -v64, v16, v80
	v_fma_f32 v80, -v65, v17, v80
	v_fma_f32 v80, -v66, v18, v80
	v_fma_f32 v80, -v67, v19, v80
	v_fma_f32 v80, -v68, v20, v80
	v_fma_f32 v80, -v69, v21, v80
	v_fma_f32 v80, -v70, v22, v80
	v_fma_f32 v80, -v71, v23, v80
	v_fma_f32 v80, -v72, v24, v80
	v_fma_f32 v80, -v73, v25, v80
	v_fma_f32 v80, -v74, v26, v80
	v_fma_f32 v80, -v75, v27, v80
	v_fma_f32 v80, -v76, v28, v80
	v_fma_f32 v80, -v77, v29, v80
	v_fma_f32 v80, -v78, v30, v80
	v_fma_mixlo_f16 v239, -v79, v31, v80
	v_fma_f32 v80, -v79, v31, v80
	ds_write_b16 v232, v239 offset:20736
	ds_read_b128 v[136:139], v228 offset:4864
	ds_read_b128 v[140:143], v228 offset:4880
	s_waitcnt lgkmcnt(14)
	ds_read_b128 v[144:147], v228 offset:4896
	s_waitcnt lgkmcnt(14)
	ds_read_b128 v[148:151], v228 offset:4912
	s_waitcnt lgkmcnt(14)
	ds_read_b128 v[152:155], v228 offset:4928
	s_waitcnt lgkmcnt(12)
	v_fma_f32 v81, -v64, v32, v81
	v_fma_f32 v81, -v65, v33, v81
	v_fma_f32 v81, -v66, v34, v81
	v_fma_f32 v81, -v67, v35, v81
	v_fma_f32 v81, -v68, v36, v81
	v_fma_f32 v81, -v69, v37, v81
	v_fma_f32 v81, -v70, v38, v81
	v_fma_f32 v81, -v71, v39, v81
	v_fma_f32 v81, -v72, v40, v81
	v_fma_f32 v81, -v73, v41, v81
	v_fma_f32 v81, -v74, v42, v81
	v_fma_f32 v81, -v75, v43, v81
	v_fma_f32 v81, -v76, v44, v81
	v_fma_f32 v81, -v77, v45, v81
	v_fma_f32 v81, -v78, v46, v81
	v_fma_f32 v81, -v79, v47, v81
	v_fma_mixlo_f16 v240, -v80, v48, v81
	v_fma_f32 v81, -v80, v48, v81
	ds_write_b16 v232, v240 offset:21008
	ds_read_b128 v[156:159], v228 offset:5120
	ds_read_b128 v[160:163], v228 offset:5136
	s_waitcnt lgkmcnt(14)
; #define LAS __attribute__((address_space(3)))
; __device__ __forceinline__ void phase_gdb(const int wvs, const Params& p, LAS unsigned char* lds, int nwg) {
;     ...
;       for (int i = 1; i < 64; ++i) {
; #pragma unroll
;         for (int j4 = 0; j4 < (i + 3) / 4; ++j4) { const f32x4 m4 = *(const LAS f32x4*)(M + i * 64 + j4 * 4);
; #pragma unroll
;           for (int jj = 0; jj < 4; ++jj) if (j4 * 4 + jj < i) x[i] -= m4[jj] * x[j4 * 4 + jj]; }
;         __builtin_amdgcn_sched_barrier(0); }
; #pragma unroll
;       for (int i = 0; i < 64; ++i) R[i * RP + t] = (hf)x[i]; }
	ds_read_b128 v[164:167], v228 offset:5152
	s_waitcnt lgkmcnt(14)
	ds_read_b128 v[168:171], v228 offset:5168
	s_waitcnt lgkmcnt(14)
	ds_read_b128 v[172:175], v228 offset:5184
	s_waitcnt lgkmcnt(12)
	v_fma_f32 v82, -v64, v52, v82
	v_fma_f32 v82, -v65, v53, v82
	v_fma_f32 v82, -v66, v54, v82
	v_fma_f32 v82, -v67, v55, v82
	v_fma_f32 v82, -v68, v56, v82
	v_fma_f32 v82, -v69, v57, v82
	v_fma_f32 v82, -v70, v58, v82
	v_fma_f32 v82, -v71, v59, v82
	v_fma_f32 v82, -v72, v60, v82
	v_fma_f32 v82, -v73, v61, v82
	v_fma_f32 v82, -v74, v62, v82
	v_fma_f32 v82, -v75, v63, v82
	v_fma_f32 v82, -v76, v128, v82
	v_fma_f32 v82, -v77, v129, v82
	v_fma_f32 v82, -v78, v130, v82
	v_fma_f32 v82, -v79, v131, v82
	v_fma_f32 v82, -v80, v132, v82
	v_fma_mixlo_f16 v0, -v81, v133, v82
	v_fma_f32 v82, -v81, v133, v82
	ds_write_b16 v232, v0 offset:21280
	ds_read_b128 v[176:179], v228 offset:5376
	ds_read_b128 v[180:183], v228 offset:5392
	s_waitcnt lgkmcnt(14)
	ds_read_b128 v[184:187], v228 offset:5408
	s_waitcnt lgkmcnt(14)
	ds_read_b128 v[188:191], v228 offset:5424
	s_waitcnt lgkmcnt(14)
	ds_read_b128 v[244:247], v228 offset:5440
	s_waitcnt lgkmcnt(14)
	ds_read_b128 v[248:251], v228 offset:5456
	s_waitcnt lgkmcnt(13)
	v_fma_f32 v83, -v64, v136, v83
	v_fma_f32 v83, -v65, v137, v83
	v_fma_f32 v83, -v66, v138, v83
	v_fma_f32 v83, -v67, v139, v83
	v_fma_f32 v83, -v68, v140, v83
	v_fma_f32 v83, -v69, v141, v83
	v_fma_f32 v83, -v70, v142, v83
	v_fma_f32 v83, -v71, v143, v83
	v_fma_f32 v83, -v72, v144, v83
	v_fma_f32 v83, -v73, v145, v83
	v_fma_f32 v83, -v74, v146, v83
	v_fma_f32 v83, -v75, v147, v83
	v_fma_f32 v83, -v76, v148, v83
	v_fma_f32 v83, -v77, v149, v83
	v_fma_f32 v83, -v78, v150, v83
	v_fma_f32 v83, -v79, v151, v83
	v_fma_f32 v83, -v80, v152, v83
	v_fma_f32 v83, -v81, v153, v83
	v_fma_mixlo_f16 v2, -v82, v154, v83
	v_fma_f32 v83, -v82, v154, v83
	ds_write_b16 v232, v2 offset:21552
	ds_read_b128 v[4:7], v228 offset:5632
	s_waitcnt lgkmcnt(14)
	ds_read_b128 v[8:11], v228 offset:5648
	s_waitcnt lgkmcnt(14)
	ds_read_b128 v[12:15], v228 offset:5664
	s_waitcnt lgkmcnt(14)
	ds_read_b128 v[16:19], v228 offset:5680
	s_waitcnt lgkmcnt(14)
	ds_read_b128 v[20:23], v228 offset:5696
	s_waitcnt lgkmcnt(14)
	ds_read_b128 v[24:27], v228 offset:5712
	s_waitcnt lgkmcnt(14)
	v_fma_f32 v84, -v64, v156, v84
	v_fma_f32 v84, -v65, v157, v84
	v_fma_f32 v84, -v66, v158, v84
	v_fma_f32 v84, -v67, v159, v84
	v_fma_f32 v84, -v68, v160, v84
	v_fma_f32 v84, -v69, v161, v84
	v_fma_f32 v84, -v70, v162, v84
	v_fma_f32 v84, -v71, v163, v84
	v_fma_f32 v84, -v72, v164, v84
	v_fma_f32 v84, -v73, v165, v84
	v_fma_f32 v84, -v74, v166, v84
	v_fma_f32 v84, -v75, v167, v84
	v_fma_f32 v84, -v76, v168, v84
	v_fma_f32 v84, -v77, v169, v84
	v_fma_f32 v84, -v78, v170, v84
	v_fma_f32 v84, -v79, v171, v84
	v_fma_f32 v84, -v80, v172, v84
	v_fma_f32 v84, -v81, v173, v84
	v_fma_f32 v84, -v82, v174, v84
	v_fma_mixlo_f16 v3, -v83, v175, v84
	v_fma_f32 v84, -v83, v175, v84
	ds_write_b16 v232, v3 offset:21824
	s_waitcnt lgkmcnt(14)
	ds_read_b128 v[28:31], v228 offset:5888
	s_waitcnt lgkmcnt(14)
	ds_read_b128 v[32:35], v228 offset:5904
	s_waitcnt lgkmcnt(14)
	ds_read_b128 v[36:39], v228 offset:5920
	s_waitcnt lgkmcnt(14)
	ds_read_b128 v[40:43], v228 offset:5936
	s_waitcnt lgkmcnt(14)
	ds_read_b128 v[44:47], v228 offset:5952
	s_waitcnt lgkmcnt(14)
	ds_read_b128 v[48:51], v228 offset:5968
	s_waitcnt lgkmcnt(14)
	v_fma_f32 v85, -v64, v176, v85
	v_fma_f32 v85, -v65, v177, v85
	v_fma_f32 v85, -v66, v178, v85
	v_fma_f32 v85, -v67, v179, v85
	v_fma_f32 v85, -v68, v180, v85
	v_fma_f32 v85, -v69, v181, v85
	v_fma_f32 v85, -v70, v182, v85
	v_fma_f32 v85, -v71, v183, v85
	v_fma_f32 v85, -v72, v184, v85
	v_fma_f32 v85, -v73, v185, v85
	v_fma_f32 v85, -v74, v186, v85
	v_fma_f32 v85, -v75, v187, v85
	v_fma_f32 v85, -v76, v188, v85
	v_fma_f32 v85, -v77, v189, v85
	v_fma_f32 v85, -v78, v190, v85
	v_fma_f32 v85, -v79, v191, v85
	v_fma_f32 v85, -v80, v244, v85
	v_fma_f32 v85, -v81, v245, v85
	v_fma_f32 v85, -v82, v246, v85
	v_fma_f32 v85, -v83, v247, v85
	v_fma_mixlo_f16 v238, -v84, v248, v85
	v_fma_f32 v85, -v84, v248, v85
	ds_write_b16 v232, v238 offset:22096
	s_waitcnt lgkmcnt(14)
	ds_read_b128 v[52:55], v228 offset:6144
	s_waitcnt lgkmcnt(14)
	ds_read_b128 v[56:59], v228 offset:6160
	s_waitcnt lgkmcnt(14)
	ds_read_b128 v[60:63], v228 offset:6176
	s_waitcnt lgkmcnt(14)
	ds_read_b128 v[128:131], v228 offset:6192
	s_waitcnt lgkmcnt(14)
	ds_read_b128 v[132:135], v228 offset:6208
	s_waitcnt lgkmcnt(14)
	ds_read_b128 v[136:139], v228 offset:6224
	s_waitcnt lgkmcnt(14)
	v_fma_f32 v86, -v64, v4, v86
	v_fma_f32 v86, -v65, v5, v86
	v_fma_f32 v86, -v66, v6, v86
	v_fma_f32 v86, -v67, v7, v86
	v_fma_f32 v86, -v68, v8, v86
	v_fma_f32 v86, -v69, v9, v86
	v_fma_f32 v86, -v70, v10, v86
	v_fma_f32 v86, -v71, v11, v86
	v_fma_f32 v86, -v72, v12, v86
	v_fma_f32 v86, -v73, v13, v86
	v_fma_f32 v86, -v74, v14, v86
	v_fma_f32 v86, -v75, v15, v86
	v_fma_f32 v86, -v76, v16, v86
	v_fma_f32 v86, -v77, v17, v86
	v_fma_f32 v86, -v78, v18, v86
	v_fma_f32 v86, -v79, v19, v86
	v_fma_f32 v86, -v80, v20, v86
	v_fma_f32 v86, -v81, v21, v86
	v_fma_f32 v86, -v82, v22, v86
	v_fma_f32 v86, -v83, v23, v86
	v_fma_f32 v86, -v84, v24, v86
	v_fma_mixlo_f16 v239, -v85, v25, v86
	v_fma_f32 v86, -v85, v25, v86
	ds_write_b16 v232, v239 offset:22368
	s_waitcnt lgkmcnt(14)
	ds_read_b128 v[140:143], v228 offset:6400
	s_waitcnt lgkmcnt(14)
	ds_read_b128 v[144:147], v228 offset:6416
	s_waitcnt lgkmcnt(14)
	ds_read_b128 v[148:151], v228 offset:6432
	s_waitcnt lgkmcnt(14)
	ds_read_b128 v[152:155], v228 offset:6448
	s_waitcnt lgkmcnt(14)
	ds_read_b128 v[156:159], v228 offset:6464
	s_waitcnt lgkmcnt(14)
; #define LAS __attribute__((address_space(3)))
; __device__ __forceinline__ void phase_gdb(const int wvs, const Params& p, LAS unsigned char* lds, int nwg) {
;     ...
;       for (int i = 1; i < 64; ++i) {
; #pragma unroll
;         for (int j4 = 0; j4 < (i + 3) / 4; ++j4) { const f32x4 m4 = *(const LAS f32x4*)(M + i * 64 + j4 * 4);
; #pragma unroll
;           for (int jj = 0; jj < 4; ++jj) if (j4 * 4 + jj < i) x[i] -= m4[jj] * x[j4 * 4 + jj]; }
;         __builtin_amdgcn_sched_barrier(0); }
; #pragma unroll
;       for (int i = 0; i < 64; ++i) R[i * RP + t] = (hf)x[i]; }
	ds_read_b128 v[160:163], v228 offset:6480
	s_waitcnt lgkmcnt(14)
	ds_read_b128 v[164:167], v228 offset:6496
	v_fma_f32 v87, -v64, v28, v87
	v_fma_f32 v87, -v65, v29, v87
	v_fma_f32 v87, -v66, v30, v87
	v_fma_f32 v87, -v67, v31, v87
	v_fma_f32 v87, -v68, v32, v87
	v_fma_f32 v87, -v69, v33, v87
	v_fma_f32 v87, -v70, v34, v87
	v_fma_f32 v87, -v71, v35, v87
	v_fma_f32 v87, -v72, v36, v87
	v_fma_f32 v87, -v73, v37, v87
	v_fma_f32 v87, -v74, v38, v87
	v_fma_f32 v87, -v75, v39, v87
	v_fma_f32 v87, -v76, v40, v87
	v_fma_f32 v87, -v77, v41, v87
	v_fma_f32 v87, -v78, v42, v87
	v_fma_f32 v87, -v79, v43, v87
	v_fma_f32 v87, -v80, v44, v87
	v_fma_f32 v87, -v81, v45, v87
	v_fma_f32 v87, -v82, v46, v87
	v_fma_f32 v87, -v83, v47, v87
	v_fma_f32 v87, -v84, v48, v87
	v_fma_f32 v87, -v85, v49, v87
	v_fma_mixlo_f16 v240, -v86, v50, v87
	v_fma_f32 v87, -v86, v50, v87
	s_waitcnt lgkmcnt(14)
	ds_write_b16 v232, v240 offset:22640
	s_waitcnt lgkmcnt(14)
	ds_read_b128 v[168:171], v228 offset:6656
	s_waitcnt lgkmcnt(14)
	ds_read_b128 v[172:175], v228 offset:6672
	s_waitcnt lgkmcnt(14)
	ds_read_b128 v[176:179], v228 offset:6688
	s_waitcnt lgkmcnt(14)
	ds_read_b128 v[180:183], v228 offset:6704
	s_waitcnt lgkmcnt(14)
	ds_read_b128 v[184:187], v228 offset:6720
	s_waitcnt lgkmcnt(14)
	ds_read_b128 v[188:191], v228 offset:6736
	s_waitcnt lgkmcnt(14)
	ds_read_b128 v[244:247], v228 offset:6752
	v_fma_f32 v88, -v64, v52, v88
	v_fma_f32 v88, -v65, v53, v88
	v_fma_f32 v88, -v66, v54, v88
	v_fma_f32 v88, -v67, v55, v88
	v_fma_f32 v88, -v68, v56, v88
	v_fma_f32 v88, -v69, v57, v88
	v_fma_f32 v88, -v70, v58, v88
	v_fma_f32 v88, -v71, v59, v88
	v_fma_f32 v88, -v72, v60, v88
	v_fma_f32 v88, -v73, v61, v88
	v_fma_f32 v88, -v74, v62, v88
	v_fma_f32 v88, -v75, v63, v88
	v_fma_f32 v88, -v76, v128, v88
	v_fma_f32 v88, -v77, v129, v88
	v_fma_f32 v88, -v78, v130, v88
	v_fma_f32 v88, -v79, v131, v88
	v_fma_f32 v88, -v80, v132, v88
	v_fma_f32 v88, -v81, v133, v88
	v_fma_f32 v88, -v82, v134, v88
	v_fma_f32 v88, -v83, v135, v88
	v_fma_f32 v88, -v84, v136, v88
	v_fma_f32 v88, -v85, v137, v88
	v_fma_f32 v88, -v86, v138, v88
	v_fma_mixlo_f16 v0, -v87, v139, v88
	v_fma_f32 v88, -v87, v139, v88
	s_waitcnt lgkmcnt(14)
	ds_write_b16 v232, v0 offset:22912
	s_waitcnt lgkmcnt(14)
	ds_read_b128 v[248:251], v228 offset:6912
	s_waitcnt lgkmcnt(14)
	ds_read_b128 v[4:7], v228 offset:6928
	s_waitcnt lgkmcnt(14)
	ds_read_b128 v[8:11], v228 offset:6944
	s_waitcnt lgkmcnt(14)
	ds_read_b128 v[12:15], v228 offset:6960
	s_waitcnt lgkmcnt(14)
	ds_read_b128 v[16:19], v228 offset:6976
	s_waitcnt lgkmcnt(14)
	ds_read_b128 v[20:23], v228 offset:6992
	s_waitcnt lgkmcnt(14)
	ds_read_b128 v[24:27], v228 offset:7008
	v_fma_f32 v89, -v64, v140, v89
	v_fma_f32 v89, -v65, v141, v89
	v_fma_f32 v89, -v66, v142, v89
	v_fma_f32 v89, -v67, v143, v89
	v_fma_f32 v89, -v68, v144, v89
	v_fma_f32 v89, -v69, v145, v89
	v_fma_f32 v89, -v70, v146, v89
	v_fma_f32 v89, -v71, v147, v89
	v_fma_f32 v89, -v72, v148, v89
	v_fma_f32 v89, -v73, v149, v89
	v_fma_f32 v89, -v74, v150, v89
	v_fma_f32 v89, -v75, v151, v89
	v_fma_f32 v89, -v76, v152, v89
	v_fma_f32 v89, -v77, v153, v89
	v_fma_f32 v89, -v78, v154, v89
	v_fma_f32 v89, -v79, v155, v89
	v_fma_f32 v89, -v80, v156, v89
	v_fma_f32 v89, -v81, v157, v89
	v_fma_f32 v89, -v82, v158, v89
	v_fma_f32 v89, -v83, v159, v89
	v_fma_f32 v89, -v84, v160, v89
	v_fma_f32 v89, -v85, v161, v89
	v_fma_f32 v89, -v86, v162, v89
	v_fma_f32 v89, -v87, v163, v89
	v_fma_mixlo_f16 v2, -v88, v164, v89
	v_fma_f32 v89, -v88, v164, v89
	s_waitcnt lgkmcnt(14)
	ds_write_b16 v232, v2 offset:23184
	s_waitcnt lgkmcnt(14)
	ds_read_b128 v[28:31], v228 offset:7168
	s_waitcnt lgkmcnt(14)
	ds_read_b128 v[32:35], v228 offset:7184
	s_waitcnt lgkmcnt(14)
	ds_read_b128 v[36:39], v228 offset:7200
	s_waitcnt lgkmcnt(14)
	ds_read_b128 v[40:43], v228 offset:7216
	s_waitcnt lgkmcnt(14)
	ds_read_b128 v[44:47], v228 offset:7232
	s_waitcnt lgkmcnt(14)
	ds_read_b128 v[48:51], v228 offset:7248
	s_waitcnt lgkmcnt(14)
	ds_read_b128 v[52:55], v228 offset:7264
	v_fma_f32 v90, -v64, v168, v90
	v_fma_f32 v90, -v65, v169, v90
	v_fma_f32 v90, -v66, v170, v90
	v_fma_f32 v90, -v67, v171, v90
	v_fma_f32 v90, -v68, v172, v90
	v_fma_f32 v90, -v69, v173, v90
	v_fma_f32 v90, -v70, v174, v90
	v_fma_f32 v90, -v71, v175, v90
	v_fma_f32 v90, -v72, v176, v90
	v_fma_f32 v90, -v73, v177, v90
	v_fma_f32 v90, -v74, v178, v90
	v_fma_f32 v90, -v75, v179, v90
	v_fma_f32 v90, -v76, v180, v90
	v_fma_f32 v90, -v77, v181, v90
	v_fma_f32 v90, -v78, v182, v90
	v_fma_f32 v90, -v79, v183, v90
	v_fma_f32 v90, -v80, v184, v90
	v_fma_f32 v90, -v81, v185, v90
	v_fma_f32 v90, -v82, v186, v90
	v_fma_f32 v90, -v83, v187, v90
	v_fma_f32 v90, -v84, v188, v90
	v_fma_f32 v90, -v85, v189, v90
	v_fma_f32 v90, -v86, v190, v90
	v_fma_f32 v90, -v87, v191, v90
	v_fma_f32 v90, -v88, v244, v90
	v_fma_mixlo_f16 v3, -v89, v245, v90
	v_fma_f32 v90, -v89, v245, v90
	s_waitcnt lgkmcnt(14)
	ds_write_b16 v232, v3 offset:23456
	s_waitcnt lgkmcnt(14)
	ds_read_b128 v[56:59], v228 offset:7424
	s_waitcnt lgkmcnt(14)
	ds_read_b128 v[60:63], v228 offset:7440
	s_waitcnt lgkmcnt(14)
	ds_read_b128 v[128:131], v228 offset:7456
	s_waitcnt lgkmcnt(14)
	ds_read_b128 v[132:135], v228 offset:7472
	s_waitcnt lgkmcnt(14)
	ds_read_b128 v[136:139], v228 offset:7488
	s_waitcnt lgkmcnt(14)
	ds_read_b128 v[140:143], v228 offset:7504
	s_waitcnt lgkmcnt(14)
	ds_read_b128 v[144:147], v228 offset:7520
	s_waitcnt lgkmcnt(14)
; #define LAS __attribute__((address_space(3)))
; __device__ __forceinline__ void phase_gdb(const int wvs, const Params& p, LAS unsigned char* lds, int nwg) {
;     ...
;       for (int i = 1; i < 64; ++i) {
; #pragma unroll
;         for (int j4 = 0; j4 < (i + 3) / 4; ++j4) { const f32x4 m4 = *(const LAS f32x4*)(M + i * 64 + j4 * 4);
; #pragma unroll
;           for (int jj = 0; jj < 4; ++jj) if (j4 * 4 + jj < i) x[i] -= m4[jj] * x[j4 * 4 + jj]; }
;         __builtin_amdgcn_sched_barrier(0); }
; #pragma unroll
;       for (int i = 0; i < 64; ++i) R[i * RP + t] = (hf)x[i]; }
	ds_read_b128 v[148:151], v228 offset:7536
	v_fma_f32 v91, -v64, v248, v91
	v_fma_f32 v91, -v65, v249, v91
	v_fma_f32 v91, -v66, v250, v91
	v_fma_f32 v91, -v67, v251, v91
	v_fma_f32 v91, -v68, v4, v91
	v_fma_f32 v91, -v69, v5, v91
	v_fma_f32 v91, -v70, v6, v91
	v_fma_f32 v91, -v71, v7, v91
	v_fma_f32 v91, -v72, v8, v91
	v_fma_f32 v91, -v73, v9, v91
	v_fma_f32 v91, -v74, v10, v91
	v_fma_f32 v91, -v75, v11, v91
	v_fma_f32 v91, -v76, v12, v91
	v_fma_f32 v91, -v77, v13, v91
	v_fma_f32 v91, -v78, v14, v91
	v_fma_f32 v91, -v79, v15, v91
	v_fma_f32 v91, -v80, v16, v91
	v_fma_f32 v91, -v81, v17, v91
	v_fma_f32 v91, -v82, v18, v91
	v_fma_f32 v91, -v83, v19, v91
	v_fma_f32 v91, -v84, v20, v91
	v_fma_f32 v91, -v85, v21, v91
	v_fma_f32 v91, -v86, v22, v91
	v_fma_f32 v91, -v87, v23, v91
	v_fma_f32 v91, -v88, v24, v91
	v_fma_f32 v91, -v89, v25, v91
	v_fma_mixlo_f16 v238, -v90, v26, v91
	v_fma_f32 v91, -v90, v26, v91
	s_waitcnt lgkmcnt(14)
	ds_write_b16 v232, v238 offset:23728
	s_waitcnt lgkmcnt(10)
	v_fma_f32 v92, -v64, v28, v92
	v_fma_f32 v92, -v65, v29, v92
	v_fma_f32 v92, -v66, v30, v92
	v_fma_f32 v92, -v67, v31, v92
	v_fma_f32 v92, -v68, v32, v92
	v_fma_f32 v92, -v69, v33, v92
	v_fma_f32 v92, -v70, v34, v92
	v_fma_f32 v92, -v71, v35, v92
	v_fma_f32 v92, -v72, v36, v92
	v_fma_f32 v92, -v73, v37, v92
	v_fma_f32 v92, -v74, v38, v92
	v_fma_f32 v92, -v75, v39, v92
	v_fma_f32 v92, -v76, v40, v92
	v_fma_f32 v92, -v77, v41, v92
	v_fma_f32 v92, -v78, v42, v92
	v_fma_f32 v92, -v79, v43, v92
	v_fma_f32 v92, -v80, v44, v92
	v_fma_f32 v92, -v81, v45, v92
	v_fma_f32 v92, -v82, v46, v92
	v_fma_f32 v92, -v83, v47, v92
	v_fma_f32 v92, -v84, v48, v92
	v_fma_f32 v92, -v85, v49, v92
	v_fma_f32 v92, -v86, v50, v92
	v_fma_f32 v92, -v87, v51, v92
	v_fma_f32 v92, -v88, v52, v92
	v_fma_f32 v92, -v89, v53, v92
	v_fma_f32 v92, -v90, v54, v92
	v_fma_mixlo_f16 v239, -v91, v55, v92
	v_fma_f32 v92, -v91, v55, v92
	ds_write_b16 v232, v239 offset:24000
	ds_read_b128 v[152:155], v228 offset:7680
	ds_read_b128 v[156:159], v228 offset:7696
	ds_read_b128 v[160:163], v228 offset:7712
	ds_read_b128 v[164:167], v228 offset:7728
	s_waitcnt lgkmcnt(14)
	ds_read_b128 v[168:171], v228 offset:7744
	s_waitcnt lgkmcnt(14)
	ds_read_b128 v[172:175], v228 offset:7760
	s_waitcnt lgkmcnt(14)
	ds_read_b128 v[176:179], v228 offset:7776
	s_waitcnt lgkmcnt(14)
	ds_read_b128 v[180:183], v228 offset:7792
	s_waitcnt lgkmcnt(10)
	v_fma_f32 v93, -v64, v56, v93
	v_fma_f32 v93, -v65, v57, v93
	v_fma_f32 v93, -v66, v58, v93
	v_fma_f32 v93, -v67, v59, v93
	v_fma_f32 v93, -v68, v60, v93
	v_fma_f32 v93, -v69, v61, v93
	v_fma_f32 v93, -v70, v62, v93
	v_fma_f32 v93, -v71, v63, v93
	v_fma_f32 v93, -v72, v128, v93
	v_fma_f32 v93, -v73, v129, v93
	v_fma_f32 v93, -v74, v130, v93
	v_fma_f32 v93, -v75, v131, v93
	v_fma_f32 v93, -v76, v132, v93
	v_fma_f32 v93, -v77, v133, v93
	v_fma_f32 v93, -v78, v134, v93
	v_fma_f32 v93, -v79, v135, v93
	v_fma_f32 v93, -v80, v136, v93
	v_fma_f32 v93, -v81, v137, v93
	v_fma_f32 v93, -v82, v138, v93
	v_fma_f32 v93, -v83, v139, v93
	v_fma_f32 v93, -v84, v140, v93
	v_fma_f32 v93, -v85, v141, v93
	v_fma_f32 v93, -v86, v142, v93
	v_fma_f32 v93, -v87, v143, v93
	v_fma_f32 v93, -v88, v144, v93
	v_fma_f32 v93, -v89, v145, v93
	v_fma_f32 v93, -v90, v146, v93
	v_fma_f32 v93, -v91, v147, v93
	v_fma_mixlo_f16 v240, -v92, v148, v93
	v_fma_f32 v93, -v92, v148, v93
	ds_write_b16 v232, v240 offset:24272
	ds_read_b128 v[184:187], v228 offset:7936
	ds_read_b128 v[188:191], v228 offset:7952
	ds_read_b128 v[244:247], v228 offset:7968
	ds_read_b128 v[248:251], v228 offset:7984
	s_waitcnt lgkmcnt(14)
	ds_read_b128 v[4:7], v228 offset:8000
	s_waitcnt lgkmcnt(14)
	ds_read_b128 v[8:11], v228 offset:8016
	s_waitcnt lgkmcnt(14)
	ds_read_b128 v[12:15], v228 offset:8032
	s_waitcnt lgkmcnt(14)
	ds_read_b128 v[16:19], v228 offset:8048
	s_waitcnt lgkmcnt(9)
	v_fma_f32 v94, -v64, v152, v94
	v_fma_f32 v94, -v65, v153, v94
	v_fma_f32 v94, -v66, v154, v94
	v_fma_f32 v94, -v67, v155, v94
	v_fma_f32 v94, -v68, v156, v94
	v_fma_f32 v94, -v69, v157, v94
	v_fma_f32 v94, -v70, v158, v94
	v_fma_f32 v94, -v71, v159, v94
	v_fma_f32 v94, -v72, v160, v94
	v_fma_f32 v94, -v73, v161, v94
	v_fma_f32 v94, -v74, v162, v94
	v_fma_f32 v94, -v75, v163, v94
	v_fma_f32 v94, -v76, v164, v94
	v_fma_f32 v94, -v77, v165, v94
	v_fma_f32 v94, -v78, v166, v94
	v_fma_f32 v94, -v79, v167, v94
	v_fma_f32 v94, -v80, v168, v94
	v_fma_f32 v94, -v81, v169, v94
	v_fma_f32 v94, -v82, v170, v94
	v_fma_f32 v94, -v83, v171, v94
	v_fma_f32 v94, -v84, v172, v94
	v_fma_f32 v94, -v85, v173, v94
	v_fma_f32 v94, -v86, v174, v94
	v_fma_f32 v94, -v87, v175, v94
	v_fma_f32 v94, -v88, v176, v94
	v_fma_f32 v94, -v89, v177, v94
	v_fma_f32 v94, -v90, v178, v94
	v_fma_f32 v94, -v91, v179, v94
	v_fma_f32 v94, -v92, v180, v94
	v_fma_mixlo_f16 v0, -v93, v181, v94
	v_fma_f32 v94, -v93, v181, v94
	ds_write_b16 v232, v0 offset:24544
	ds_read_b128 v[20:23], v228 offset:8192
	ds_read_b128 v[24:27], v228 offset:8208
	ds_read_b128 v[28:31], v228 offset:8224
	ds_read_b128 v[32:35], v228 offset:8240
	ds_read_b128 v[36:39], v228 offset:8256
	s_waitcnt lgkmcnt(14)
	ds_read_b128 v[40:43], v228 offset:8272
	s_waitcnt lgkmcnt(14)
	ds_read_b128 v[44:47], v228 offset:8288
	s_waitcnt lgkmcnt(14)
	ds_read_b128 v[48:51], v228 offset:8304
	s_waitcnt lgkmcnt(9)
; #define LAS __attribute__((address_space(3)))
; __device__ __forceinline__ void phase_gdb(const int wvs, const Params& p, LAS unsigned char* lds, int nwg) {
;     ...
;       for (int i = 1; i < 64; ++i) {
; #pragma unroll
;         for (int j4 = 0; j4 < (i + 3) / 4; ++j4) { const f32x4 m4 = *(const LAS f32x4*)(M + i * 64 + j4 * 4);
; #pragma unroll
;           for (int jj = 0; jj < 4; ++jj) if (j4 * 4 + jj < i) x[i] -= m4[jj] * x[j4 * 4 + jj]; }
;         __builtin_amdgcn_sched_barrier(0); }
; #pragma unroll
;       for (int i = 0; i < 64; ++i) R[i * RP + t] = (hf)x[i]; }
	v_fma_f32 v95, -v64, v184, v95
	v_fma_f32 v95, -v65, v185, v95
	v_fma_f32 v95, -v66, v186, v95
	v_fma_f32 v95, -v67, v187, v95
	v_fma_f32 v95, -v68, v188, v95
	v_fma_f32 v95, -v69, v189, v95
	v_fma_f32 v95, -v70, v190, v95
	v_fma_f32 v95, -v71, v191, v95
	v_fma_f32 v95, -v72, v244, v95
	v_fma_f32 v95, -v73, v245, v95
	v_fma_f32 v95, -v74, v246, v95
	v_fma_f32 v95, -v75, v247, v95
	v_fma_f32 v95, -v76, v248, v95
	v_fma_f32 v95, -v77, v249, v95
	v_fma_f32 v95, -v78, v250, v95
	v_fma_f32 v95, -v79, v251, v95
	v_fma_f32 v95, -v80, v4, v95
	v_fma_f32 v95, -v81, v5, v95
	v_fma_f32 v95, -v82, v6, v95
	v_fma_f32 v95, -v83, v7, v95
	v_fma_f32 v95, -v84, v8, v95
	v_fma_f32 v95, -v85, v9, v95
	v_fma_f32 v95, -v86, v10, v95
	v_fma_f32 v95, -v87, v11, v95
	v_fma_f32 v95, -v88, v12, v95
	v_fma_f32 v95, -v89, v13, v95
	v_fma_f32 v95, -v90, v14, v95
	v_fma_f32 v95, -v91, v15, v95
	v_fma_f32 v95, -v92, v16, v95
	v_fma_f32 v95, -v93, v17, v95
	v_fma_mixlo_f16 v2, -v94, v18, v95
	v_fma_f32 v95, -v94, v18, v95
	ds_write_b16 v232, v2 offset:24816
	ds_read_b128 v[52:55], v228 offset:8448
	ds_read_b128 v[56:59], v228 offset:8464
	ds_read_b128 v[60:63], v228 offset:8480
	ds_read_b128 v[128:131], v228 offset:8496
	ds_read_b128 v[132:135], v228 offset:8512
	s_waitcnt lgkmcnt(14)
	ds_read_b128 v[136:139], v228 offset:8528
	s_waitcnt lgkmcnt(14)
	ds_read_b128 v[140:143], v228 offset:8544
	s_waitcnt lgkmcnt(14)
	ds_read_b128 v[144:147], v228 offset:8560
	s_waitcnt lgkmcnt(14)
	ds_read_b128 v[148:151], v228 offset:8576
	s_waitcnt lgkmcnt(10)
	v_fma_f32 v96, -v64, v20, v96
	v_fma_f32 v96, -v65, v21, v96
	v_fma_f32 v96, -v66, v22, v96
	v_fma_f32 v96, -v67, v23, v96
	v_fma_f32 v96, -v68, v24, v96
	v_fma_f32 v96, -v69, v25, v96
	v_fma_f32 v96, -v70, v26, v96
	v_fma_f32 v96, -v71, v27, v96
	v_fma_f32 v96, -v72, v28, v96
	v_fma_f32 v96, -v73, v29, v96
	v_fma_f32 v96, -v74, v30, v96
	v_fma_f32 v96, -v75, v31, v96
	v_fma_f32 v96, -v76, v32, v96
	v_fma_f32 v96, -v77, v33, v96
	v_fma_f32 v96, -v78, v34, v96
	v_fma_f32 v96, -v79, v35, v96
	v_fma_f32 v96, -v80, v36, v96
	v_fma_f32 v96, -v81, v37, v96
	v_fma_f32 v96, -v82, v38, v96
	v_fma_f32 v96, -v83, v39, v96
	v_fma_f32 v96, -v84, v40, v96
	v_fma_f32 v96, -v85, v41, v96
	v_fma_f32 v96, -v86, v42, v96
	v_fma_f32 v96, -v87, v43, v96
	v_fma_f32 v96, -v88, v44, v96
	v_fma_f32 v96, -v89, v45, v96
	v_fma_f32 v96, -v90, v46, v96
	v_fma_f32 v96, -v91, v47, v96
	v_fma_f32 v96, -v92, v48, v96
	v_fma_f32 v96, -v93, v49, v96
	v_fma_f32 v96, -v94, v50, v96
	v_fma_mixlo_f16 v3, -v95, v51, v96
	v_fma_f32 v96, -v95, v51, v96
	ds_write_b16 v232, v3 offset:25088
	ds_read_b128 v[152:155], v228 offset:8704
	ds_read_b128 v[156:159], v228 offset:8720
	ds_read_b128 v[160:163], v228 offset:8736
	ds_read_b128 v[164:167], v228 offset:8752
	s_waitcnt lgkmcnt(14)
	ds_read_b128 v[168:171], v228 offset:8768
	s_waitcnt lgkmcnt(14)
	ds_read_b128 v[172:175], v228 offset:8784
	s_waitcnt lgkmcnt(14)
	ds_read_b128 v[176:179], v228 offset:8800
	s_waitcnt lgkmcnt(14)
	ds_read_b128 v[180:183], v228 offset:8816
	s_waitcnt lgkmcnt(14)
	ds_read_b128 v[184:187], v228 offset:8832
	s_waitcnt lgkmcnt(10)
	v_fma_f32 v97, -v64, v52, v97
	v_fma_f32 v97, -v65, v53, v97
	v_fma_f32 v97, -v66, v54, v97
	v_fma_f32 v97, -v67, v55, v97
	v_fma_f32 v97, -v68, v56, v97
	v_fma_f32 v97, -v69, v57, v97
	v_fma_f32 v97, -v70, v58, v97
	v_fma_f32 v97, -v71, v59, v97
	v_fma_f32 v97, -v72, v60, v97
	v_fma_f32 v97, -v73, v61, v97
	v_fma_f32 v97, -v74, v62, v97
	v_fma_f32 v97, -v75, v63, v97
	v_fma_f32 v97, -v76, v128, v97
	v_fma_f32 v97, -v77, v129, v97
	v_fma_f32 v97, -v78, v130, v97
	v_fma_f32 v97, -v79, v131, v97
	v_fma_f32 v97, -v80, v132, v97
	v_fma_f32 v97, -v81, v133, v97
	v_fma_f32 v97, -v82, v134, v97
	v_fma_f32 v97, -v83, v135, v97
	v_fma_f32 v97, -v84, v136, v97
	v_fma_f32 v97, -v85, v137, v97
	v_fma_f32 v97, -v86, v138, v97
	v_fma_f32 v97, -v87, v139, v97
	v_fma_f32 v97, -v88, v140, v97
	v_fma_f32 v97, -v89, v141, v97
	v_fma_f32 v97, -v90, v142, v97
	v_fma_f32 v97, -v91, v143, v97
	v_fma_f32 v97, -v92, v144, v97
	v_fma_f32 v97, -v93, v145, v97
	v_fma_f32 v97, -v94, v146, v97
	v_fma_f32 v97, -v95, v147, v97
	v_fma_mixlo_f16 v238, -v96, v148, v97
	v_fma_f32 v97, -v96, v148, v97
	ds_write_b16 v232, v238 offset:25360
	ds_read_b128 v[188:191], v228 offset:8960
	ds_read_b128 v[244:247], v228 offset:8976
	ds_read_b128 v[248:251], v228 offset:8992
	ds_read_b128 v[4:7], v228 offset:9008
	s_waitcnt lgkmcnt(14)
	ds_read_b128 v[8:11], v228 offset:9024
	s_waitcnt lgkmcnt(14)
	ds_read_b128 v[12:15], v228 offset:9040
	s_waitcnt lgkmcnt(14)
	ds_read_b128 v[16:19], v228 offset:9056
	s_waitcnt lgkmcnt(14)
	ds_read_b128 v[20:23], v228 offset:9072
	s_waitcnt lgkmcnt(14)
	ds_read_b128 v[24:27], v228 offset:9088
	s_waitcnt lgkmcnt(10)
	v_fma_f32 v98, -v64, v152, v98
	v_fma_f32 v98, -v65, v153, v98
	v_fma_f32 v98, -v66, v154, v98
	v_fma_f32 v98, -v67, v155, v98
	v_fma_f32 v98, -v68, v156, v98
	v_fma_f32 v98, -v69, v157, v98
	v_fma_f32 v98, -v70, v158, v98
	v_fma_f32 v98, -v71, v159, v98
	v_fma_f32 v98, -v72, v160, v98
	v_fma_f32 v98, -v73, v161, v98
	v_fma_f32 v98, -v74, v162, v98
	v_fma_f32 v98, -v75, v163, v98
	v_fma_f32 v98, -v76, v164, v98
	v_fma_f32 v98, -v77, v165, v98
	v_fma_f32 v98, -v78, v166, v98
	v_fma_f32 v98, -v79, v167, v98
	v_fma_f32 v98, -v80, v168, v98
	v_fma_f32 v98, -v81, v169, v98
	v_fma_f32 v98, -v82, v170, v98
	v_fma_f32 v98, -v83, v171, v98
	v_fma_f32 v98, -v84, v172, v98
	v_fma_f32 v98, -v85, v173, v98
	v_fma_f32 v98, -v86, v174, v98
	v_fma_f32 v98, -v87, v175, v98
	v_fma_f32 v98, -v88, v176, v98
	v_fma_f32 v98, -v89, v177, v98
	v_fma_f32 v98, -v90, v178, v98
	v_fma_f32 v98, -v91, v179, v98
	v_fma_f32 v98, -v92, v180, v98
	v_fma_f32 v98, -v93, v181, v98
	v_fma_f32 v98, -v94, v182, v98
	v_fma_f32 v98, -v95, v183, v98
	v_fma_f32 v98, -v96, v184, v98
	v_fma_mixlo_f16 v239, -v97, v185, v98
	v_fma_f32 v98, -v97, v185, v98
	ds_write_b16 v232, v239 offset:25632
	ds_read_b128 v[28:31], v228 offset:9216
	ds_read_b128 v[32:35], v228 offset:9232
	ds_read_b128 v[36:39], v228 offset:9248
	ds_read_b128 v[40:43], v228 offset:9264
	s_waitcnt lgkmcnt(14)
; #define LAS __attribute__((address_space(3)))
; __device__ __forceinline__ void phase_gdb(const int wvs, const Params& p, LAS unsigned char* lds, int nwg) {
;     ...
;       for (int i = 1; i < 64; ++i) {
; #pragma unroll
;         for (int j4 = 0; j4 < (i + 3) / 4; ++j4) { const f32x4 m4 = *(const LAS f32x4*)(M + i * 64 + j4 * 4);
; #pragma unroll
;           for (int jj = 0; jj < 4; ++jj) if (j4 * 4 + jj < i) x[i] -= m4[jj] * x[j4 * 4 + jj]; }
;         __builtin_amdgcn_sched_barrier(0); }
; #pragma unroll
;       for (int i = 0; i < 64; ++i) R[i * RP + t] = (hf)x[i]; }
	ds_read_b128 v[44:47], v228 offset:9280
	s_waitcnt lgkmcnt(14)
	ds_read_b128 v[48:51], v228 offset:9296
	s_waitcnt lgkmcnt(14)
	ds_read_b128 v[52:55], v228 offset:9312
	s_waitcnt lgkmcnt(14)
	ds_read_b128 v[56:59], v228 offset:9328
	s_waitcnt lgkmcnt(14)
	ds_read_b128 v[60:63], v228 offset:9344
	s_waitcnt lgkmcnt(10)
	v_fma_f32 v99, -v64, v188, v99
	v_fma_f32 v99, -v65, v189, v99
	v_fma_f32 v99, -v66, v190, v99
	v_fma_f32 v99, -v67, v191, v99
	v_fma_f32 v99, -v68, v244, v99
	v_fma_f32 v99, -v69, v245, v99
	v_fma_f32 v99, -v70, v246, v99
	v_fma_f32 v99, -v71, v247, v99
	v_fma_f32 v99, -v72, v248, v99
	v_fma_f32 v99, -v73, v249, v99
	v_fma_f32 v99, -v74, v250, v99
	v_fma_f32 v99, -v75, v251, v99
	v_fma_f32 v99, -v76, v4, v99
	v_fma_f32 v99, -v77, v5, v99
	v_fma_f32 v99, -v78, v6, v99
	v_fma_f32 v99, -v79, v7, v99
	v_fma_f32 v99, -v80, v8, v99
	v_fma_f32 v99, -v81, v9, v99
	v_fma_f32 v99, -v82, v10, v99
	v_fma_f32 v99, -v83, v11, v99
	v_fma_f32 v99, -v84, v12, v99
	v_fma_f32 v99, -v85, v13, v99
	v_fma_f32 v99, -v86, v14, v99
	v_fma_f32 v99, -v87, v15, v99
	v_fma_f32 v99, -v88, v16, v99
	v_fma_f32 v99, -v89, v17, v99
	v_fma_f32 v99, -v90, v18, v99
	v_fma_f32 v99, -v91, v19, v99
	v_fma_f32 v99, -v92, v20, v99
	v_fma_f32 v99, -v93, v21, v99
	v_fma_f32 v99, -v94, v22, v99
	v_fma_f32 v99, -v95, v23, v99
	v_fma_f32 v99, -v96, v24, v99
	v_fma_f32 v99, -v97, v25, v99
	v_fma_mixlo_f16 v240, -v98, v26, v99
	v_fma_f32 v99, -v98, v26, v99
	ds_write_b16 v232, v240 offset:25904
	ds_read_b128 v[128:131], v228 offset:9472
	ds_read_b128 v[132:135], v228 offset:9488
	ds_read_b128 v[136:139], v228 offset:9504
	ds_read_b128 v[140:143], v228 offset:9520
	s_waitcnt lgkmcnt(14)
	ds_read_b128 v[144:147], v228 offset:9536
	s_waitcnt lgkmcnt(14)
	ds_read_b128 v[148:151], v228 offset:9552
	s_waitcnt lgkmcnt(14)
	ds_read_b128 v[152:155], v228 offset:9568
	s_waitcnt lgkmcnt(14)
	ds_read_b128 v[156:159], v228 offset:9584
	s_waitcnt lgkmcnt(14)
	ds_read_b128 v[160:163], v228 offset:9600
	s_waitcnt lgkmcnt(14)
	ds_read_b128 v[164:167], v228 offset:9616
	s_waitcnt lgkmcnt(11)
	v_fma_f32 v100, -v64, v28, v100
	v_fma_f32 v100, -v65, v29, v100
	v_fma_f32 v100, -v66, v30, v100
	v_fma_f32 v100, -v67, v31, v100
	v_fma_f32 v100, -v68, v32, v100
	v_fma_f32 v100, -v69, v33, v100
	v_fma_f32 v100, -v70, v34, v100
	v_fma_f32 v100, -v71, v35, v100
	v_fma_f32 v100, -v72, v36, v100
	v_fma_f32 v100, -v73, v37, v100
	v_fma_f32 v100, -v74, v38, v100
	v_fma_f32 v100, -v75, v39, v100
	v_fma_f32 v100, -v76, v40, v100
	v_fma_f32 v100, -v77, v41, v100
	v_fma_f32 v100, -v78, v42, v100
	v_fma_f32 v100, -v79, v43, v100
	v_fma_f32 v100, -v80, v44, v100
	v_fma_f32 v100, -v81, v45, v100
	v_fma_f32 v100, -v82, v46, v100
	v_fma_f32 v100, -v83, v47, v100
	v_fma_f32 v100, -v84, v48, v100
	v_fma_f32 v100, -v85, v49, v100
	v_fma_f32 v100, -v86, v50, v100
	v_fma_f32 v100, -v87, v51, v100
	v_fma_f32 v100, -v88, v52, v100
	v_fma_f32 v100, -v89, v53, v100
	v_fma_f32 v100, -v90, v54, v100
	v_fma_f32 v100, -v91, v55, v100
	v_fma_f32 v100, -v92, v56, v100
	v_fma_f32 v100, -v93, v57, v100
	v_fma_f32 v100, -v94, v58, v100
	v_fma_f32 v100, -v95, v59, v100
	v_fma_f32 v100, -v96, v60, v100
	v_fma_f32 v100, -v97, v61, v100
	v_fma_f32 v100, -v98, v62, v100
	v_fma_mixlo_f16 v0, -v99, v63, v100
	v_fma_f32 v100, -v99, v63, v100
	ds_write_b16 v232, v0 offset:26176
	ds_read_b128 v[168:171], v228 offset:9728
	ds_read_b128 v[172:175], v228 offset:9744
	ds_read_b128 v[176:179], v228 offset:9760
	s_waitcnt lgkmcnt(14)
	ds_read_b128 v[180:183], v228 offset:9776
	s_waitcnt lgkmcnt(14)
	ds_read_b128 v[184:187], v228 offset:9792
	s_waitcnt lgkmcnt(14)
	ds_read_b128 v[188:191], v228 offset:9808
	s_waitcnt lgkmcnt(14)
	ds_read_b128 v[244:247], v228 offset:9824
	s_waitcnt lgkmcnt(14)
	ds_read_b128 v[248:251], v228 offset:9840
	s_waitcnt lgkmcnt(14)
	ds_read_b128 v[4:7], v228 offset:9856
	s_waitcnt lgkmcnt(14)
	ds_read_b128 v[8:11], v228 offset:9872
	s_waitcnt lgkmcnt(11)
	v_fma_f32 v101, -v64, v128, v101
	v_fma_f32 v101, -v65, v129, v101
	v_fma_f32 v101, -v66, v130, v101
	v_fma_f32 v101, -v67, v131, v101
	v_fma_f32 v101, -v68, v132, v101
	v_fma_f32 v101, -v69, v133, v101
	v_fma_f32 v101, -v70, v134, v101
	v_fma_f32 v101, -v71, v135, v101
	v_fma_f32 v101, -v72, v136, v101
	v_fma_f32 v101, -v73, v137, v101
	v_fma_f32 v101, -v74, v138, v101
	v_fma_f32 v101, -v75, v139, v101
	v_fma_f32 v101, -v76, v140, v101
	v_fma_f32 v101, -v77, v141, v101
	v_fma_f32 v101, -v78, v142, v101
	v_fma_f32 v101, -v79, v143, v101
	v_fma_f32 v101, -v80, v144, v101
	v_fma_f32 v101, -v81, v145, v101
	v_fma_f32 v101, -v82, v146, v101
	v_fma_f32 v101, -v83, v147, v101
	v_fma_f32 v101, -v84, v148, v101
	v_fma_f32 v101, -v85, v149, v101
	v_fma_f32 v101, -v86, v150, v101
	v_fma_f32 v101, -v87, v151, v101
	v_fma_f32 v101, -v88, v152, v101
	v_fma_f32 v101, -v89, v153, v101
	v_fma_f32 v101, -v90, v154, v101
	v_fma_f32 v101, -v91, v155, v101
	v_fma_f32 v101, -v92, v156, v101
	v_fma_f32 v101, -v93, v157, v101
	v_fma_f32 v101, -v94, v158, v101
	v_fma_f32 v101, -v95, v159, v101
	v_fma_f32 v101, -v96, v160, v101
	v_fma_f32 v101, -v97, v161, v101
	v_fma_f32 v101, -v98, v162, v101
	v_fma_f32 v101, -v99, v163, v101
	v_fma_mixlo_f16 v2, -v100, v164, v101
	v_fma_f32 v101, -v100, v164, v101
	ds_write_b16 v232, v2 offset:26448
	ds_read_b128 v[12:15], v228 offset:9984
	ds_read_b128 v[16:19], v228 offset:10000
	ds_read_b128 v[20:23], v228 offset:10016
	s_waitcnt lgkmcnt(14)
	ds_read_b128 v[24:27], v228 offset:10032
	s_waitcnt lgkmcnt(14)
	ds_read_b128 v[28:31], v228 offset:10048
	s_waitcnt lgkmcnt(14)
	ds_read_b128 v[32:35], v228 offset:10064
	s_waitcnt lgkmcnt(14)
; #define LAS __attribute__((address_space(3)))
; __device__ __forceinline__ void phase_gdb(const int wvs, const Params& p, LAS unsigned char* lds, int nwg) {
;     ...
;       for (int i = 1; i < 64; ++i) {
; #pragma unroll
;         for (int j4 = 0; j4 < (i + 3) / 4; ++j4) { const f32x4 m4 = *(const LAS f32x4*)(M + i * 64 + j4 * 4);
; #pragma unroll
;           for (int jj = 0; jj < 4; ++jj) if (j4 * 4 + jj < i) x[i] -= m4[jj] * x[j4 * 4 + jj]; }
;         __builtin_amdgcn_sched_barrier(0); }
; #pragma unroll
;       for (int i = 0; i < 64; ++i) R[i * RP + t] = (hf)x[i]; }
	ds_read_b128 v[36:39], v228 offset:10080
	s_waitcnt lgkmcnt(14)
	ds_read_b128 v[40:43], v228 offset:10096
	s_waitcnt lgkmcnt(14)
	ds_read_b128 v[44:47], v228 offset:10112
	s_waitcnt lgkmcnt(14)
	ds_read_b128 v[48:51], v228 offset:10128
	s_waitcnt lgkmcnt(11)
	v_fma_f32 v102, -v64, v168, v102
	v_fma_f32 v102, -v65, v169, v102
	v_fma_f32 v102, -v66, v170, v102
	v_fma_f32 v102, -v67, v171, v102
	v_fma_f32 v102, -v68, v172, v102
	v_fma_f32 v102, -v69, v173, v102
	v_fma_f32 v102, -v70, v174, v102
	v_fma_f32 v102, -v71, v175, v102
	v_fma_f32 v102, -v72, v176, v102
	v_fma_f32 v102, -v73, v177, v102
	v_fma_f32 v102, -v74, v178, v102
	v_fma_f32 v102, -v75, v179, v102
	v_fma_f32 v102, -v76, v180, v102
	v_fma_f32 v102, -v77, v181, v102
	v_fma_f32 v102, -v78, v182, v102
	v_fma_f32 v102, -v79, v183, v102
	v_fma_f32 v102, -v80, v184, v102
	v_fma_f32 v102, -v81, v185, v102
	v_fma_f32 v102, -v82, v186, v102
	v_fma_f32 v102, -v83, v187, v102
	v_fma_f32 v102, -v84, v188, v102
	v_fma_f32 v102, -v85, v189, v102
	v_fma_f32 v102, -v86, v190, v102
	v_fma_f32 v102, -v87, v191, v102
	v_fma_f32 v102, -v88, v244, v102
	v_fma_f32 v102, -v89, v245, v102
	v_fma_f32 v102, -v90, v246, v102
	v_fma_f32 v102, -v91, v247, v102
	v_fma_f32 v102, -v92, v248, v102
	v_fma_f32 v102, -v93, v249, v102
	v_fma_f32 v102, -v94, v250, v102
	v_fma_f32 v102, -v95, v251, v102
	v_fma_f32 v102, -v96, v4, v102
	v_fma_f32 v102, -v97, v5, v102
	v_fma_f32 v102, -v98, v6, v102
	v_fma_f32 v102, -v99, v7, v102
	v_fma_f32 v102, -v100, v8, v102
	v_fma_mixlo_f16 v3, -v101, v9, v102
	v_fma_f32 v102, -v101, v9, v102
	ds_write_b16 v232, v3 offset:26720
	ds_read_b128 v[52:55], v228 offset:10240
	ds_read_b128 v[56:59], v228 offset:10256
	ds_read_b128 v[60:63], v228 offset:10272
	s_waitcnt lgkmcnt(14)
	ds_read_b128 v[128:131], v228 offset:10288
	s_waitcnt lgkmcnt(14)
	ds_read_b128 v[132:135], v228 offset:10304
	s_waitcnt lgkmcnt(14)
	ds_read_b128 v[136:139], v228 offset:10320
	s_waitcnt lgkmcnt(14)
	ds_read_b128 v[140:143], v228 offset:10336
	s_waitcnt lgkmcnt(14)
	ds_read_b128 v[144:147], v228 offset:10352
	s_waitcnt lgkmcnt(14)
	ds_read_b128 v[148:151], v228 offset:10368
	s_waitcnt lgkmcnt(14)
	ds_read_b128 v[152:155], v228 offset:10384
	s_waitcnt lgkmcnt(11)
	v_fma_f32 v103, -v64, v12, v103
	v_fma_f32 v103, -v65, v13, v103
	v_fma_f32 v103, -v66, v14, v103
	v_fma_f32 v103, -v67, v15, v103
	v_fma_f32 v103, -v68, v16, v103
	v_fma_f32 v103, -v69, v17, v103
	v_fma_f32 v103, -v70, v18, v103
	v_fma_f32 v103, -v71, v19, v103
	v_fma_f32 v103, -v72, v20, v103
	v_fma_f32 v103, -v73, v21, v103
	v_fma_f32 v103, -v74, v22, v103
	v_fma_f32 v103, -v75, v23, v103
	v_fma_f32 v103, -v76, v24, v103
	v_fma_f32 v103, -v77, v25, v103
	v_fma_f32 v103, -v78, v26, v103
	v_fma_f32 v103, -v79, v27, v103
	v_fma_f32 v103, -v80, v28, v103
	v_fma_f32 v103, -v81, v29, v103
	v_fma_f32 v103, -v82, v30, v103
	v_fma_f32 v103, -v83, v31, v103
	v_fma_f32 v103, -v84, v32, v103
	v_fma_f32 v103, -v85, v33, v103
	v_fma_f32 v103, -v86, v34, v103
	v_fma_f32 v103, -v87, v35, v103
	v_fma_f32 v103, -v88, v36, v103
	v_fma_f32 v103, -v89, v37, v103
	v_fma_f32 v103, -v90, v38, v103
	v_fma_f32 v103, -v91, v39, v103
	v_fma_f32 v103, -v92, v40, v103
	v_fma_f32 v103, -v93, v41, v103
	v_fma_f32 v103, -v94, v42, v103
	v_fma_f32 v103, -v95, v43, v103
	v_fma_f32 v103, -v96, v44, v103
	v_fma_f32 v103, -v97, v45, v103
	v_fma_f32 v103, -v98, v46, v103
	v_fma_f32 v103, -v99, v47, v103
	v_fma_f32 v103, -v100, v48, v103
	v_fma_f32 v103, -v101, v49, v103
	v_fma_mixlo_f16 v238, -v102, v50, v103
	v_fma_f32 v103, -v102, v50, v103
	ds_write_b16 v232, v238 offset:26992
	ds_read_b128 v[156:159], v228 offset:10496
	ds_read_b128 v[160:163], v228 offset:10512
	ds_read_b128 v[164:167], v228 offset:10528
	s_waitcnt lgkmcnt(14)
	ds_read_b128 v[168:171], v228 offset:10544
	s_waitcnt lgkmcnt(14)
	ds_read_b128 v[172:175], v228 offset:10560
	s_waitcnt lgkmcnt(14)
	ds_read_b128 v[176:179], v228 offset:10576
	s_waitcnt lgkmcnt(14)
	ds_read_b128 v[180:183], v228 offset:10592
	s_waitcnt lgkmcnt(14)
	ds_read_b128 v[184:187], v228 offset:10608
	s_waitcnt lgkmcnt(14)
	ds_read_b128 v[188:191], v228 offset:10624
	s_waitcnt lgkmcnt(14)
	ds_read_b128 v[244:247], v228 offset:10640
	s_waitcnt lgkmcnt(14)
	ds_read_b128 v[248:251], v228 offset:10656
	s_waitcnt lgkmcnt(12)
	v_fma_f32 v104, -v64, v52, v104
	v_fma_f32 v104, -v65, v53, v104
	v_fma_f32 v104, -v66, v54, v104
	v_fma_f32 v104, -v67, v55, v104
	v_fma_f32 v104, -v68, v56, v104
	v_fma_f32 v104, -v69, v57, v104
	v_fma_f32 v104, -v70, v58, v104
	v_fma_f32 v104, -v71, v59, v104
	v_fma_f32 v104, -v72, v60, v104
	v_fma_f32 v104, -v73, v61, v104
	v_fma_f32 v104, -v74, v62, v104
	v_fma_f32 v104, -v75, v63, v104
	v_fma_f32 v104, -v76, v128, v104
	v_fma_f32 v104, -v77, v129, v104
	v_fma_f32 v104, -v78, v130, v104
	v_fma_f32 v104, -v79, v131, v104
	v_fma_f32 v104, -v80, v132, v104
	v_fma_f32 v104, -v81, v133, v104
	v_fma_f32 v104, -v82, v134, v104
	v_fma_f32 v104, -v83, v135, v104
	v_fma_f32 v104, -v84, v136, v104
	v_fma_f32 v104, -v85, v137, v104
	v_fma_f32 v104, -v86, v138, v104
	v_fma_f32 v104, -v87, v139, v104
	v_fma_f32 v104, -v88, v140, v104
	v_fma_f32 v104, -v89, v141, v104
	v_fma_f32 v104, -v90, v142, v104
	v_fma_f32 v104, -v91, v143, v104
	v_fma_f32 v104, -v92, v144, v104
	v_fma_f32 v104, -v93, v145, v104
	v_fma_f32 v104, -v94, v146, v104
	v_fma_f32 v104, -v95, v147, v104
	v_fma_f32 v104, -v96, v148, v104
	v_fma_f32 v104, -v97, v149, v104
	v_fma_f32 v104, -v98, v150, v104
	v_fma_f32 v104, -v99, v151, v104
	v_fma_f32 v104, -v100, v152, v104
	v_fma_f32 v104, -v101, v153, v104
	v_fma_f32 v104, -v102, v154, v104
	v_fma_mixlo_f16 v239, -v103, v155, v104
	v_fma_f32 v104, -v103, v155, v104
	ds_write_b16 v232, v239 offset:27264
	ds_read_b128 v[4:7], v228 offset:10752
	ds_read_b128 v[8:11], v228 offset:10768
	s_waitcnt lgkmcnt(14)
; #define LAS __attribute__((address_space(3)))
; __device__ __forceinline__ void phase_gdb(const int wvs, const Params& p, LAS unsigned char* lds, int nwg) {
;     ...
;       for (int i = 1; i < 64; ++i) {
; #pragma unroll
;         for (int j4 = 0; j4 < (i + 3) / 4; ++j4) { const f32x4 m4 = *(const LAS f32x4*)(M + i * 64 + j4 * 4);
; #pragma unroll
;           for (int jj = 0; jj < 4; ++jj) if (j4 * 4 + jj < i) x[i] -= m4[jj] * x[j4 * 4 + jj]; }
;         __builtin_amdgcn_sched_barrier(0); }
; #pragma unroll
;       for (int i = 0; i < 64; ++i) R[i * RP + t] = (hf)x[i]; }
	ds_read_b128 v[12:15], v228 offset:10784
	s_waitcnt lgkmcnt(14)
	ds_read_b128 v[16:19], v228 offset:10800
	s_waitcnt lgkmcnt(14)
	ds_read_b128 v[20:23], v228 offset:10816
	s_waitcnt lgkmcnt(14)
	ds_read_b128 v[24:27], v228 offset:10832
	s_waitcnt lgkmcnt(14)
	ds_read_b128 v[28:31], v228 offset:10848
	s_waitcnt lgkmcnt(14)
	ds_read_b128 v[32:35], v228 offset:10864
	s_waitcnt lgkmcnt(14)
	ds_read_b128 v[36:39], v228 offset:10880
	s_waitcnt lgkmcnt(14)
	ds_read_b128 v[40:43], v228 offset:10896
	s_waitcnt lgkmcnt(14)
	ds_read_b128 v[44:47], v228 offset:10912
	s_waitcnt lgkmcnt(12)
	v_fma_f32 v105, -v64, v156, v105
	v_fma_f32 v105, -v65, v157, v105
	v_fma_f32 v105, -v66, v158, v105
	v_fma_f32 v105, -v67, v159, v105
	v_fma_f32 v105, -v68, v160, v105
	v_fma_f32 v105, -v69, v161, v105
	v_fma_f32 v105, -v70, v162, v105
	v_fma_f32 v105, -v71, v163, v105
	v_fma_f32 v105, -v72, v164, v105
	v_fma_f32 v105, -v73, v165, v105
	v_fma_f32 v105, -v74, v166, v105
	v_fma_f32 v105, -v75, v167, v105
	v_fma_f32 v105, -v76, v168, v105
	v_fma_f32 v105, -v77, v169, v105
	v_fma_f32 v105, -v78, v170, v105
	v_fma_f32 v105, -v79, v171, v105
	v_fma_f32 v105, -v80, v172, v105
	v_fma_f32 v105, -v81, v173, v105
	v_fma_f32 v105, -v82, v174, v105
	v_fma_f32 v105, -v83, v175, v105
	v_fma_f32 v105, -v84, v176, v105
	v_fma_f32 v105, -v85, v177, v105
	v_fma_f32 v105, -v86, v178, v105
	v_fma_f32 v105, -v87, v179, v105
	v_fma_f32 v105, -v88, v180, v105
	v_fma_f32 v105, -v89, v181, v105
	v_fma_f32 v105, -v90, v182, v105
	v_fma_f32 v105, -v91, v183, v105
	v_fma_f32 v105, -v92, v184, v105
	v_fma_f32 v105, -v93, v185, v105
	v_fma_f32 v105, -v94, v186, v105
	v_fma_f32 v105, -v95, v187, v105
	v_fma_f32 v105, -v96, v188, v105
	v_fma_f32 v105, -v97, v189, v105
	v_fma_f32 v105, -v98, v190, v105
	v_fma_f32 v105, -v99, v191, v105
	v_fma_f32 v105, -v100, v244, v105
	v_fma_f32 v105, -v101, v245, v105
	v_fma_f32 v105, -v102, v246, v105
	v_fma_f32 v105, -v103, v247, v105
	v_fma_mixlo_f16 v240, -v104, v248, v105
	v_fma_f32 v105, -v104, v248, v105
	ds_write_b16 v232, v240 offset:27536
	ds_read_b128 v[48:51], v228 offset:11008
	ds_read_b128 v[52:55], v228 offset:11024
	s_waitcnt lgkmcnt(14)
	ds_read_b128 v[56:59], v228 offset:11040
	s_waitcnt lgkmcnt(14)
	ds_read_b128 v[60:63], v228 offset:11056
	s_waitcnt lgkmcnt(14)
	ds_read_b128 v[128:131], v228 offset:11072
	s_waitcnt lgkmcnt(14)
	ds_read_b128 v[132:135], v228 offset:11088
	s_waitcnt lgkmcnt(14)
	ds_read_b128 v[136:139], v228 offset:11104
	s_waitcnt lgkmcnt(14)
	ds_read_b128 v[140:143], v228 offset:11120
	s_waitcnt lgkmcnt(14)
	ds_read_b128 v[144:147], v228 offset:11136
	s_waitcnt lgkmcnt(14)
	ds_read_b128 v[148:151], v228 offset:11152
	s_waitcnt lgkmcnt(14)
	ds_read_b128 v[152:155], v228 offset:11168
	s_waitcnt lgkmcnt(12)
	v_fma_f32 v106, -v64, v4, v106
	v_fma_f32 v106, -v65, v5, v106
	v_fma_f32 v106, -v66, v6, v106
	v_fma_f32 v106, -v67, v7, v106
	v_fma_f32 v106, -v68, v8, v106
	v_fma_f32 v106, -v69, v9, v106
	v_fma_f32 v106, -v70, v10, v106
	v_fma_f32 v106, -v71, v11, v106
	v_fma_f32 v106, -v72, v12, v106
	v_fma_f32 v106, -v73, v13, v106
	v_fma_f32 v106, -v74, v14, v106
	v_fma_f32 v106, -v75, v15, v106
	v_fma_f32 v106, -v76, v16, v106
	v_fma_f32 v106, -v77, v17, v106
	v_fma_f32 v106, -v78, v18, v106
	v_fma_f32 v106, -v79, v19, v106
	v_fma_f32 v106, -v80, v20, v106
	v_fma_f32 v106, -v81, v21, v106
	v_fma_f32 v106, -v82, v22, v106
	v_fma_f32 v106, -v83, v23, v106
	v_fma_f32 v106, -v84, v24, v106
	v_fma_f32 v106, -v85, v25, v106
	v_fma_f32 v106, -v86, v26, v106
	v_fma_f32 v106, -v87, v27, v106
	v_fma_f32 v106, -v88, v28, v106
	v_fma_f32 v106, -v89, v29, v106
	v_fma_f32 v106, -v90, v30, v106
	v_fma_f32 v106, -v91, v31, v106
	v_fma_f32 v106, -v92, v32, v106
	v_fma_f32 v106, -v93, v33, v106
	v_fma_f32 v106, -v94, v34, v106
	v_fma_f32 v106, -v95, v35, v106
	v_fma_f32 v106, -v96, v36, v106
	v_fma_f32 v106, -v97, v37, v106
	v_fma_f32 v106, -v98, v38, v106
	v_fma_f32 v106, -v99, v39, v106
	v_fma_f32 v106, -v100, v40, v106
	v_fma_f32 v106, -v101, v41, v106
	v_fma_f32 v106, -v102, v42, v106
	v_fma_f32 v106, -v103, v43, v106
	v_fma_f32 v106, -v104, v44, v106
	v_fma_mixlo_f16 v0, -v105, v45, v106
	v_fma_f32 v106, -v105, v45, v106
	ds_write_b16 v232, v0 offset:27808
	ds_read_b128 v[156:159], v228 offset:11264
	ds_read_b128 v[160:163], v228 offset:11280
	s_waitcnt lgkmcnt(14)
	ds_read_b128 v[164:167], v228 offset:11296
	s_waitcnt lgkmcnt(14)
	ds_read_b128 v[168:171], v228 offset:11312
	s_waitcnt lgkmcnt(14)
	ds_read_b128 v[172:175], v228 offset:11328
	s_waitcnt lgkmcnt(14)
	ds_read_b128 v[176:179], v228 offset:11344
	s_waitcnt lgkmcnt(14)
	ds_read_b128 v[180:183], v228 offset:11360
	s_waitcnt lgkmcnt(14)
	ds_read_b128 v[184:187], v228 offset:11376
	s_waitcnt lgkmcnt(14)
	ds_read_b128 v[188:191], v228 offset:11392
	s_waitcnt lgkmcnt(14)
	ds_read_b128 v[244:247], v228 offset:11408
	s_waitcnt lgkmcnt(14)
	ds_read_b128 v[248:251], v228 offset:11424
	s_waitcnt lgkmcnt(12)
; #define LAS __attribute__((address_space(3)))
; __device__ __forceinline__ void phase_gdb(const int wvs, const Params& p, LAS unsigned char* lds, int nwg) {
;     ...
;       for (int i = 1; i < 64; ++i) {
; #pragma unroll
;         for (int j4 = 0; j4 < (i + 3) / 4; ++j4) { const f32x4 m4 = *(const LAS f32x4*)(M + i * 64 + j4 * 4);
; #pragma unroll
;           for (int jj = 0; jj < 4; ++jj) if (j4 * 4 + jj < i) x[i] -= m4[jj] * x[j4 * 4 + jj]; }
;         __builtin_amdgcn_sched_barrier(0); }
; #pragma unroll
;       for (int i = 0; i < 64; ++i) R[i * RP + t] = (hf)x[i]; }
	v_fma_f32 v107, -v64, v48, v107
	v_fma_f32 v107, -v65, v49, v107
	v_fma_f32 v107, -v66, v50, v107
	v_fma_f32 v107, -v67, v51, v107
	v_fma_f32 v107, -v68, v52, v107
	v_fma_f32 v107, -v69, v53, v107
	v_fma_f32 v107, -v70, v54, v107
	v_fma_f32 v107, -v71, v55, v107
	v_fma_f32 v107, -v72, v56, v107
	v_fma_f32 v107, -v73, v57, v107
	v_fma_f32 v107, -v74, v58, v107
	v_fma_f32 v107, -v75, v59, v107
	v_fma_f32 v107, -v76, v60, v107
	v_fma_f32 v107, -v77, v61, v107
	v_fma_f32 v107, -v78, v62, v107
	v_fma_f32 v107, -v79, v63, v107
	v_fma_f32 v107, -v80, v128, v107
	v_fma_f32 v107, -v81, v129, v107
	v_fma_f32 v107, -v82, v130, v107
	v_fma_f32 v107, -v83, v131, v107
	v_fma_f32 v107, -v84, v132, v107
	v_fma_f32 v107, -v85, v133, v107
	v_fma_f32 v107, -v86, v134, v107
	v_fma_f32 v107, -v87, v135, v107
	v_fma_f32 v107, -v88, v136, v107
	v_fma_f32 v107, -v89, v137, v107
	v_fma_f32 v107, -v90, v138, v107
	v_fma_f32 v107, -v91, v139, v107
	v_fma_f32 v107, -v92, v140, v107
	v_fma_f32 v107, -v93, v141, v107
	v_fma_f32 v107, -v94, v142, v107
	v_fma_f32 v107, -v95, v143, v107
	v_fma_f32 v107, -v96, v144, v107
	v_fma_f32 v107, -v97, v145, v107
	v_fma_f32 v107, -v98, v146, v107
	v_fma_f32 v107, -v99, v147, v107
	v_fma_f32 v107, -v100, v148, v107
	v_fma_f32 v107, -v101, v149, v107
	v_fma_f32 v107, -v102, v150, v107
	v_fma_f32 v107, -v103, v151, v107
	v_fma_f32 v107, -v104, v152, v107
	v_fma_f32 v107, -v105, v153, v107
	v_fma_mixlo_f16 v2, -v106, v154, v107
	v_fma_f32 v107, -v106, v154, v107
	ds_write_b16 v232, v2 offset:28080
	ds_read_b128 v[4:7], v228 offset:11520
	ds_read_b128 v[8:11], v228 offset:11536
	s_waitcnt lgkmcnt(14)
	ds_read_b128 v[12:15], v228 offset:11552
	s_waitcnt lgkmcnt(14)
	ds_read_b128 v[16:19], v228 offset:11568
	s_waitcnt lgkmcnt(14)
	ds_read_b128 v[20:23], v228 offset:11584
	s_waitcnt lgkmcnt(14)
	ds_read_b128 v[24:27], v228 offset:11600
	s_waitcnt lgkmcnt(14)
	ds_read_b128 v[28:31], v228 offset:11616
	s_waitcnt lgkmcnt(14)
	ds_read_b128 v[32:35], v228 offset:11632
	s_waitcnt lgkmcnt(14)
	ds_read_b128 v[36:39], v228 offset:11648
	s_waitcnt lgkmcnt(14)
	ds_read_b128 v[40:43], v228 offset:11664
	s_waitcnt lgkmcnt(14)
	ds_read_b128 v[44:47], v228 offset:11680
	s_waitcnt lgkmcnt(14)
	ds_read_b128 v[48:51], v228 offset:11696
	s_waitcnt lgkmcnt(13)
	v_fma_f32 v108, -v64, v156, v108
	v_fma_f32 v108, -v65, v157, v108
	v_fma_f32 v108, -v66, v158, v108
	v_fma_f32 v108, -v67, v159, v108
	v_fma_f32 v108, -v68, v160, v108
	v_fma_f32 v108, -v69, v161, v108
	v_fma_f32 v108, -v70, v162, v108
	v_fma_f32 v108, -v71, v163, v108
	v_fma_f32 v108, -v72, v164, v108
	v_fma_f32 v108, -v73, v165, v108
	v_fma_f32 v108, -v74, v166, v108
	v_fma_f32 v108, -v75, v167, v108
	v_fma_f32 v108, -v76, v168, v108
	v_fma_f32 v108, -v77, v169, v108
	v_fma_f32 v108, -v78, v170, v108
	v_fma_f32 v108, -v79, v171, v108
	v_fma_f32 v108, -v80, v172, v108
	v_fma_f32 v108, -v81, v173, v108
	v_fma_f32 v108, -v82, v174, v108
	v_fma_f32 v108, -v83, v175, v108
	v_fma_f32 v108, -v84, v176, v108
	v_fma_f32 v108, -v85, v177, v108
	v_fma_f32 v108, -v86, v178, v108
	v_fma_f32 v108, -v87, v179, v108
	v_fma_f32 v108, -v88, v180, v108
	v_fma_f32 v108, -v89, v181, v108
	v_fma_f32 v108, -v90, v182, v108
	v_fma_f32 v108, -v91, v183, v108
	v_fma_f32 v108, -v92, v184, v108
	v_fma_f32 v108, -v93, v185, v108
	v_fma_f32 v108, -v94, v186, v108
	v_fma_f32 v108, -v95, v187, v108
	v_fma_f32 v108, -v96, v188, v108
	v_fma_f32 v108, -v97, v189, v108
	v_fma_f32 v108, -v98, v190, v108
	v_fma_f32 v108, -v99, v191, v108
	v_fma_f32 v108, -v100, v244, v108
	v_fma_f32 v108, -v101, v245, v108
	v_fma_f32 v108, -v102, v246, v108
	v_fma_f32 v108, -v103, v247, v108
	v_fma_f32 v108, -v104, v248, v108
	v_fma_f32 v108, -v105, v249, v108
	v_fma_f32 v108, -v106, v250, v108
	v_fma_mixlo_f16 v3, -v107, v251, v108
	v_fma_f32 v108, -v107, v251, v108
	ds_write_b16 v232, v3 offset:28352
	ds_read_b128 v[52:55], v228 offset:11776
	s_waitcnt lgkmcnt(14)
	ds_read_b128 v[56:59], v228 offset:11792
	s_waitcnt lgkmcnt(14)
	ds_read_b128 v[60:63], v228 offset:11808
	s_waitcnt lgkmcnt(14)
	ds_read_b128 v[128:131], v228 offset:11824
	s_waitcnt lgkmcnt(14)
	ds_read_b128 v[132:135], v228 offset:11840
	s_waitcnt lgkmcnt(14)
	ds_read_b128 v[136:139], v228 offset:11856
	s_waitcnt lgkmcnt(14)
	ds_read_b128 v[140:143], v228 offset:11872
	s_waitcnt lgkmcnt(14)
	ds_read_b128 v[144:147], v228 offset:11888
	s_waitcnt lgkmcnt(14)
	ds_read_b128 v[148:151], v228 offset:11904
	s_waitcnt lgkmcnt(14)
	ds_read_b128 v[152:155], v228 offset:11920
	s_waitcnt lgkmcnt(14)
	ds_read_b128 v[156:159], v228 offset:11936
	s_waitcnt lgkmcnt(14)
	ds_read_b128 v[160:163], v228 offset:11952
	s_waitcnt lgkmcnt(13)
	v_fma_f32 v109, -v64, v4, v109
	v_fma_f32 v109, -v65, v5, v109
	v_fma_f32 v109, -v66, v6, v109
	v_fma_f32 v109, -v67, v7, v109
	v_fma_f32 v109, -v68, v8, v109
	v_fma_f32 v109, -v69, v9, v109
	v_fma_f32 v109, -v70, v10, v109
	v_fma_f32 v109, -v71, v11, v109
	v_fma_f32 v109, -v72, v12, v109
	v_fma_f32 v109, -v73, v13, v109
	v_fma_f32 v109, -v74, v14, v109
	v_fma_f32 v109, -v75, v15, v109
	v_fma_f32 v109, -v76, v16, v109
	v_fma_f32 v109, -v77, v17, v109
	v_fma_f32 v109, -v78, v18, v109
	v_fma_f32 v109, -v79, v19, v109
	v_fma_f32 v109, -v80, v20, v109
	v_fma_f32 v109, -v81, v21, v109
	v_fma_f32 v109, -v82, v22, v109
	v_fma_f32 v109, -v83, v23, v109
	v_fma_f32 v109, -v84, v24, v109
	v_fma_f32 v109, -v85, v25, v109
	v_fma_f32 v109, -v86, v26, v109
	v_fma_f32 v109, -v87, v27, v109
	v_fma_f32 v109, -v88, v28, v109
	v_fma_f32 v109, -v89, v29, v109
	v_fma_f32 v109, -v90, v30, v109
	v_fma_f32 v109, -v91, v31, v109
	v_fma_f32 v109, -v92, v32, v109
	v_fma_f32 v109, -v93, v33, v109
	v_fma_f32 v109, -v94, v34, v109
	v_fma_f32 v109, -v95, v35, v109
	v_fma_f32 v109, -v96, v36, v109
	v_fma_f32 v109, -v97, v37, v109
	v_fma_f32 v109, -v98, v38, v109
	v_fma_f32 v109, -v99, v39, v109
	v_fma_f32 v109, -v100, v40, v109
	v_fma_f32 v109, -v101, v41, v109
	v_fma_f32 v109, -v102, v42, v109
	v_fma_f32 v109, -v103, v43, v109
	v_fma_f32 v109, -v104, v44, v109
	v_fma_f32 v109, -v105, v45, v109
	v_fma_f32 v109, -v106, v46, v109
	v_fma_f32 v109, -v107, v47, v109
	v_fma_mixlo_f16 v238, -v108, v48, v109
	v_fma_f32 v109, -v108, v48, v109
	ds_write_b16 v232, v238 offset:28624
	ds_read_b128 v[164:167], v228 offset:12032
	s_waitcnt lgkmcnt(14)
; #define LAS __attribute__((address_space(3)))
; __device__ __forceinline__ void phase_gdb(const int wvs, const Params& p, LAS unsigned char* lds, int nwg) {
;     ...
;       for (int i = 1; i < 64; ++i) {
; #pragma unroll
;         for (int j4 = 0; j4 < (i + 3) / 4; ++j4) { const f32x4 m4 = *(const LAS f32x4*)(M + i * 64 + j4 * 4);
; #pragma unroll
;           for (int jj = 0; jj < 4; ++jj) if (j4 * 4 + jj < i) x[i] -= m4[jj] * x[j4 * 4 + jj]; }
;         __builtin_amdgcn_sched_barrier(0); }
; #pragma unroll
;       for (int i = 0; i < 64; ++i) R[i * RP + t] = (hf)x[i]; }
	ds_read_b128 v[168:171], v228 offset:12048
	s_waitcnt lgkmcnt(14)
	ds_read_b128 v[172:175], v228 offset:12064
	s_waitcnt lgkmcnt(14)
	ds_read_b128 v[176:179], v228 offset:12080
	s_waitcnt lgkmcnt(14)
	ds_read_b128 v[180:183], v228 offset:12096
	s_waitcnt lgkmcnt(14)
	ds_read_b128 v[184:187], v228 offset:12112
	s_waitcnt lgkmcnt(14)
	ds_read_b128 v[188:191], v228 offset:12128
	s_waitcnt lgkmcnt(14)
	ds_read_b128 v[244:247], v228 offset:12144
	s_waitcnt lgkmcnt(14)
	ds_read_b128 v[248:251], v228 offset:12160
	s_waitcnt lgkmcnt(14)
	ds_read_b128 v[4:7], v228 offset:12176
	s_waitcnt lgkmcnt(14)
	ds_read_b128 v[8:11], v228 offset:12192
	s_waitcnt lgkmcnt(14)
	ds_read_b128 v[12:15], v228 offset:12208
	s_waitcnt lgkmcnt(13)
	v_fma_f32 v110, -v64, v52, v110
	v_fma_f32 v110, -v65, v53, v110
	v_fma_f32 v110, -v66, v54, v110
	v_fma_f32 v110, -v67, v55, v110
	v_fma_f32 v110, -v68, v56, v110
	v_fma_f32 v110, -v69, v57, v110
	v_fma_f32 v110, -v70, v58, v110
	v_fma_f32 v110, -v71, v59, v110
	v_fma_f32 v110, -v72, v60, v110
	v_fma_f32 v110, -v73, v61, v110
	v_fma_f32 v110, -v74, v62, v110
	v_fma_f32 v110, -v75, v63, v110
	v_fma_f32 v110, -v76, v128, v110
	v_fma_f32 v110, -v77, v129, v110
	v_fma_f32 v110, -v78, v130, v110
	v_fma_f32 v110, -v79, v131, v110
	v_fma_f32 v110, -v80, v132, v110
	v_fma_f32 v110, -v81, v133, v110
	v_fma_f32 v110, -v82, v134, v110
	v_fma_f32 v110, -v83, v135, v110
	v_fma_f32 v110, -v84, v136, v110
	v_fma_f32 v110, -v85, v137, v110
	v_fma_f32 v110, -v86, v138, v110
	v_fma_f32 v110, -v87, v139, v110
	v_fma_f32 v110, -v88, v140, v110
	v_fma_f32 v110, -v89, v141, v110
	v_fma_f32 v110, -v90, v142, v110
	v_fma_f32 v110, -v91, v143, v110
	v_fma_f32 v110, -v92, v144, v110
	v_fma_f32 v110, -v93, v145, v110
	v_fma_f32 v110, -v94, v146, v110
	v_fma_f32 v110, -v95, v147, v110
	v_fma_f32 v110, -v96, v148, v110
	v_fma_f32 v110, -v97, v149, v110
	v_fma_f32 v110, -v98, v150, v110
	v_fma_f32 v110, -v99, v151, v110
	v_fma_f32 v110, -v100, v152, v110
	v_fma_f32 v110, -v101, v153, v110
	v_fma_f32 v110, -v102, v154, v110
	v_fma_f32 v110, -v103, v155, v110
	v_fma_f32 v110, -v104, v156, v110
	v_fma_f32 v110, -v105, v157, v110
	v_fma_f32 v110, -v106, v158, v110
	v_fma_f32 v110, -v107, v159, v110
	v_fma_f32 v110, -v108, v160, v110
	v_fma_mixlo_f16 v239, -v109, v161, v110
	v_fma_f32 v110, -v109, v161, v110
	ds_write_b16 v232, v239 offset:28896
	ds_read_b128 v[16:19], v228 offset:12288
	s_waitcnt lgkmcnt(14)
	ds_read_b128 v[20:23], v228 offset:12304
	s_waitcnt lgkmcnt(14)
	ds_read_b128 v[24:27], v228 offset:12320
	s_waitcnt lgkmcnt(14)
	ds_read_b128 v[28:31], v228 offset:12336
	s_waitcnt lgkmcnt(14)
	ds_read_b128 v[32:35], v228 offset:12352
	s_waitcnt lgkmcnt(14)
	ds_read_b128 v[36:39], v228 offset:12368
	s_waitcnt lgkmcnt(14)
	ds_read_b128 v[40:43], v228 offset:12384
	s_waitcnt lgkmcnt(14)
	ds_read_b128 v[44:47], v228 offset:12400
	s_waitcnt lgkmcnt(14)
	ds_read_b128 v[48:51], v228 offset:12416
	s_waitcnt lgkmcnt(14)
	ds_read_b128 v[52:55], v228 offset:12432
	s_waitcnt lgkmcnt(14)
	ds_read_b128 v[56:59], v228 offset:12448
	s_waitcnt lgkmcnt(14)
	ds_read_b128 v[60:63], v228 offset:12464
	s_waitcnt lgkmcnt(13)
	v_fma_f32 v111, -v64, v164, v111
	v_fma_f32 v111, -v65, v165, v111
	v_fma_f32 v111, -v66, v166, v111
	v_fma_f32 v111, -v67, v167, v111
	v_fma_f32 v111, -v68, v168, v111
	v_fma_f32 v111, -v69, v169, v111
	v_fma_f32 v111, -v70, v170, v111
	v_fma_f32 v111, -v71, v171, v111
	v_fma_f32 v111, -v72, v172, v111
	v_fma_f32 v111, -v73, v173, v111
	v_fma_f32 v111, -v74, v174, v111
	v_fma_f32 v111, -v75, v175, v111
	v_fma_f32 v111, -v76, v176, v111
	v_fma_f32 v111, -v77, v177, v111
	v_fma_f32 v111, -v78, v178, v111
	v_fma_f32 v111, -v79, v179, v111
	v_fma_f32 v111, -v80, v180, v111
	v_fma_f32 v111, -v81, v181, v111
	v_fma_f32 v111, -v82, v182, v111
	v_fma_f32 v111, -v83, v183, v111
	v_fma_f32 v111, -v84, v184, v111
	v_fma_f32 v111, -v85, v185, v111
	v_fma_f32 v111, -v86, v186, v111
	v_fma_f32 v111, -v87, v187, v111
	v_fma_f32 v111, -v88, v188, v111
	v_fma_f32 v111, -v89, v189, v111
	v_fma_f32 v111, -v90, v190, v111
	v_fma_f32 v111, -v91, v191, v111
	v_fma_f32 v111, -v92, v244, v111
	v_fma_f32 v111, -v93, v245, v111
	v_fma_f32 v111, -v94, v246, v111
	v_fma_f32 v111, -v95, v247, v111
	v_fma_f32 v111, -v96, v248, v111
	v_fma_f32 v111, -v97, v249, v111
	v_fma_f32 v111, -v98, v250, v111
	v_fma_f32 v111, -v99, v251, v111
	v_fma_f32 v111, -v100, v4, v111
	v_fma_f32 v111, -v101, v5, v111
	v_fma_f32 v111, -v102, v6, v111
	v_fma_f32 v111, -v103, v7, v111
	v_fma_f32 v111, -v104, v8, v111
	v_fma_f32 v111, -v105, v9, v111
	v_fma_f32 v111, -v106, v10, v111
	v_fma_f32 v111, -v107, v11, v111
	v_fma_f32 v111, -v108, v12, v111
	v_fma_f32 v111, -v109, v13, v111
	v_fma_mixlo_f16 v240, -v110, v14, v111
	v_fma_f32 v111, -v110, v14, v111
	ds_write_b16 v232, v240 offset:29168
	ds_read_b128 v[128:131], v228 offset:12544
	s_waitcnt lgkmcnt(14)
	ds_read_b128 v[132:135], v228 offset:12560
	s_waitcnt lgkmcnt(14)
	ds_read_b128 v[136:139], v228 offset:12576
	s_waitcnt lgkmcnt(14)
	ds_read_b128 v[140:143], v228 offset:12592
	s_waitcnt lgkmcnt(14)
	ds_read_b128 v[144:147], v228 offset:12608
	s_waitcnt lgkmcnt(14)
	ds_read_b128 v[148:151], v228 offset:12624
	s_waitcnt lgkmcnt(14)
	ds_read_b128 v[152:155], v228 offset:12640
	s_waitcnt lgkmcnt(14)
	ds_read_b128 v[156:159], v228 offset:12656
	s_waitcnt lgkmcnt(14)
	ds_read_b128 v[160:163], v228 offset:12672
	s_waitcnt lgkmcnt(14)
	ds_read_b128 v[164:167], v228 offset:12688
	s_waitcnt lgkmcnt(14)
	ds_read_b128 v[168:171], v228 offset:12704
	s_waitcnt lgkmcnt(14)
	ds_read_b128 v[172:175], v228 offset:12720
	s_waitcnt lgkmcnt(14)
; #define LAS __attribute__((address_space(3)))
; __device__ __forceinline__ void phase_gdb(const int wvs, const Params& p, LAS unsigned char* lds, int nwg) {
;     ...
;       for (int i = 1; i < 64; ++i) {
; #pragma unroll
;         for (int j4 = 0; j4 < (i + 3) / 4; ++j4) { const f32x4 m4 = *(const LAS f32x4*)(M + i * 64 + j4 * 4);
; #pragma unroll
;           for (int jj = 0; jj < 4; ++jj) if (j4 * 4 + jj < i) x[i] -= m4[jj] * x[j4 * 4 + jj]; }
;         __builtin_amdgcn_sched_barrier(0); }
; #pragma unroll
;       for (int i = 0; i < 64; ++i) R[i * RP + t] = (hf)x[i]; }
	ds_read_b128 v[176:179], v228 offset:12736
	s_waitcnt lgkmcnt(14)
	v_fma_f32 v112, -v64, v16, v112
	v_fma_f32 v112, -v65, v17, v112
	v_fma_f32 v112, -v66, v18, v112
	v_fma_f32 v112, -v67, v19, v112
	v_fma_f32 v112, -v68, v20, v112
	v_fma_f32 v112, -v69, v21, v112
	v_fma_f32 v112, -v70, v22, v112
	v_fma_f32 v112, -v71, v23, v112
	v_fma_f32 v112, -v72, v24, v112
	v_fma_f32 v112, -v73, v25, v112
	v_fma_f32 v112, -v74, v26, v112
	v_fma_f32 v112, -v75, v27, v112
	v_fma_f32 v112, -v76, v28, v112
	v_fma_f32 v112, -v77, v29, v112
	v_fma_f32 v112, -v78, v30, v112
	v_fma_f32 v112, -v79, v31, v112
	v_fma_f32 v112, -v80, v32, v112
	v_fma_f32 v112, -v81, v33, v112
	v_fma_f32 v112, -v82, v34, v112
	v_fma_f32 v112, -v83, v35, v112
	v_fma_f32 v112, -v84, v36, v112
	v_fma_f32 v112, -v85, v37, v112
	v_fma_f32 v112, -v86, v38, v112
	v_fma_f32 v112, -v87, v39, v112
	v_fma_f32 v112, -v88, v40, v112
	v_fma_f32 v112, -v89, v41, v112
	v_fma_f32 v112, -v90, v42, v112
	v_fma_f32 v112, -v91, v43, v112
	v_fma_f32 v112, -v92, v44, v112
	v_fma_f32 v112, -v93, v45, v112
	v_fma_f32 v112, -v94, v46, v112
	v_fma_f32 v112, -v95, v47, v112
	v_fma_f32 v112, -v96, v48, v112
	v_fma_f32 v112, -v97, v49, v112
	v_fma_f32 v112, -v98, v50, v112
	v_fma_f32 v112, -v99, v51, v112
	v_fma_f32 v112, -v100, v52, v112
	v_fma_f32 v112, -v101, v53, v112
	v_fma_f32 v112, -v102, v54, v112
	v_fma_f32 v112, -v103, v55, v112
	v_fma_f32 v112, -v104, v56, v112
	v_fma_f32 v112, -v105, v57, v112
	v_fma_f32 v112, -v106, v58, v112
	v_fma_f32 v112, -v107, v59, v112
	v_fma_f32 v112, -v108, v60, v112
	v_fma_f32 v112, -v109, v61, v112
	v_fma_f32 v112, -v110, v62, v112
	v_fma_mixlo_f16 v0, -v111, v63, v112
	v_fma_f32 v112, -v111, v63, v112
	ds_write_b16 v232, v0 offset:29440
	s_waitcnt lgkmcnt(14)
	ds_read_b128 v[180:183], v228 offset:12800
	s_waitcnt lgkmcnt(14)
	ds_read_b128 v[184:187], v228 offset:12816
	s_waitcnt lgkmcnt(14)
	ds_read_b128 v[188:191], v228 offset:12832
	s_waitcnt lgkmcnt(14)
	ds_read_b128 v[244:247], v228 offset:12848
	s_waitcnt lgkmcnt(14)
	ds_read_b128 v[248:251], v228 offset:12864
	s_waitcnt lgkmcnt(14)
	ds_read_b128 v[4:7], v228 offset:12880
	s_waitcnt lgkmcnt(14)
	ds_read_b128 v[8:11], v228 offset:12896
	s_waitcnt lgkmcnt(14)
	ds_read_b128 v[12:15], v228 offset:12912
	s_waitcnt lgkmcnt(14)
	ds_read_b128 v[16:19], v228 offset:12928
	s_waitcnt lgkmcnt(14)
	ds_read_b128 v[20:23], v228 offset:12944
	s_waitcnt lgkmcnt(14)
	ds_read_b128 v[24:27], v228 offset:12960
	s_waitcnt lgkmcnt(14)
	ds_read_b128 v[28:31], v228 offset:12976
	s_waitcnt lgkmcnt(14)
	ds_read_b128 v[32:35], v228 offset:12992
	s_waitcnt lgkmcnt(14)
	v_fma_f32 v113, -v64, v128, v113
	v_fma_f32 v113, -v65, v129, v113
	v_fma_f32 v113, -v66, v130, v113
	v_fma_f32 v113, -v67, v131, v113
	v_fma_f32 v113, -v68, v132, v113
	v_fma_f32 v113, -v69, v133, v113
	v_fma_f32 v113, -v70, v134, v113
	v_fma_f32 v113, -v71, v135, v113
	v_fma_f32 v113, -v72, v136, v113
	v_fma_f32 v113, -v73, v137, v113
	v_fma_f32 v113, -v74, v138, v113
	v_fma_f32 v113, -v75, v139, v113
	v_fma_f32 v113, -v76, v140, v113
	v_fma_f32 v113, -v77, v141, v113
	v_fma_f32 v113, -v78, v142, v113
	v_fma_f32 v113, -v79, v143, v113
	v_fma_f32 v113, -v80, v144, v113
	v_fma_f32 v113, -v81, v145, v113
	v_fma_f32 v113, -v82, v146, v113
	v_fma_f32 v113, -v83, v147, v113
	v_fma_f32 v113, -v84, v148, v113
	v_fma_f32 v113, -v85, v149, v113
	v_fma_f32 v113, -v86, v150, v113
	v_fma_f32 v113, -v87, v151, v113
	v_fma_f32 v113, -v88, v152, v113
	v_fma_f32 v113, -v89, v153, v113
	v_fma_f32 v113, -v90, v154, v113
	v_fma_f32 v113, -v91, v155, v113
	v_fma_f32 v113, -v92, v156, v113
	v_fma_f32 v113, -v93, v157, v113
	v_fma_f32 v113, -v94, v158, v113
	v_fma_f32 v113, -v95, v159, v113
	v_fma_f32 v113, -v96, v160, v113
	v_fma_f32 v113, -v97, v161, v113
	v_fma_f32 v113, -v98, v162, v113
	v_fma_f32 v113, -v99, v163, v113
	v_fma_f32 v113, -v100, v164, v113
	v_fma_f32 v113, -v101, v165, v113
	v_fma_f32 v113, -v102, v166, v113
	v_fma_f32 v113, -v103, v167, v113
	v_fma_f32 v113, -v104, v168, v113
	v_fma_f32 v113, -v105, v169, v113
	v_fma_f32 v113, -v106, v170, v113
	v_fma_f32 v113, -v107, v171, v113
	v_fma_f32 v113, -v108, v172, v113
	v_fma_f32 v113, -v109, v173, v113
	v_fma_f32 v113, -v110, v174, v113
	v_fma_f32 v113, -v111, v175, v113
	v_fma_mixlo_f16 v2, -v112, v176, v113
	v_fma_f32 v113, -v112, v176, v113
	ds_write_b16 v232, v2 offset:29712
	s_waitcnt lgkmcnt(14)
	ds_read_b128 v[36:39], v228 offset:13056
	s_waitcnt lgkmcnt(14)
	ds_read_b128 v[40:43], v228 offset:13072
	s_waitcnt lgkmcnt(14)
	ds_read_b128 v[44:47], v228 offset:13088
	s_waitcnt lgkmcnt(14)
	ds_read_b128 v[48:51], v228 offset:13104
	s_waitcnt lgkmcnt(14)
	ds_read_b128 v[52:55], v228 offset:13120
	s_waitcnt lgkmcnt(14)
	ds_read_b128 v[56:59], v228 offset:13136
	s_waitcnt lgkmcnt(14)
	ds_read_b128 v[60:63], v228 offset:13152
	s_waitcnt lgkmcnt(14)
	ds_read_b128 v[128:131], v228 offset:13168
	s_waitcnt lgkmcnt(14)
	ds_read_b128 v[132:135], v228 offset:13184
	s_waitcnt lgkmcnt(14)
	ds_read_b128 v[136:139], v228 offset:13200
	s_waitcnt lgkmcnt(14)
	ds_read_b128 v[140:143], v228 offset:13216
	s_waitcnt lgkmcnt(14)
	ds_read_b128 v[144:147], v228 offset:13232
	s_waitcnt lgkmcnt(14)
	ds_read_b128 v[148:151], v228 offset:13248
	s_waitcnt lgkmcnt(14)
; #define LAS __attribute__((address_space(3)))
; __device__ __forceinline__ void phase_gdb(const int wvs, const Params& p, LAS unsigned char* lds, int nwg) {
;     ...
;       for (int i = 1; i < 64; ++i) {
; #pragma unroll
;         for (int j4 = 0; j4 < (i + 3) / 4; ++j4) { const f32x4 m4 = *(const LAS f32x4*)(M + i * 64 + j4 * 4);
; #pragma unroll
;           for (int jj = 0; jj < 4; ++jj) if (j4 * 4 + jj < i) x[i] -= m4[jj] * x[j4 * 4 + jj]; }
;         __builtin_amdgcn_sched_barrier(0); }
; #pragma unroll
;       for (int i = 0; i < 64; ++i) R[i * RP + t] = (hf)x[i]; }
	v_fma_f32 v114, -v64, v180, v114
	v_fma_f32 v114, -v65, v181, v114
	v_fma_f32 v114, -v66, v182, v114
	v_fma_f32 v114, -v67, v183, v114
	v_fma_f32 v114, -v68, v184, v114
	v_fma_f32 v114, -v69, v185, v114
	v_fma_f32 v114, -v70, v186, v114
	v_fma_f32 v114, -v71, v187, v114
	v_fma_f32 v114, -v72, v188, v114
	v_fma_f32 v114, -v73, v189, v114
	v_fma_f32 v114, -v74, v190, v114
	v_fma_f32 v114, -v75, v191, v114
	v_fma_f32 v114, -v76, v244, v114
	v_fma_f32 v114, -v77, v245, v114
	v_fma_f32 v114, -v78, v246, v114
	v_fma_f32 v114, -v79, v247, v114
	v_fma_f32 v114, -v80, v248, v114
	v_fma_f32 v114, -v81, v249, v114
	v_fma_f32 v114, -v82, v250, v114
	v_fma_f32 v114, -v83, v251, v114
	v_fma_f32 v114, -v84, v4, v114
	v_fma_f32 v114, -v85, v5, v114
	v_fma_f32 v114, -v86, v6, v114
	v_fma_f32 v114, -v87, v7, v114
	v_fma_f32 v114, -v88, v8, v114
	v_fma_f32 v114, -v89, v9, v114
	v_fma_f32 v114, -v90, v10, v114
	v_fma_f32 v114, -v91, v11, v114
	v_fma_f32 v114, -v92, v12, v114
	v_fma_f32 v114, -v93, v13, v114
	v_fma_f32 v114, -v94, v14, v114
	v_fma_f32 v114, -v95, v15, v114
	v_fma_f32 v114, -v96, v16, v114
	v_fma_f32 v114, -v97, v17, v114
	v_fma_f32 v114, -v98, v18, v114
	v_fma_f32 v114, -v99, v19, v114
	v_fma_f32 v114, -v100, v20, v114
	v_fma_f32 v114, -v101, v21, v114
	v_fma_f32 v114, -v102, v22, v114
	v_fma_f32 v114, -v103, v23, v114
	v_fma_f32 v114, -v104, v24, v114
	v_fma_f32 v114, -v105, v25, v114
	v_fma_f32 v114, -v106, v26, v114
	v_fma_f32 v114, -v107, v27, v114
	v_fma_f32 v114, -v108, v28, v114
	v_fma_f32 v114, -v109, v29, v114
	v_fma_f32 v114, -v110, v30, v114
	v_fma_f32 v114, -v111, v31, v114
	v_fma_f32 v114, -v112, v32, v114
	v_fma_mixlo_f16 v3, -v113, v33, v114
	v_fma_f32 v114, -v113, v33, v114
	ds_write_b16 v232, v3 offset:29984
	s_waitcnt lgkmcnt(14)
	ds_read_b128 v[152:155], v228 offset:13312
	s_waitcnt lgkmcnt(14)
	ds_read_b128 v[156:159], v228 offset:13328
	s_waitcnt lgkmcnt(14)
	ds_read_b128 v[160:163], v228 offset:13344
	s_waitcnt lgkmcnt(14)
	ds_read_b128 v[164:167], v228 offset:13360
	s_waitcnt lgkmcnt(14)
	ds_read_b128 v[168:171], v228 offset:13376
	s_waitcnt lgkmcnt(14)
	ds_read_b128 v[172:175], v228 offset:13392
	s_waitcnt lgkmcnt(14)
	ds_read_b128 v[176:179], v228 offset:13408
	s_waitcnt lgkmcnt(14)
	ds_read_b128 v[180:183], v228 offset:13424
	s_waitcnt lgkmcnt(14)
	ds_read_b128 v[184:187], v228 offset:13440
	s_waitcnt lgkmcnt(14)
	ds_read_b128 v[188:191], v228 offset:13456
	s_waitcnt lgkmcnt(14)
	ds_read_b128 v[244:247], v228 offset:13472
	s_waitcnt lgkmcnt(14)
	ds_read_b128 v[248:251], v228 offset:13488
	s_waitcnt lgkmcnt(14)
	ds_read_b128 v[4:7], v228 offset:13504
	s_waitcnt lgkmcnt(14)
	v_fma_f32 v115, -v64, v36, v115
	v_fma_f32 v115, -v65, v37, v115
	v_fma_f32 v115, -v66, v38, v115
	v_fma_f32 v115, -v67, v39, v115
	v_fma_f32 v115, -v68, v40, v115
	v_fma_f32 v115, -v69, v41, v115
	v_fma_f32 v115, -v70, v42, v115
	v_fma_f32 v115, -v71, v43, v115
	v_fma_f32 v115, -v72, v44, v115
	v_fma_f32 v115, -v73, v45, v115
	v_fma_f32 v115, -v74, v46, v115
	v_fma_f32 v115, -v75, v47, v115
	v_fma_f32 v115, -v76, v48, v115
	v_fma_f32 v115, -v77, v49, v115
	v_fma_f32 v115, -v78, v50, v115
	v_fma_f32 v115, -v79, v51, v115
	v_fma_f32 v115, -v80, v52, v115
	v_fma_f32 v115, -v81, v53, v115
	v_fma_f32 v115, -v82, v54, v115
	v_fma_f32 v115, -v83, v55, v115
	v_fma_f32 v115, -v84, v56, v115
	v_fma_f32 v115, -v85, v57, v115
	v_fma_f32 v115, -v86, v58, v115
	v_fma_f32 v115, -v87, v59, v115
	v_fma_f32 v115, -v88, v60, v115
	v_fma_f32 v115, -v89, v61, v115
	v_fma_f32 v115, -v90, v62, v115
	v_fma_f32 v115, -v91, v63, v115
	v_fma_f32 v115, -v92, v128, v115
	v_fma_f32 v115, -v93, v129, v115
	v_fma_f32 v115, -v94, v130, v115
	v_fma_f32 v115, -v95, v131, v115
	v_fma_f32 v115, -v96, v132, v115
	v_fma_f32 v115, -v97, v133, v115
	v_fma_f32 v115, -v98, v134, v115
	v_fma_f32 v115, -v99, v135, v115
	v_fma_f32 v115, -v100, v136, v115
	v_fma_f32 v115, -v101, v137, v115
	v_fma_f32 v115, -v102, v138, v115
	v_fma_f32 v115, -v103, v139, v115
	v_fma_f32 v115, -v104, v140, v115
	v_fma_f32 v115, -v105, v141, v115
	v_fma_f32 v115, -v106, v142, v115
	v_fma_f32 v115, -v107, v143, v115
	v_fma_f32 v115, -v108, v144, v115
	v_fma_f32 v115, -v109, v145, v115
	v_fma_f32 v115, -v110, v146, v115
	v_fma_f32 v115, -v111, v147, v115
	v_fma_f32 v115, -v112, v148, v115
	v_fma_f32 v115, -v113, v149, v115
	v_fma_mixlo_f16 v238, -v114, v150, v115
	v_fma_f32 v115, -v114, v150, v115
	ds_write_b16 v232, v238 offset:30256
	s_waitcnt lgkmcnt(14)
	ds_read_b128 v[8:11], v228 offset:13568
	s_waitcnt lgkmcnt(14)
	ds_read_b128 v[12:15], v228 offset:13584
	s_waitcnt lgkmcnt(14)
	ds_read_b128 v[16:19], v228 offset:13600
	s_waitcnt lgkmcnt(14)
	ds_read_b128 v[20:23], v228 offset:13616
	s_waitcnt lgkmcnt(14)
	ds_read_b128 v[24:27], v228 offset:13632
	s_waitcnt lgkmcnt(14)
	ds_read_b128 v[28:31], v228 offset:13648
	s_waitcnt lgkmcnt(14)
	ds_read_b128 v[32:35], v228 offset:13664
	s_waitcnt lgkmcnt(14)
	ds_read_b128 v[36:39], v228 offset:13680
	s_waitcnt lgkmcnt(14)
	ds_read_b128 v[40:43], v228 offset:13696
	s_waitcnt lgkmcnt(14)
	ds_read_b128 v[44:47], v228 offset:13712
	s_waitcnt lgkmcnt(14)
	ds_read_b128 v[48:51], v228 offset:13728
	s_waitcnt lgkmcnt(14)
	ds_read_b128 v[52:55], v228 offset:13744
	s_waitcnt lgkmcnt(14)
	ds_read_b128 v[56:59], v228 offset:13760
	s_waitcnt lgkmcnt(14)
; #define LAS __attribute__((address_space(3)))
; __device__ __forceinline__ void phase_gdb(const int wvs, const Params& p, LAS unsigned char* lds, int nwg) {
;     ...
;       for (int i = 1; i < 64; ++i) {
; #pragma unroll
;         for (int j4 = 0; j4 < (i + 3) / 4; ++j4) { const f32x4 m4 = *(const LAS f32x4*)(M + i * 64 + j4 * 4);
; #pragma unroll
;           for (int jj = 0; jj < 4; ++jj) if (j4 * 4 + jj < i) x[i] -= m4[jj] * x[j4 * 4 + jj]; }
;         __builtin_amdgcn_sched_barrier(0); }
; #pragma unroll
;       for (int i = 0; i < 64; ++i) R[i * RP + t] = (hf)x[i]; }
	ds_read_b128 v[60:63], v228 offset:13776
	v_fma_f32 v116, -v64, v152, v116
	v_fma_f32 v116, -v65, v153, v116
	v_fma_f32 v116, -v66, v154, v116
	v_fma_f32 v116, -v67, v155, v116
	v_fma_f32 v116, -v68, v156, v116
	v_fma_f32 v116, -v69, v157, v116
	v_fma_f32 v116, -v70, v158, v116
	v_fma_f32 v116, -v71, v159, v116
	v_fma_f32 v116, -v72, v160, v116
	v_fma_f32 v116, -v73, v161, v116
	v_fma_f32 v116, -v74, v162, v116
	v_fma_f32 v116, -v75, v163, v116
	v_fma_f32 v116, -v76, v164, v116
	v_fma_f32 v116, -v77, v165, v116
	v_fma_f32 v116, -v78, v166, v116
	v_fma_f32 v116, -v79, v167, v116
	v_fma_f32 v116, -v80, v168, v116
	v_fma_f32 v116, -v81, v169, v116
	v_fma_f32 v116, -v82, v170, v116
	v_fma_f32 v116, -v83, v171, v116
	v_fma_f32 v116, -v84, v172, v116
	v_fma_f32 v116, -v85, v173, v116
	v_fma_f32 v116, -v86, v174, v116
	v_fma_f32 v116, -v87, v175, v116
	v_fma_f32 v116, -v88, v176, v116
	v_fma_f32 v116, -v89, v177, v116
	v_fma_f32 v116, -v90, v178, v116
	v_fma_f32 v116, -v91, v179, v116
	v_fma_f32 v116, -v92, v180, v116
	v_fma_f32 v116, -v93, v181, v116
	v_fma_f32 v116, -v94, v182, v116
	v_fma_f32 v116, -v95, v183, v116
	v_fma_f32 v116, -v96, v184, v116
	v_fma_f32 v116, -v97, v185, v116
	v_fma_f32 v116, -v98, v186, v116
	v_fma_f32 v116, -v99, v187, v116
	v_fma_f32 v116, -v100, v188, v116
	v_fma_f32 v116, -v101, v189, v116
	v_fma_f32 v116, -v102, v190, v116
	v_fma_f32 v116, -v103, v191, v116
	v_fma_f32 v116, -v104, v244, v116
	v_fma_f32 v116, -v105, v245, v116
	v_fma_f32 v116, -v106, v246, v116
	v_fma_f32 v116, -v107, v247, v116
	v_fma_f32 v116, -v108, v248, v116
	v_fma_f32 v116, -v109, v249, v116
	v_fma_f32 v116, -v110, v250, v116
	v_fma_f32 v116, -v111, v251, v116
	v_fma_f32 v116, -v112, v4, v116
	v_fma_f32 v116, -v113, v5, v116
	v_fma_f32 v116, -v114, v6, v116
	v_fma_mixlo_f16 v239, -v115, v7, v116
	v_fma_f32 v116, -v115, v7, v116
	s_waitcnt lgkmcnt(14)
	ds_write_b16 v232, v239 offset:30528
	s_waitcnt lgkmcnt(14)
	ds_read_b128 v[128:131], v228 offset:13824
	s_waitcnt lgkmcnt(14)
	ds_read_b128 v[132:135], v228 offset:13840
	s_waitcnt lgkmcnt(14)
	ds_read_b128 v[136:139], v228 offset:13856
	s_waitcnt lgkmcnt(14)
	ds_read_b128 v[140:143], v228 offset:13872
	s_waitcnt lgkmcnt(14)
	ds_read_b128 v[144:147], v228 offset:13888
	s_waitcnt lgkmcnt(14)
	ds_read_b128 v[148:151], v228 offset:13904
	s_waitcnt lgkmcnt(14)
	ds_read_b128 v[152:155], v228 offset:13920
	s_waitcnt lgkmcnt(14)
	ds_read_b128 v[156:159], v228 offset:13936
	s_waitcnt lgkmcnt(14)
	ds_read_b128 v[160:163], v228 offset:13952
	s_waitcnt lgkmcnt(14)
	ds_read_b128 v[164:167], v228 offset:13968
	s_waitcnt lgkmcnt(14)
	ds_read_b128 v[168:171], v228 offset:13984
	s_waitcnt lgkmcnt(14)
	ds_read_b128 v[172:175], v228 offset:14000
	s_waitcnt lgkmcnt(14)
	ds_read_b128 v[176:179], v228 offset:14016
	s_waitcnt lgkmcnt(14)
	ds_read_b128 v[180:183], v228 offset:14032
	v_fma_f32 v117, -v64, v8, v117
	v_fma_f32 v117, -v65, v9, v117
	v_fma_f32 v117, -v66, v10, v117
	v_fma_f32 v117, -v67, v11, v117
	v_fma_f32 v117, -v68, v12, v117
	v_fma_f32 v117, -v69, v13, v117
	v_fma_f32 v117, -v70, v14, v117
	v_fma_f32 v117, -v71, v15, v117
	v_fma_f32 v117, -v72, v16, v117
	v_fma_f32 v117, -v73, v17, v117
	v_fma_f32 v117, -v74, v18, v117
	v_fma_f32 v117, -v75, v19, v117
	v_fma_f32 v117, -v76, v20, v117
	v_fma_f32 v117, -v77, v21, v117
	v_fma_f32 v117, -v78, v22, v117
	v_fma_f32 v117, -v79, v23, v117
	v_fma_f32 v117, -v80, v24, v117
	v_fma_f32 v117, -v81, v25, v117
	v_fma_f32 v117, -v82, v26, v117
	v_fma_f32 v117, -v83, v27, v117
	v_fma_f32 v117, -v84, v28, v117
	v_fma_f32 v117, -v85, v29, v117
	v_fma_f32 v117, -v86, v30, v117
	v_fma_f32 v117, -v87, v31, v117
	v_fma_f32 v117, -v88, v32, v117
	v_fma_f32 v117, -v89, v33, v117
	v_fma_f32 v117, -v90, v34, v117
	v_fma_f32 v117, -v91, v35, v117
	v_fma_f32 v117, -v92, v36, v117
	v_fma_f32 v117, -v93, v37, v117
	v_fma_f32 v117, -v94, v38, v117
	v_fma_f32 v117, -v95, v39, v117
	v_fma_f32 v117, -v96, v40, v117
	v_fma_f32 v117, -v97, v41, v117
	v_fma_f32 v117, -v98, v42, v117
	v_fma_f32 v117, -v99, v43, v117
	v_fma_f32 v117, -v100, v44, v117
	v_fma_f32 v117, -v101, v45, v117
	v_fma_f32 v117, -v102, v46, v117
	v_fma_f32 v117, -v103, v47, v117
	v_fma_f32 v117, -v104, v48, v117
	v_fma_f32 v117, -v105, v49, v117
	v_fma_f32 v117, -v106, v50, v117
	v_fma_f32 v117, -v107, v51, v117
	v_fma_f32 v117, -v108, v52, v117
	v_fma_f32 v117, -v109, v53, v117
	v_fma_f32 v117, -v110, v54, v117
	v_fma_f32 v117, -v111, v55, v117
	v_fma_f32 v117, -v112, v56, v117
	v_fma_f32 v117, -v113, v57, v117
	v_fma_f32 v117, -v114, v58, v117
	v_fma_f32 v117, -v115, v59, v117
	v_fma_mixlo_f16 v240, -v116, v60, v117
	v_fma_f32 v117, -v116, v60, v117
	s_waitcnt lgkmcnt(14)
	ds_write_b16 v232, v240 offset:30800
	s_waitcnt lgkmcnt(14)
	ds_read_b128 v[184:187], v228 offset:14080
	s_waitcnt lgkmcnt(14)
	ds_read_b128 v[188:191], v228 offset:14096
	s_waitcnt lgkmcnt(14)
	ds_read_b128 v[244:247], v228 offset:14112
	s_waitcnt lgkmcnt(14)
	ds_read_b128 v[248:251], v228 offset:14128
	s_waitcnt lgkmcnt(14)
	ds_read_b128 v[4:7], v228 offset:14144
	s_waitcnt lgkmcnt(14)
	ds_read_b128 v[8:11], v228 offset:14160
	s_waitcnt lgkmcnt(14)
	ds_read_b128 v[12:15], v228 offset:14176
	s_waitcnt lgkmcnt(14)
	ds_read_b128 v[16:19], v228 offset:14192
	s_waitcnt lgkmcnt(14)
	ds_read_b128 v[20:23], v228 offset:14208
	s_waitcnt lgkmcnt(14)
	ds_read_b128 v[24:27], v228 offset:14224
	s_waitcnt lgkmcnt(14)
	ds_read_b128 v[28:31], v228 offset:14240
	s_waitcnt lgkmcnt(14)
	ds_read_b128 v[32:35], v228 offset:14256
	s_waitcnt lgkmcnt(14)
	ds_read_b128 v[36:39], v228 offset:14272
	s_waitcnt lgkmcnt(14)
; #define LAS __attribute__((address_space(3)))
; __device__ __forceinline__ void phase_gdb(const int wvs, const Params& p, LAS unsigned char* lds, int nwg) {
;     ...
;       for (int i = 1; i < 64; ++i) {
; #pragma unroll
;         for (int j4 = 0; j4 < (i + 3) / 4; ++j4) { const f32x4 m4 = *(const LAS f32x4*)(M + i * 64 + j4 * 4);
; #pragma unroll
;           for (int jj = 0; jj < 4; ++jj) if (j4 * 4 + jj < i) x[i] -= m4[jj] * x[j4 * 4 + jj]; }
;         __builtin_amdgcn_sched_barrier(0); }
; #pragma unroll
;       for (int i = 0; i < 64; ++i) R[i * RP + t] = (hf)x[i]; }
	ds_read_b128 v[40:43], v228 offset:14288
	v_fma_f32 v118, -v64, v128, v118
	v_fma_f32 v118, -v65, v129, v118
	v_fma_f32 v118, -v66, v130, v118
	v_fma_f32 v118, -v67, v131, v118
	v_fma_f32 v118, -v68, v132, v118
	v_fma_f32 v118, -v69, v133, v118
	v_fma_f32 v118, -v70, v134, v118
	v_fma_f32 v118, -v71, v135, v118
	v_fma_f32 v118, -v72, v136, v118
	v_fma_f32 v118, -v73, v137, v118
	v_fma_f32 v118, -v74, v138, v118
	v_fma_f32 v118, -v75, v139, v118
	v_fma_f32 v118, -v76, v140, v118
	v_fma_f32 v118, -v77, v141, v118
	v_fma_f32 v118, -v78, v142, v118
	v_fma_f32 v118, -v79, v143, v118
	v_fma_f32 v118, -v80, v144, v118
	v_fma_f32 v118, -v81, v145, v118
	v_fma_f32 v118, -v82, v146, v118
	v_fma_f32 v118, -v83, v147, v118
	v_fma_f32 v118, -v84, v148, v118
	v_fma_f32 v118, -v85, v149, v118
	v_fma_f32 v118, -v86, v150, v118
	v_fma_f32 v118, -v87, v151, v118
	v_fma_f32 v118, -v88, v152, v118
	v_fma_f32 v118, -v89, v153, v118
	v_fma_f32 v118, -v90, v154, v118
	v_fma_f32 v118, -v91, v155, v118
	v_fma_f32 v118, -v92, v156, v118
	v_fma_f32 v118, -v93, v157, v118
	v_fma_f32 v118, -v94, v158, v118
	v_fma_f32 v118, -v95, v159, v118
	v_fma_f32 v118, -v96, v160, v118
	v_fma_f32 v118, -v97, v161, v118
	v_fma_f32 v118, -v98, v162, v118
	v_fma_f32 v118, -v99, v163, v118
	v_fma_f32 v118, -v100, v164, v118
	v_fma_f32 v118, -v101, v165, v118
	v_fma_f32 v118, -v102, v166, v118
	v_fma_f32 v118, -v103, v167, v118
	v_fma_f32 v118, -v104, v168, v118
	v_fma_f32 v118, -v105, v169, v118
	v_fma_f32 v118, -v106, v170, v118
	v_fma_f32 v118, -v107, v171, v118
	v_fma_f32 v118, -v108, v172, v118
	v_fma_f32 v118, -v109, v173, v118
	v_fma_f32 v118, -v110, v174, v118
	v_fma_f32 v118, -v111, v175, v118
	v_fma_f32 v118, -v112, v176, v118
	v_fma_f32 v118, -v113, v177, v118
	v_fma_f32 v118, -v114, v178, v118
	v_fma_f32 v118, -v115, v179, v118
	v_fma_f32 v118, -v116, v180, v118
	v_fma_mixlo_f16 v0, -v117, v181, v118
	v_fma_f32 v118, -v117, v181, v118
	s_waitcnt lgkmcnt(14)
	ds_write_b16 v232, v0 offset:31072
	s_waitcnt lgkmcnt(14)
	ds_read_b128 v[44:47], v228 offset:14336
	s_waitcnt lgkmcnt(14)
	ds_read_b128 v[48:51], v228 offset:14352
	s_waitcnt lgkmcnt(14)
	ds_read_b128 v[52:55], v228 offset:14368
	s_waitcnt lgkmcnt(14)
	ds_read_b128 v[56:59], v228 offset:14384
	s_waitcnt lgkmcnt(14)
	ds_read_b128 v[60:63], v228 offset:14400
	s_waitcnt lgkmcnt(14)
	ds_read_b128 v[128:131], v228 offset:14416
	s_waitcnt lgkmcnt(14)
	ds_read_b128 v[132:135], v228 offset:14432
	s_waitcnt lgkmcnt(14)
	ds_read_b128 v[136:139], v228 offset:14448
	s_waitcnt lgkmcnt(14)
	ds_read_b128 v[140:143], v228 offset:14464
	s_waitcnt lgkmcnt(14)
	ds_read_b128 v[144:147], v228 offset:14480
	s_waitcnt lgkmcnt(14)
	ds_read_b128 v[148:151], v228 offset:14496
	s_waitcnt lgkmcnt(14)
	ds_read_b128 v[152:155], v228 offset:14512
	s_waitcnt lgkmcnt(14)
	ds_read_b128 v[156:159], v228 offset:14528
	s_waitcnt lgkmcnt(14)
	ds_read_b128 v[160:163], v228 offset:14544
	v_fma_f32 v119, -v64, v184, v119
	v_fma_f32 v119, -v65, v185, v119
	v_fma_f32 v119, -v66, v186, v119
	v_fma_f32 v119, -v67, v187, v119
	v_fma_f32 v119, -v68, v188, v119
	v_fma_f32 v119, -v69, v189, v119
	v_fma_f32 v119, -v70, v190, v119
	v_fma_f32 v119, -v71, v191, v119
	v_fma_f32 v119, -v72, v244, v119
	v_fma_f32 v119, -v73, v245, v119
	v_fma_f32 v119, -v74, v246, v119
	v_fma_f32 v119, -v75, v247, v119
	v_fma_f32 v119, -v76, v248, v119
	v_fma_f32 v119, -v77, v249, v119
	v_fma_f32 v119, -v78, v250, v119
	v_fma_f32 v119, -v79, v251, v119
	v_fma_f32 v119, -v80, v4, v119
	v_fma_f32 v119, -v81, v5, v119
	v_fma_f32 v119, -v82, v6, v119
	v_fma_f32 v119, -v83, v7, v119
	v_fma_f32 v119, -v84, v8, v119
	v_fma_f32 v119, -v85, v9, v119
	v_fma_f32 v119, -v86, v10, v119
	v_fma_f32 v119, -v87, v11, v119
	v_fma_f32 v119, -v88, v12, v119
	v_fma_f32 v119, -v89, v13, v119
	v_fma_f32 v119, -v90, v14, v119
	v_fma_f32 v119, -v91, v15, v119
	v_fma_f32 v119, -v92, v16, v119
	v_fma_f32 v119, -v93, v17, v119
	v_fma_f32 v119, -v94, v18, v119
	v_fma_f32 v119, -v95, v19, v119
	v_fma_f32 v119, -v96, v20, v119
	v_fma_f32 v119, -v97, v21, v119
	v_fma_f32 v119, -v98, v22, v119
	v_fma_f32 v119, -v99, v23, v119
	v_fma_f32 v119, -v100, v24, v119
	v_fma_f32 v119, -v101, v25, v119
	v_fma_f32 v119, -v102, v26, v119
	v_fma_f32 v119, -v103, v27, v119
	v_fma_f32 v119, -v104, v28, v119
	v_fma_f32 v119, -v105, v29, v119
	v_fma_f32 v119, -v106, v30, v119
	v_fma_f32 v119, -v107, v31, v119
	v_fma_f32 v119, -v108, v32, v119
	v_fma_f32 v119, -v109, v33, v119
	v_fma_f32 v119, -v110, v34, v119
	v_fma_f32 v119, -v111, v35, v119
	v_fma_f32 v119, -v112, v36, v119
	v_fma_f32 v119, -v113, v37, v119
	v_fma_f32 v119, -v114, v38, v119
	v_fma_f32 v119, -v115, v39, v119
	v_fma_f32 v119, -v116, v40, v119
	v_fma_f32 v119, -v117, v41, v119
	v_fma_mixlo_f16 v2, -v118, v42, v119
	v_fma_f32 v119, -v118, v42, v119
	s_waitcnt lgkmcnt(14)
	ds_write_b16 v232, v2 offset:31344
	s_waitcnt lgkmcnt(14)
	ds_read_b128 v[164:167], v228 offset:14592
	s_waitcnt lgkmcnt(14)
	ds_read_b128 v[168:171], v228 offset:14608
	s_waitcnt lgkmcnt(14)
	ds_read_b128 v[172:175], v228 offset:14624
	s_waitcnt lgkmcnt(14)
	ds_read_b128 v[176:179], v228 offset:14640
	s_waitcnt lgkmcnt(14)
	ds_read_b128 v[180:183], v228 offset:14656
	s_waitcnt lgkmcnt(14)
	ds_read_b128 v[184:187], v228 offset:14672
	s_waitcnt lgkmcnt(14)
	ds_read_b128 v[188:191], v228 offset:14688
	s_waitcnt lgkmcnt(14)
	ds_read_b128 v[244:247], v228 offset:14704
	s_waitcnt lgkmcnt(14)
	ds_read_b128 v[248:251], v228 offset:14720
	s_waitcnt lgkmcnt(14)
	ds_read_b128 v[4:7], v228 offset:14736
	s_waitcnt lgkmcnt(14)
	ds_read_b128 v[8:11], v228 offset:14752
	s_waitcnt lgkmcnt(14)
; #define LAS __attribute__((address_space(3)))
; __device__ __forceinline__ void phase_gdb(const int wvs, const Params& p, LAS unsigned char* lds, int nwg) {
;     ...
;       for (int i = 1; i < 64; ++i) {
; #pragma unroll
;         for (int j4 = 0; j4 < (i + 3) / 4; ++j4) { const f32x4 m4 = *(const LAS f32x4*)(M + i * 64 + j4 * 4);
; #pragma unroll
;           for (int jj = 0; jj < 4; ++jj) if (j4 * 4 + jj < i) x[i] -= m4[jj] * x[j4 * 4 + jj]; }
;         __builtin_amdgcn_sched_barrier(0); }
; #pragma unroll
;       for (int i = 0; i < 64; ++i) R[i * RP + t] = (hf)x[i]; }
	ds_read_b128 v[12:15], v228 offset:14768
	s_waitcnt lgkmcnt(14)
	ds_read_b128 v[16:19], v228 offset:14784
	s_waitcnt lgkmcnt(14)
	ds_read_b128 v[20:23], v228 offset:14800
	s_waitcnt lgkmcnt(14)
	ds_read_b128 v[24:27], v228 offset:14816
	v_fma_f32 v120, -v64, v44, v120
	v_fma_f32 v120, -v65, v45, v120
	v_fma_f32 v120, -v66, v46, v120
	v_fma_f32 v120, -v67, v47, v120
	v_fma_f32 v120, -v68, v48, v120
	v_fma_f32 v120, -v69, v49, v120
	v_fma_f32 v120, -v70, v50, v120
	v_fma_f32 v120, -v71, v51, v120
	v_fma_f32 v120, -v72, v52, v120
	v_fma_f32 v120, -v73, v53, v120
	v_fma_f32 v120, -v74, v54, v120
	v_fma_f32 v120, -v75, v55, v120
	v_fma_f32 v120, -v76, v56, v120
	v_fma_f32 v120, -v77, v57, v120
	v_fma_f32 v120, -v78, v58, v120
	v_fma_f32 v120, -v79, v59, v120
	v_fma_f32 v120, -v80, v60, v120
	v_fma_f32 v120, -v81, v61, v120
	v_fma_f32 v120, -v82, v62, v120
	v_fma_f32 v120, -v83, v63, v120
	v_fma_f32 v120, -v84, v128, v120
	v_fma_f32 v120, -v85, v129, v120
	v_fma_f32 v120, -v86, v130, v120
	v_fma_f32 v120, -v87, v131, v120
	v_fma_f32 v120, -v88, v132, v120
	v_fma_f32 v120, -v89, v133, v120
	v_fma_f32 v120, -v90, v134, v120
	v_fma_f32 v120, -v91, v135, v120
	v_fma_f32 v120, -v92, v136, v120
	v_fma_f32 v120, -v93, v137, v120
	v_fma_f32 v120, -v94, v138, v120
	v_fma_f32 v120, -v95, v139, v120
	v_fma_f32 v120, -v96, v140, v120
	v_fma_f32 v120, -v97, v141, v120
	v_fma_f32 v120, -v98, v142, v120
	v_fma_f32 v120, -v99, v143, v120
	v_fma_f32 v120, -v100, v144, v120
	v_fma_f32 v120, -v101, v145, v120
	v_fma_f32 v120, -v102, v146, v120
	v_fma_f32 v120, -v103, v147, v120
	v_fma_f32 v120, -v104, v148, v120
	v_fma_f32 v120, -v105, v149, v120
	v_fma_f32 v120, -v106, v150, v120
	v_fma_f32 v120, -v107, v151, v120
	v_fma_f32 v120, -v108, v152, v120
	v_fma_f32 v120, -v109, v153, v120
	v_fma_f32 v120, -v110, v154, v120
	v_fma_f32 v120, -v111, v155, v120
	v_fma_f32 v120, -v112, v156, v120
	v_fma_f32 v120, -v113, v157, v120
	v_fma_f32 v120, -v114, v158, v120
	v_fma_f32 v120, -v115, v159, v120
	v_fma_f32 v120, -v116, v160, v120
	v_fma_f32 v120, -v117, v161, v120
	v_fma_f32 v120, -v118, v162, v120
	v_fma_mixlo_f16 v3, -v119, v163, v120
	v_fma_f32 v120, -v119, v163, v120
	s_waitcnt lgkmcnt(14)
	ds_write_b16 v232, v3 offset:31616
	s_waitcnt lgkmcnt(14)
	ds_read_b128 v[28:31], v228 offset:14848
	s_waitcnt lgkmcnt(14)
	ds_read_b128 v[32:35], v228 offset:14864
	s_waitcnt lgkmcnt(14)
	ds_read_b128 v[36:39], v228 offset:14880
	s_waitcnt lgkmcnt(14)
	ds_read_b128 v[40:43], v228 offset:14896
	s_waitcnt lgkmcnt(14)
	ds_read_b128 v[44:47], v228 offset:14912
	s_waitcnt lgkmcnt(14)
	ds_read_b128 v[48:51], v228 offset:14928
	s_waitcnt lgkmcnt(14)
	ds_read_b128 v[52:55], v228 offset:14944
	s_waitcnt lgkmcnt(14)
	ds_read_b128 v[56:59], v228 offset:14960
	s_waitcnt lgkmcnt(14)
	ds_read_b128 v[60:63], v228 offset:14976
	s_waitcnt lgkmcnt(14)
	ds_read_b128 v[128:131], v228 offset:14992
	s_waitcnt lgkmcnt(14)
	ds_read_b128 v[132:135], v228 offset:15008
	s_waitcnt lgkmcnt(14)
	ds_read_b128 v[136:139], v228 offset:15024
	s_waitcnt lgkmcnt(14)
	ds_read_b128 v[140:143], v228 offset:15040
	s_waitcnt lgkmcnt(14)
	ds_read_b128 v[144:147], v228 offset:15056
	s_waitcnt lgkmcnt(14)
	ds_read_b128 v[148:151], v228 offset:15072
	v_fma_f32 v121, -v64, v164, v121
	v_fma_f32 v121, -v65, v165, v121
	v_fma_f32 v121, -v66, v166, v121
	v_fma_f32 v121, -v67, v167, v121
	v_fma_f32 v121, -v68, v168, v121
	v_fma_f32 v121, -v69, v169, v121
	v_fma_f32 v121, -v70, v170, v121
	v_fma_f32 v121, -v71, v171, v121
	v_fma_f32 v121, -v72, v172, v121
	v_fma_f32 v121, -v73, v173, v121
	v_fma_f32 v121, -v74, v174, v121
	v_fma_f32 v121, -v75, v175, v121
	v_fma_f32 v121, -v76, v176, v121
	v_fma_f32 v121, -v77, v177, v121
	v_fma_f32 v121, -v78, v178, v121
	v_fma_f32 v121, -v79, v179, v121
	v_fma_f32 v121, -v80, v180, v121
	v_fma_f32 v121, -v81, v181, v121
	v_fma_f32 v121, -v82, v182, v121
	v_fma_f32 v121, -v83, v183, v121
	v_fma_f32 v121, -v84, v184, v121
	v_fma_f32 v121, -v85, v185, v121
	v_fma_f32 v121, -v86, v186, v121
	v_fma_f32 v121, -v87, v187, v121
	v_fma_f32 v121, -v88, v188, v121
	v_fma_f32 v121, -v89, v189, v121
	v_fma_f32 v121, -v90, v190, v121
	v_fma_f32 v121, -v91, v191, v121
	v_fma_f32 v121, -v92, v244, v121
	v_fma_f32 v121, -v93, v245, v121
	v_fma_f32 v121, -v94, v246, v121
	v_fma_f32 v121, -v95, v247, v121
	v_fma_f32 v121, -v96, v248, v121
	v_fma_f32 v121, -v97, v249, v121
	v_fma_f32 v121, -v98, v250, v121
	v_fma_f32 v121, -v99, v251, v121
	v_fma_f32 v121, -v100, v4, v121
	v_fma_f32 v121, -v101, v5, v121
	v_fma_f32 v121, -v102, v6, v121
	v_fma_f32 v121, -v103, v7, v121
	v_fma_f32 v121, -v104, v8, v121
	v_fma_f32 v121, -v105, v9, v121
	v_fma_f32 v121, -v106, v10, v121
	v_fma_f32 v121, -v107, v11, v121
	v_fma_f32 v121, -v108, v12, v121
	v_fma_f32 v121, -v109, v13, v121
	v_fma_f32 v121, -v110, v14, v121
	v_fma_f32 v121, -v111, v15, v121
	v_fma_f32 v121, -v112, v16, v121
	v_fma_f32 v121, -v113, v17, v121
	v_fma_f32 v121, -v114, v18, v121
	v_fma_f32 v121, -v115, v19, v121
	v_fma_f32 v121, -v116, v20, v121
	v_fma_f32 v121, -v117, v21, v121
	v_fma_f32 v121, -v118, v22, v121
	v_fma_f32 v121, -v119, v23, v121
	v_fma_mixlo_f16 v238, -v120, v24, v121
	v_fma_f32 v121, -v120, v24, v121
	s_waitcnt lgkmcnt(14)
	ds_write_b16 v232, v238 offset:31888
	s_waitcnt lgkmcnt(14)
	ds_read_b128 v[152:155], v228 offset:15104
	s_waitcnt lgkmcnt(14)
	ds_read_b128 v[156:159], v228 offset:15120
	s_waitcnt lgkmcnt(14)
	ds_read_b128 v[160:163], v228 offset:15136
	s_waitcnt lgkmcnt(14)
	ds_read_b128 v[164:167], v228 offset:15152
	s_waitcnt lgkmcnt(14)
	ds_read_b128 v[168:171], v228 offset:15168
	s_waitcnt lgkmcnt(14)
; #define LAS __attribute__((address_space(3)))
; __device__ __forceinline__ void phase_gdb(const int wvs, const Params& p, LAS unsigned char* lds, int nwg) {
;     ...
;       for (int i = 1; i < 64; ++i) {
; #pragma unroll
;         for (int j4 = 0; j4 < (i + 3) / 4; ++j4) { const f32x4 m4 = *(const LAS f32x4*)(M + i * 64 + j4 * 4);
; #pragma unroll
;           for (int jj = 0; jj < 4; ++jj) if (j4 * 4 + jj < i) x[i] -= m4[jj] * x[j4 * 4 + jj]; }
;         __builtin_amdgcn_sched_barrier(0); }
; #pragma unroll
;       for (int i = 0; i < 64; ++i) R[i * RP + t] = (hf)x[i]; }
	ds_read_b128 v[172:175], v228 offset:15184
	s_waitcnt lgkmcnt(14)
	ds_read_b128 v[176:179], v228 offset:15200
	s_waitcnt lgkmcnt(14)
	ds_read_b128 v[180:183], v228 offset:15216
	s_waitcnt lgkmcnt(14)
	ds_read_b128 v[184:187], v228 offset:15232
	s_waitcnt lgkmcnt(14)
	ds_read_b128 v[188:191], v228 offset:15248
	s_waitcnt lgkmcnt(14)
	ds_read_b128 v[244:247], v228 offset:15264
	s_waitcnt lgkmcnt(14)
	ds_read_b128 v[248:251], v228 offset:15280
	s_waitcnt lgkmcnt(14)
	ds_read_b128 v[4:7], v228 offset:15296
	s_waitcnt lgkmcnt(14)
	ds_read_b128 v[8:11], v228 offset:15312
	s_waitcnt lgkmcnt(14)
	ds_read_b128 v[12:15], v228 offset:15328
	v_fma_f32 v122, -v64, v28, v122
	v_fma_f32 v122, -v65, v29, v122
	v_fma_f32 v122, -v66, v30, v122
	v_fma_f32 v122, -v67, v31, v122
	v_fma_f32 v122, -v68, v32, v122
	v_fma_f32 v122, -v69, v33, v122
	v_fma_f32 v122, -v70, v34, v122
	v_fma_f32 v122, -v71, v35, v122
	v_fma_f32 v122, -v72, v36, v122
	v_fma_f32 v122, -v73, v37, v122
	v_fma_f32 v122, -v74, v38, v122
	v_fma_f32 v122, -v75, v39, v122
	v_fma_f32 v122, -v76, v40, v122
	v_fma_f32 v122, -v77, v41, v122
	v_fma_f32 v122, -v78, v42, v122
	v_fma_f32 v122, -v79, v43, v122
	v_fma_f32 v122, -v80, v44, v122
	v_fma_f32 v122, -v81, v45, v122
	v_fma_f32 v122, -v82, v46, v122
	v_fma_f32 v122, -v83, v47, v122
	v_fma_f32 v122, -v84, v48, v122
	v_fma_f32 v122, -v85, v49, v122
	v_fma_f32 v122, -v86, v50, v122
	v_fma_f32 v122, -v87, v51, v122
	v_fma_f32 v122, -v88, v52, v122
	v_fma_f32 v122, -v89, v53, v122
	v_fma_f32 v122, -v90, v54, v122
	v_fma_f32 v122, -v91, v55, v122
	v_fma_f32 v122, -v92, v56, v122
	v_fma_f32 v122, -v93, v57, v122
	v_fma_f32 v122, -v94, v58, v122
	v_fma_f32 v122, -v95, v59, v122
	v_fma_f32 v122, -v96, v60, v122
	v_fma_f32 v122, -v97, v61, v122
	v_fma_f32 v122, -v98, v62, v122
	v_fma_f32 v122, -v99, v63, v122
	v_fma_f32 v122, -v100, v128, v122
	v_fma_f32 v122, -v101, v129, v122
	v_fma_f32 v122, -v102, v130, v122
	v_fma_f32 v122, -v103, v131, v122
	v_fma_f32 v122, -v104, v132, v122
	v_fma_f32 v122, -v105, v133, v122
	v_fma_f32 v122, -v106, v134, v122
	v_fma_f32 v122, -v107, v135, v122
	v_fma_f32 v122, -v108, v136, v122
	v_fma_f32 v122, -v109, v137, v122
	v_fma_f32 v122, -v110, v138, v122
	v_fma_f32 v122, -v111, v139, v122
	v_fma_f32 v122, -v112, v140, v122
	v_fma_f32 v122, -v113, v141, v122
	v_fma_f32 v122, -v114, v142, v122
	v_fma_f32 v122, -v115, v143, v122
	v_fma_f32 v122, -v116, v144, v122
	v_fma_f32 v122, -v117, v145, v122
	v_fma_f32 v122, -v118, v146, v122
	v_fma_f32 v122, -v119, v147, v122
	v_fma_f32 v122, -v120, v148, v122
	v_fma_mixlo_f16 v239, -v121, v149, v122
	v_fma_f32 v122, -v121, v149, v122
	s_waitcnt lgkmcnt(14)
	ds_write_b16 v232, v239 offset:32160
	s_waitcnt lgkmcnt(14)
	ds_read_b128 v[16:19], v228 offset:15360
	s_waitcnt lgkmcnt(14)
	ds_read_b128 v[20:23], v228 offset:15376
	s_waitcnt lgkmcnt(14)
	ds_read_b128 v[24:27], v228 offset:15392
	s_waitcnt lgkmcnt(14)
	ds_read_b128 v[28:31], v228 offset:15408
	s_waitcnt lgkmcnt(14)
	ds_read_b128 v[32:35], v228 offset:15424
	s_waitcnt lgkmcnt(14)
	ds_read_b128 v[36:39], v228 offset:15440
	s_waitcnt lgkmcnt(14)
	ds_read_b128 v[40:43], v228 offset:15456
	s_waitcnt lgkmcnt(14)
	ds_read_b128 v[44:47], v228 offset:15472
	s_waitcnt lgkmcnt(14)
	ds_read_b128 v[48:51], v228 offset:15488
	s_waitcnt lgkmcnt(14)
	ds_read_b128 v[52:55], v228 offset:15504
	s_waitcnt lgkmcnt(14)
	ds_read_b128 v[56:59], v228 offset:15520
	s_waitcnt lgkmcnt(14)
	ds_read_b128 v[60:63], v228 offset:15536
	s_waitcnt lgkmcnt(14)
	ds_read_b128 v[128:131], v228 offset:15552
	s_waitcnt lgkmcnt(14)
	ds_read_b128 v[132:135], v228 offset:15568
	s_waitcnt lgkmcnt(14)
	ds_read_b128 v[136:139], v228 offset:15584
	v_fma_f32 v123, -v64, v152, v123
	v_fma_f32 v123, -v65, v153, v123
	v_fma_f32 v123, -v66, v154, v123
	v_fma_f32 v123, -v67, v155, v123
	v_fma_f32 v123, -v68, v156, v123
	v_fma_f32 v123, -v69, v157, v123
	v_fma_f32 v123, -v70, v158, v123
	v_fma_f32 v123, -v71, v159, v123
	v_fma_f32 v123, -v72, v160, v123
	v_fma_f32 v123, -v73, v161, v123
	v_fma_f32 v123, -v74, v162, v123
	v_fma_f32 v123, -v75, v163, v123
	v_fma_f32 v123, -v76, v164, v123
	v_fma_f32 v123, -v77, v165, v123
	v_fma_f32 v123, -v78, v166, v123
	v_fma_f32 v123, -v79, v167, v123
	v_fma_f32 v123, -v80, v168, v123
	v_fma_f32 v123, -v81, v169, v123
	v_fma_f32 v123, -v82, v170, v123
	v_fma_f32 v123, -v83, v171, v123
	v_fma_f32 v123, -v84, v172, v123
	v_fma_f32 v123, -v85, v173, v123
	v_fma_f32 v123, -v86, v174, v123
	v_fma_f32 v123, -v87, v175, v123
	v_fma_f32 v123, -v88, v176, v123
	v_fma_f32 v123, -v89, v177, v123
	v_fma_f32 v123, -v90, v178, v123
	v_fma_f32 v123, -v91, v179, v123
	v_fma_f32 v123, -v92, v180, v123
	v_fma_f32 v123, -v93, v181, v123
	v_fma_f32 v123, -v94, v182, v123
	v_fma_f32 v123, -v95, v183, v123
	v_fma_f32 v123, -v96, v184, v123
	v_fma_f32 v123, -v97, v185, v123
	v_fma_f32 v123, -v98, v186, v123
	v_fma_f32 v123, -v99, v187, v123
	v_fma_f32 v123, -v100, v188, v123
	v_fma_f32 v123, -v101, v189, v123
	v_fma_f32 v123, -v102, v190, v123
	v_fma_f32 v123, -v103, v191, v123
	v_fma_f32 v123, -v104, v244, v123
	v_fma_f32 v123, -v105, v245, v123
	v_fma_f32 v123, -v106, v246, v123
	v_fma_f32 v123, -v107, v247, v123
	v_fma_f32 v123, -v108, v248, v123
	v_fma_f32 v123, -v109, v249, v123
	v_fma_f32 v123, -v110, v250, v123
	v_fma_f32 v123, -v111, v251, v123
	v_fma_f32 v123, -v112, v4, v123
	v_fma_f32 v123, -v113, v5, v123
	v_fma_f32 v123, -v114, v6, v123
	v_fma_f32 v123, -v115, v7, v123
	v_fma_f32 v123, -v116, v8, v123
	v_fma_f32 v123, -v117, v9, v123
	v_fma_f32 v123, -v118, v10, v123
	v_fma_f32 v123, -v119, v11, v123
	v_fma_f32 v123, -v120, v12, v123
	v_fma_f32 v123, -v121, v13, v123
	v_fma_mixlo_f16 v240, -v122, v14, v123
	v_fma_f32 v123, -v122, v14, v123
	s_waitcnt lgkmcnt(14)
; #define LAS __attribute__((address_space(3)))
; __device__ __forceinline__ void phase_gdb(const int wvs, const Params& p, LAS unsigned char* lds, int nwg) {
;     ...
;       for (int i = 1; i < 64; ++i) {
; #pragma unroll
;         for (int j4 = 0; j4 < (i + 3) / 4; ++j4) { const f32x4 m4 = *(const LAS f32x4*)(M + i * 64 + j4 * 4);
; #pragma unroll
;           for (int jj = 0; jj < 4; ++jj) if (j4 * 4 + jj < i) x[i] -= m4[jj] * x[j4 * 4 + jj]; }
;         __builtin_amdgcn_sched_barrier(0); }
; #pragma unroll
;       for (int i = 0; i < 64; ++i) R[i * RP + t] = (hf)x[i]; }
	ds_write_b16 v232, v240 offset:32432
	s_waitcnt lgkmcnt(14)
	ds_read_b128 v[140:143], v228 offset:15616
	s_waitcnt lgkmcnt(14)
	ds_read_b128 v[144:147], v228 offset:15632
	s_waitcnt lgkmcnt(14)
	ds_read_b128 v[148:151], v228 offset:15648
	s_waitcnt lgkmcnt(14)
	ds_read_b128 v[152:155], v228 offset:15664
	s_waitcnt lgkmcnt(14)
	ds_read_b128 v[156:159], v228 offset:15680
	s_waitcnt lgkmcnt(14)
	ds_read_b128 v[160:163], v228 offset:15696
	s_waitcnt lgkmcnt(14)
	ds_read_b128 v[164:167], v228 offset:15712
	s_waitcnt lgkmcnt(14)
	ds_read_b128 v[168:171], v228 offset:15728
	s_waitcnt lgkmcnt(14)
	ds_read_b128 v[172:175], v228 offset:15744
	s_waitcnt lgkmcnt(14)
	ds_read_b128 v[176:179], v228 offset:15760
	s_waitcnt lgkmcnt(14)
	ds_read_b128 v[180:183], v228 offset:15776
	s_waitcnt lgkmcnt(14)
	ds_read_b128 v[184:187], v228 offset:15792
	s_waitcnt lgkmcnt(14)
	ds_read_b128 v[188:191], v228 offset:15808
	s_waitcnt lgkmcnt(14)
	ds_read_b128 v[244:247], v228 offset:15824
	s_waitcnt lgkmcnt(14)
	ds_read_b128 v[248:251], v228 offset:15840
	s_waitcnt lgkmcnt(14)
	ds_read_b128 v[4:7], v228 offset:15856
	v_fma_f32 v124, -v64, v16, v124
	v_fma_f32 v124, -v65, v17, v124
	v_fma_f32 v124, -v66, v18, v124
	v_fma_f32 v124, -v67, v19, v124
	v_fma_f32 v124, -v68, v20, v124
	v_fma_f32 v124, -v69, v21, v124
	v_fma_f32 v124, -v70, v22, v124
	v_fma_f32 v124, -v71, v23, v124
	v_fma_f32 v124, -v72, v24, v124
	v_fma_f32 v124, -v73, v25, v124
	v_fma_f32 v124, -v74, v26, v124
	v_fma_f32 v124, -v75, v27, v124
	v_fma_f32 v124, -v76, v28, v124
	v_fma_f32 v124, -v77, v29, v124
	v_fma_f32 v124, -v78, v30, v124
	v_fma_f32 v124, -v79, v31, v124
	v_fma_f32 v124, -v80, v32, v124
	v_fma_f32 v124, -v81, v33, v124
	v_fma_f32 v124, -v82, v34, v124
	v_fma_f32 v124, -v83, v35, v124
	v_fma_f32 v124, -v84, v36, v124
	v_fma_f32 v124, -v85, v37, v124
	v_fma_f32 v124, -v86, v38, v124
	v_fma_f32 v124, -v87, v39, v124
	v_fma_f32 v124, -v88, v40, v124
	v_fma_f32 v124, -v89, v41, v124
	v_fma_f32 v124, -v90, v42, v124
	v_fma_f32 v124, -v91, v43, v124
	v_fma_f32 v124, -v92, v44, v124
	v_fma_f32 v124, -v93, v45, v124
	v_fma_f32 v124, -v94, v46, v124
	v_fma_f32 v124, -v95, v47, v124
	v_fma_f32 v124, -v96, v48, v124
	v_fma_f32 v124, -v97, v49, v124
	v_fma_f32 v124, -v98, v50, v124
	v_fma_f32 v124, -v99, v51, v124
	v_fma_f32 v124, -v100, v52, v124
	v_fma_f32 v124, -v101, v53, v124
	v_fma_f32 v124, -v102, v54, v124
	v_fma_f32 v124, -v103, v55, v124
	v_fma_f32 v124, -v104, v56, v124
	v_fma_f32 v124, -v105, v57, v124
	v_fma_f32 v124, -v106, v58, v124
	v_fma_f32 v124, -v107, v59, v124
	v_fma_f32 v124, -v108, v60, v124
	v_fma_f32 v124, -v109, v61, v124
	v_fma_f32 v124, -v110, v62, v124
	v_fma_f32 v124, -v111, v63, v124
	v_fma_f32 v124, -v112, v128, v124
	v_fma_f32 v124, -v113, v129, v124
	v_fma_f32 v124, -v114, v130, v124
	v_fma_f32 v124, -v115, v131, v124
	v_fma_f32 v124, -v116, v132, v124
	v_fma_f32 v124, -v117, v133, v124
	v_fma_f32 v124, -v118, v134, v124
	v_fma_f32 v124, -v119, v135, v124
	v_fma_f32 v124, -v120, v136, v124
	v_fma_f32 v124, -v121, v137, v124
	v_fma_f32 v124, -v122, v138, v124
	v_fma_mixlo_f16 v0, -v123, v139, v124
	v_fma_f32 v124, -v123, v139, v124
	s_waitcnt lgkmcnt(14)
	ds_write_b16 v232, v0 offset:32704
	s_waitcnt lgkmcnt(14)
	ds_read_b128 v[8:11], v228 offset:15872
	s_waitcnt lgkmcnt(14)
	ds_read_b128 v[12:15], v228 offset:15888
	s_waitcnt lgkmcnt(14)
	ds_read_b128 v[16:19], v228 offset:15904
	s_waitcnt lgkmcnt(14)
	ds_read_b128 v[20:23], v228 offset:15920
	s_waitcnt lgkmcnt(14)
	ds_read_b128 v[24:27], v228 offset:15936
	s_waitcnt lgkmcnt(14)
	ds_read_b128 v[28:31], v228 offset:15952
	s_waitcnt lgkmcnt(14)
	ds_read_b128 v[32:35], v228 offset:15968
	s_waitcnt lgkmcnt(14)
	ds_read_b128 v[36:39], v228 offset:15984
	s_waitcnt lgkmcnt(14)
	ds_read_b128 v[40:43], v228 offset:16000
	s_waitcnt lgkmcnt(14)
	ds_read_b128 v[44:47], v228 offset:16016
	s_waitcnt lgkmcnt(14)
	ds_read_b128 v[48:51], v228 offset:16032
	s_waitcnt lgkmcnt(14)
	ds_read_b128 v[52:55], v228 offset:16048
	s_waitcnt lgkmcnt(14)
	ds_read_b128 v[56:59], v228 offset:16064
	s_waitcnt lgkmcnt(14)
	ds_read_b128 v[60:63], v228 offset:16080
	s_waitcnt lgkmcnt(14)
	ds_read_b128 v[128:131], v228 offset:16096
	s_waitcnt lgkmcnt(14)
	ds_read_b128 v[132:135], v228 offset:16112
	v_fma_f32 v125, -v64, v140, v125
	v_fma_f32 v125, -v65, v141, v125
	v_fma_f32 v125, -v66, v142, v125
	v_fma_f32 v125, -v67, v143, v125
	v_fma_f32 v125, -v68, v144, v125
	v_fma_f32 v125, -v69, v145, v125
	v_fma_f32 v125, -v70, v146, v125
	v_fma_f32 v125, -v71, v147, v125
	v_fma_f32 v125, -v72, v148, v125
	v_fma_f32 v125, -v73, v149, v125
	v_fma_f32 v125, -v74, v150, v125
	v_fma_f32 v125, -v75, v151, v125
	v_fma_f32 v125, -v76, v152, v125
	v_fma_f32 v125, -v77, v153, v125
	v_fma_f32 v125, -v78, v154, v125
	v_fma_f32 v125, -v79, v155, v125
	v_fma_f32 v125, -v80, v156, v125
	v_fma_f32 v125, -v81, v157, v125
	v_fma_f32 v125, -v82, v158, v125
	v_fma_f32 v125, -v83, v159, v125
	v_fma_f32 v125, -v84, v160, v125
	v_fma_f32 v125, -v85, v161, v125
	v_fma_f32 v125, -v86, v162, v125
	v_fma_f32 v125, -v87, v163, v125
	v_fma_f32 v125, -v88, v164, v125
	v_fma_f32 v125, -v89, v165, v125
	v_fma_f32 v125, -v90, v166, v125
	v_fma_f32 v125, -v91, v167, v125
	v_fma_f32 v125, -v92, v168, v125
	v_fma_f32 v125, -v93, v169, v125
	v_fma_f32 v125, -v94, v170, v125
	v_fma_f32 v125, -v95, v171, v125
	v_fma_f32 v125, -v96, v172, v125
	v_fma_f32 v125, -v97, v173, v125
	v_fma_f32 v125, -v98, v174, v125
	v_fma_f32 v125, -v99, v175, v125
	v_fma_f32 v125, -v100, v176, v125
	v_fma_f32 v125, -v101, v177, v125
	v_fma_f32 v125, -v102, v178, v125
	v_fma_f32 v125, -v103, v179, v125
	v_fma_f32 v125, -v104, v180, v125
	v_fma_f32 v125, -v105, v181, v125
	v_fma_f32 v125, -v106, v182, v125
	v_fma_f32 v125, -v107, v183, v125
	v_fma_f32 v125, -v108, v184, v125
	v_fma_f32 v125, -v109, v185, v125
	v_fma_f32 v125, -v110, v186, v125
	v_fma_f32 v125, -v111, v187, v125
	v_fma_f32 v125, -v112, v188, v125
	v_fma_f32 v125, -v113, v189, v125
	v_fma_f32 v125, -v114, v190, v125
	v_fma_f32 v125, -v115, v191, v125
	v_fma_f32 v125, -v116, v244, v125
	v_fma_f32 v125, -v117, v245, v125
	v_fma_f32 v125, -v118, v246, v125
	v_fma_f32 v125, -v119, v247, v125
	v_fma_f32 v125, -v120, v248, v125
	v_fma_f32 v125, -v121, v249, v125
	v_fma_f32 v125, -v122, v250, v125
	v_fma_f32 v125, -v123, v251, v125
	v_fma_mixlo_f16 v2, -v124, v4, v125
	v_fma_f32 v125, -v124, v4, v125
	s_waitcnt lgkmcnt(14)
; #define LAS __attribute__((address_space(3)))
; __device__ __forceinline__ void phase_gdb(const int wvs, const Params& p, LAS unsigned char* lds, int nwg) {
;     ...
;       for (int i = 1; i < 64; ++i) {
; #pragma unroll
;         for (int j4 = 0; j4 < (i + 3) / 4; ++j4) { const f32x4 m4 = *(const LAS f32x4*)(M + i * 64 + j4 * 4);
; #pragma unroll
;           for (int jj = 0; jj < 4; ++jj) if (j4 * 4 + jj < i) x[i] -= m4[jj] * x[j4 * 4 + jj]; }
;         __builtin_amdgcn_sched_barrier(0); }
; #pragma unroll
;       for (int i = 0; i < 64; ++i) R[i * RP + t] = (hf)x[i]; }
;     __syncthreads();
	ds_write_b16 v232, v2 offset:32976
	s_waitcnt lgkmcnt(14)
	ds_read_b128 v[136:139], v228 offset:16128
	s_waitcnt lgkmcnt(14)
	ds_read_b128 v[140:143], v228 offset:16144
	s_waitcnt lgkmcnt(14)
	ds_read_b128 v[144:147], v228 offset:16160
	s_waitcnt lgkmcnt(14)
	ds_read_b128 v[148:151], v228 offset:16176
	s_waitcnt lgkmcnt(14)
	ds_read_b128 v[152:155], v228 offset:16192
	s_waitcnt lgkmcnt(14)
	ds_read_b128 v[156:159], v228 offset:16208
	s_waitcnt lgkmcnt(14)
	ds_read_b128 v[160:163], v228 offset:16224
	s_waitcnt lgkmcnt(14)
	ds_read_b128 v[164:167], v228 offset:16240
	s_waitcnt lgkmcnt(14)
	ds_read_b128 v[168:171], v228 offset:16256
	s_waitcnt lgkmcnt(14)
	ds_read_b128 v[172:175], v228 offset:16272
	s_waitcnt lgkmcnt(14)
	ds_read_b128 v[176:179], v228 offset:16288
	s_waitcnt lgkmcnt(14)
	ds_read_b128 v[180:183], v228 offset:16304
	s_waitcnt lgkmcnt(14)
	ds_read_b128 v[184:187], v228 offset:16320
	s_waitcnt lgkmcnt(14)
	ds_read_b128 v[188:191], v228 offset:16336
	s_waitcnt lgkmcnt(14)
	ds_read_b128 v[244:247], v228 offset:16352
	s_waitcnt lgkmcnt(14)
	ds_read_b128 v[248:251], v228 offset:16368
	v_fma_f32 v126, -v64, v8, v126
	v_fma_f32 v126, -v65, v9, v126
	v_fma_f32 v126, -v66, v10, v126
	v_fma_f32 v126, -v67, v11, v126
	v_fma_f32 v126, -v68, v12, v126
	v_fma_f32 v126, -v69, v13, v126
	v_fma_f32 v126, -v70, v14, v126
	v_fma_f32 v126, -v71, v15, v126
	v_fma_f32 v126, -v72, v16, v126
	v_fma_f32 v126, -v73, v17, v126
	v_fma_f32 v126, -v74, v18, v126
	v_fma_f32 v126, -v75, v19, v126
	v_fma_f32 v126, -v76, v20, v126
	v_fma_f32 v126, -v77, v21, v126
	v_fma_f32 v126, -v78, v22, v126
	v_fma_f32 v126, -v79, v23, v126
	v_fma_f32 v126, -v80, v24, v126
	v_fma_f32 v126, -v81, v25, v126
	v_fma_f32 v126, -v82, v26, v126
	v_fma_f32 v126, -v83, v27, v126
	v_fma_f32 v126, -v84, v28, v126
	v_fma_f32 v126, -v85, v29, v126
	v_fma_f32 v126, -v86, v30, v126
	v_fma_f32 v126, -v87, v31, v126
	v_fma_f32 v126, -v88, v32, v126
	v_fma_f32 v126, -v89, v33, v126
	v_fma_f32 v126, -v90, v34, v126
	v_fma_f32 v126, -v91, v35, v126
	v_fma_f32 v126, -v92, v36, v126
	v_fma_f32 v126, -v93, v37, v126
	v_fma_f32 v126, -v94, v38, v126
	v_fma_f32 v126, -v95, v39, v126
	v_fma_f32 v126, -v96, v40, v126
	v_fma_f32 v126, -v97, v41, v126
	v_fma_f32 v126, -v98, v42, v126
	v_fma_f32 v126, -v99, v43, v126
	v_fma_f32 v126, -v100, v44, v126
	v_fma_f32 v126, -v101, v45, v126
	v_fma_f32 v126, -v102, v46, v126
	v_fma_f32 v126, -v103, v47, v126
	v_fma_f32 v126, -v104, v48, v126
	v_fma_f32 v126, -v105, v49, v126
	v_fma_f32 v126, -v106, v50, v126
	v_fma_f32 v126, -v107, v51, v126
	v_fma_f32 v126, -v108, v52, v126
	v_fma_f32 v126, -v109, v53, v126
	v_fma_f32 v126, -v110, v54, v126
	v_fma_f32 v126, -v111, v55, v126
	v_fma_f32 v126, -v112, v56, v126
	v_fma_f32 v126, -v113, v57, v126
	v_fma_f32 v126, -v114, v58, v126
	v_fma_f32 v126, -v115, v59, v126
	v_fma_f32 v126, -v116, v60, v126
	v_fma_f32 v126, -v117, v61, v126
	v_fma_f32 v126, -v118, v62, v126
	v_fma_f32 v126, -v119, v63, v126
	v_fma_f32 v126, -v120, v128, v126
	v_fma_f32 v126, -v121, v129, v126
	v_fma_f32 v126, -v122, v130, v126
	v_fma_f32 v126, -v123, v131, v126
	v_fma_f32 v126, -v124, v132, v126
	v_fma_mixlo_f16 v3, -v125, v133, v126
	v_fma_f32 v126, -v125, v133, v126
	s_waitcnt lgkmcnt(14)
	ds_write_b16 v232, v3 offset:33248
	s_waitcnt lgkmcnt(1)
	v_fma_f32 v127, -v64, v136, v127
	v_fma_f32 v127, -v65, v137, v127
	v_fma_f32 v127, -v66, v138, v127
	v_fma_f32 v127, -v67, v139, v127
	v_fma_f32 v127, -v68, v140, v127
	v_fma_f32 v127, -v69, v141, v127
	v_fma_f32 v127, -v70, v142, v127
	v_fma_f32 v127, -v71, v143, v127
	v_fma_f32 v127, -v72, v144, v127
	v_fma_f32 v127, -v73, v145, v127
	v_fma_f32 v127, -v74, v146, v127
	v_fma_f32 v127, -v75, v147, v127
	v_fma_f32 v127, -v76, v148, v127
	v_fma_f32 v127, -v77, v149, v127
	v_fma_f32 v127, -v78, v150, v127
	v_fma_f32 v127, -v79, v151, v127
	v_fma_f32 v127, -v80, v152, v127
	v_fma_f32 v127, -v81, v153, v127
	v_fma_f32 v127, -v82, v154, v127
	v_fma_f32 v127, -v83, v155, v127
	v_fma_f32 v127, -v84, v156, v127
	v_fma_f32 v127, -v85, v157, v127
	v_fma_f32 v127, -v86, v158, v127
	v_fma_f32 v127, -v87, v159, v127
	v_fma_f32 v127, -v88, v160, v127
	v_fma_f32 v127, -v89, v161, v127
	v_fma_f32 v127, -v90, v162, v127
	v_fma_f32 v127, -v91, v163, v127
	v_fma_f32 v127, -v92, v164, v127
	v_fma_f32 v127, -v93, v165, v127
	v_fma_f32 v127, -v94, v166, v127
	v_fma_f32 v127, -v95, v167, v127
	v_fma_f32 v127, -v96, v168, v127
	v_fma_f32 v127, -v97, v169, v127
	v_fma_f32 v127, -v98, v170, v127
	v_fma_f32 v127, -v99, v171, v127
	v_fma_f32 v127, -v100, v172, v127
	v_fma_f32 v127, -v101, v173, v127
	v_fma_f32 v127, -v102, v174, v127
	v_fma_f32 v127, -v103, v175, v127
	v_fma_f32 v127, -v104, v176, v127
	v_fma_f32 v127, -v105, v177, v127
	v_fma_f32 v127, -v106, v178, v127
	v_fma_f32 v127, -v107, v179, v127
	v_fma_f32 v127, -v108, v180, v127
	v_fma_f32 v127, -v109, v181, v127
	v_fma_f32 v127, -v110, v182, v127
	v_fma_f32 v127, -v111, v183, v127
	v_fma_f32 v127, -v112, v184, v127
	v_fma_f32 v127, -v113, v185, v127
	v_fma_f32 v127, -v114, v186, v127
	v_fma_f32 v127, -v115, v187, v127
	v_fma_f32 v127, -v116, v188, v127
	v_fma_f32 v127, -v117, v189, v127
	v_fma_f32 v127, -v118, v190, v127
	v_fma_f32 v127, -v119, v191, v127
	v_fma_f32 v127, -v120, v244, v127
	v_fma_f32 v127, -v121, v245, v127
	v_fma_f32 v127, -v122, v246, v127
	v_fma_f32 v127, -v123, v247, v127
	v_fma_f32 v127, -v124, v248, v127
	v_fma_f32 v127, -v125, v249, v127
	v_fma_mixlo_f16 v238, -v126, v250, v127
	v_fma_f32 v127, -v126, v250, v127
	ds_write_b16 v232, v238 offset:33520
	v_mov_b32_e32 v14, v224
	s_waitcnt lgkmcnt(0)
	s_barrier
; #define LAS __attribute__((address_space(3)))
; __device__ __forceinline__ void phase_gdb(const int wvs, const Params& p, LAS unsigned char* lds, int nwg) {
;     ...
;     { int tid2 = tid; asm volatile("" : "+v"(tid2));
;       const int tq2 = tid2 >> 7, t2 = tid2 & 127, rr2 = t2 >> 4, cc2 = (t2 & 15) * 8; LAS hf* R2 = (LAS hf*)(lds + tq2 * SLOT + 16384);
;       const int task2 = grp * 4 + tq2, d2 = task2 & 1, h2 = (task2 >> 1) % 6, n2 = (task2 / 12) % NCH64, b2 = task2 / (12 * NCH64); const size_t tokbase2 = (size_t)b2 * TPB + n2 * 64;
; #pragma unroll 1
;       for (int ps = 0; ps < 8; ++ps) { const int i = ps * 8 + rr2; const h8 v = *(const LAS h8*)(R2 + i * RP + cc2); const size_t tk = tokbase2 + (d2 ? 63 - i : i);
;         hf* dst = cc2 < 64 ? P + tk * PP + (d2 ? PC_GV : PC_GQ) + h2 * 64 + cc2 : (d2 == 0 ? P + tk * PP + PC_GK + h2 * 64 + cc2 - 64 : WB + tk * 384 + h2 * 64 + cc2 - 64);
	s_mov_b32 s2, 0x8700
	v_ashrrev_i32_e32 v0, 7, v14
	v_lshlrev_b32_e32 v2, 3, v14
	v_mul_lo_u32 v16, v0, s2
	v_add_u32_e32 v0, s12, v0
	v_and_b32_e32 v8, 0x78, v2
	v_ashrrev_i32_e32 v2, 1, v0
	v_mul_hi_i32 v3, v2, s52
	v_lshrrev_b32_e32 v4, 31, v3
	v_add_u32_e32 v3, v3, v4
	v_mul_lo_u32 v3, v3, 6
	v_sub_u32_e32 v9, v2, v3
	v_mul_hi_i32 v2, v0, s52
	v_lshrrev_b32_e32 v3, 31, v2
	v_ashrrev_i32_e32 v2, 1, v2
	v_add_u32_e32 v2, v2, v3
	v_mul_hi_i32 v3, v2, s89
	v_lshrrev_b32_e32 v4, 31, v3
	v_lshrrev_b32_e32 v3, 5, v3
	v_add_u32_e32 v3, v3, v4
	v_mul_lo_u32 v3, v3, s35
	s_mov_b32 s2, 0xa0a0a0a1
	v_sub_u32_e32 v4, v2, v3
	v_mul_hi_i32 v2, v0, s2
	v_add_u32_e32 v0, v2, v0
	v_lshrrev_b32_e32 v2, 31, v0
	v_ashrrev_i32_e32 v0, 9, v0
	v_add_u32_e32 v0, v0, v2
	v_lshlrev_b32_e32 v4, 6, v4
	v_mul_hi_i32_i24_e32 v3, 0x1100, v0
	v_mul_i32_i24_e32 v2, 0x1100, v0
	v_ashrrev_i32_e32 v5, 31, v4
	v_lshl_add_u64 v[6:7], v[2:3], 0, v[4:5]
	v_lshlrev_b32_e32 v2, 6, v9
	v_ashrrev_i32_e32 v3, 31, v2
	v_and_b32_e32 v0, 0x80, v14
	v_lshlrev_b64 v[2:3], 1, v[2:3]
	v_cmp_ne_u32_e64 s[8:9], 0, v0
	v_lshl_add_u64 v[4:5], s[14:15], 0, v[2:3]
	v_lshlrev_b32_e32 v0, 1, v8
	v_and_b32_e32 v12, 0x80, v14
	v_cmp_lt_u32_e64 s[10:11], 63, v8
	v_lshl_add_u64 v[8:9], v[4:5], 0, v[0:1]
	v_lshl_add_u64 v[4:5], s[16:17], 0, v[2:3]
	v_lshl_add_u64 v[10:11], v[4:5], 0, v[0:1]
	v_cmp_eq_u32_e64 s[12:13], 0, v12
	v_mov_b32_e32 v4, 0x800
	v_mov_b32_e32 v5, 0x200
	v_cndmask_b32_e64 v4, v4, v5, s[12:13]
	v_mov_b32_e32 v5, v1
	v_lshl_add_u64 v[4:5], s[16:17], 0, v[4:5]
	v_lshl_add_u64 v[2:3], v[4:5], 0, v[2:3]
	v_bfe_u32 v18, v14, 4, 3
	v_lshl_add_u64 v[12:13], v[2:3], 0, v[0:1]
	v_and_b32_e32 v2, 15, v14
	v_lshrrev_b32_e32 v15, 4, v14
	v_mad_u32_u24 v0, v18, s67, v16
	v_lshlrev_b32_e32 v2, 4, v2
	s_add_i32 s18, 0, 0x4000
	s_mov_b32 s2, 0
	v_bitop3_b32 v19, v15, 63, 7 bitop3:0x6c
	v_add3_u32 v20, v0, v2, s18
	s_branch .LBB0_1029

; __device__ __forceinline__ int ltid(int wvs) { int t = (wvs << 6) | (int)__builtin_amdgcn_mbcnt_hi(~0u, __builtin_amdgcn_mbcnt_lo(~0u, 0u)); asm volatile("" : "+v"(t)); return t; }
; __device__ __forceinline__ int lbid() { int b = __builtin_amdgcn_workgroup_id_x(); asm volatile("" : "+s"(b)); return b; }
; __device__ __forceinline__ void phase_rwa(const int wvs, const Params& p, int layer) {
;   const int lane = ltid(wvs) & 63, gw = lbid() * 8 + (ltid(wvs) >> 6);
;   hf* P = (hf*)(p.ws + OFF_BIG); hf* RL1 = (hf*)(p.ws + OFF_RL1); hf* RL3 = (hf*)(p.ws + OFF_RL3); float* INVN = (float*)(p.ws + OFF_INVN);
;   const float* mu = p.in[I_MU] + layer * 1536; const float* kkw = p.in[I_KK] + layer * 384;
;   int t0, tq;
;   if (gw < 768) { t0 = 3 * gw; tq = 3; } else if (gw < 1920) { t0 = 2304 + 11 * (gw - 768); tq = 11; } else { t0 = 14976 + 19 * (gw - 1920); tq = 19; }
.LBB0_1037:
	s_mov_b64 s[2:3], s[0:1]
	s_load_dwordx2 s[6:7], s[2:3], 0xc8
	s_load_dwordx2 s[4:5], s[2:3], 0xf8
	s_load_dwordx2 s[20:21], s[2:3], 0x138
	v_mov_b32_e32 v0, v193
	s_mov_b32 s2, s28
	v_mov_b32_e32 v2, v193
	s_nop 0
	v_ashrrev_i32_e32 v2, 6, v2
	v_lshl_add_u32 v2, s2, 3, v2
	s_movk_i32 s2, 0x2ff
	v_cmp_lt_i32_e32 vcc, s2, v2
	s_and_saveexec_b64 s[2:3], vcc
	s_xor_b64 s[8:9], exec, s[2:3]
	s_cbranch_execz .LBB0_1043
	s_movk_i32 s2, 0x77f
	v_cmp_lt_u32_e32 vcc, s2, v2
	s_and_saveexec_b64 s[2:3], vcc
	s_xor_b64 s[10:11], exec, s[2:3]
	v_mov_b32_e32 v4, 0xffffc400
	v_mov_b32_e32 v5, -1
	v_mad_u64_u32 v[78:79], s[2:3], v2, 16, v[4:5]
	s_or_saveexec_b64 s[10:11], s[10:11]
	v_mov_b32_e32 v4, 16
	s_xor_b64 exec, exec, s[10:11]
	v_mov_b32_e32 v6, 0xfffff100
	v_mov_b32_e32 v7, -1
	v_mov_b32_e32 v4, 10
	v_mad_u64_u32 v[78:79], s[2:3], v2, 10, v[6:7]
	s_or_b64 exec, exec, s[10:11]
.LBB0_1043:
	s_andn2_saveexec_b64 s[8:9], s[8:9]
	v_lshl_add_u32 v78, v2, 2, v2
	v_mov_b32_e32 v4, 5
	s_or_b64 exec, exec, s[8:9]
	v_mul_hi_i32 v2, v78, s89
	v_lshrrev_b32_e32 v3, 31, v2
	v_ashrrev_i32_e32 v2, 11, v2
	v_add_u32_e32 v2, v2, v3
	v_mul_i32_i24_e32 v2, 0x1100, v2
	v_sub_u32_e32 v2, v78, v2
	v_and_b32_e32 v82, 3, v0
	v_cmp_lt_i32_e32 vcc, s29, v2
	s_and_saveexec_b64 s[2:3], vcc
	s_xor_b64 s[8:9], exec, s[2:3]
	s_cbranch_execz .LBB0_1059
	v_cmp_lt_i32_e32 vcc, 1, v82
	s_and_saveexec_b64 s[2:3], vcc
	s_xor_b64 s[10:11], exec, s[2:3]
	s_cbranch_execz .LBB0_1052
	v_add_u32_e32 v2, 0xffffff00, v2
	v_cmp_lt_i32_e32 vcc, 2, v82
	s_and_saveexec_b64 s[2:3], vcc
	s_xor_b64 s[12:13], exec, s[2:3]
	s_movk_i32 s2, 0xfc0
	v_add_u32_e32 v3, 64, v78
	v_cmp_gt_u32_e32 vcc, s2, v2
	s_nop 1
	v_cndmask_b32_e32 v147, -1, v3, vcc
	s_andn2_saveexec_b64 s[12:13], s[12:13]
	v_subrev_u32_e32 v3, 64, v78
	v_cmp_lt_u32_e32 vcc, 63, v2
	s_nop 1
	v_cndmask_b32_e32 v147, -1, v3, vcc
	s_or_b64 exec, exec, s[12:13]

; #define LAS __attribute__((address_space(3)))
; __device__ __forceinline__ void phase_rwc(const int wvs, const Params& p, LAS unsigned char* lds, int layer, int wg0) {
;     ...
;   } else {
;     const int rowl = wv * 4 + (lane >> 4), kg = lane & 15;
;     f32x4 S = {0.f, 0.f, 0.f, 0.f};
;     __syncthreads();
; #pragma unroll 2
;     for (int blk = 0; blk < NBLK; ++blk) {
;       LAS float* Wv = (LAS float*)(lds + (blk & 1) * BUFSZ) + kg * 4; LAS float* Vv = (LAS float*)(lds + (blk & 1) * BUFSZ) + 5 * 2048 + rowl;
;       LAS float* ypw = (LAS float*)(lds + YOFF + (blk & 1) * YSZ) + rowl * 16 + kg;
;       asm volatile("" : "+v"(Wv), "+v"(Vv), "+v"(ypw));
;       f32x4 w4 = *(const LAS f32x4*)(Wv), kk4 = *(const LAS f32x4*)(Wv + 2048), b4 = *(const LAS f32x4*)(Wv + 4096), kd4 = *(const LAS f32x4*)(Wv + 6144), r4 = *(const LAS f32x4*)(Wv + 8192); float vv = Vv[0];
;       f32x4 xw4 = *(const LAS f32x4*)(Wv + 64), xkk4 = *(const LAS f32x4*)(Wv + 2048 + 64), xb4 = *(const LAS f32x4*)(Wv + 4096 + 64), xkd4 = *(const LAS f32x4*)(Wv + 6144 + 64), xr4 = *(const LAS f32x4*)(Wv + 8192 + 64); float xvv = Vv[16];
; #pragma unroll 16
;       for (int t = 0; t < 32; ++t) {
;         const int tn = t + 2;
;         const f32x4 nw4 = *(const LAS f32x4*)(Wv + tn * 64), nkk4 = *(const LAS f32x4*)(Wv + 2048 + tn * 64), nb4 = *(const LAS f32x4*)(Wv + 4096 + tn * 64), nkd4 = *(const LAS f32x4*)(Wv + 6144 + tn * 64), nr4 = *(const LAS f32x4*)(Wv + 8192 + tn * 64);
;         const float nvv = Vv[tn * 16];
;         const f32x4 pa = S * kk4;
;         const f32x4 t1 = S * w4 + vv * kd4;
;         float sa = (pa[0] + pa[2]) + (pa[1] + pa[3]);
;         sa = row16_sum(sa);
;         S = t1 + sa * b4;
;         const f32x4 py = S * r4;
;         ypw[t * 256] = (py[0] + py[2]) + (py[1] + py[3]);
.LBB0_1240:
	s_mov_b64 s[4:5], s[0:1]
	s_mov_b32 s10, s28
	s_add_i32 s2, s10, 0xffffff10
	s_cmp_lt_u32 s2, 0xffffff40
	s_cbranch_scc1 .LBB0_1367
	v_mov_b32_e32 v25, v193
	s_nop 0
	v_ashrrev_i32_e32 v0, 6, v25
	v_cmp_gt_i32_e32 vcc, 4, v0
	v_and_b32_e32 v17, 15, v25
	s_and_saveexec_b64 s[6:7], vcc
	s_xor_b64 s[6:7], exec, s[6:7]
	s_cbranch_execz .LBB0_1248
	v_bfe_u32 v2, v25, 4, 2
	v_lshl_or_b32 v0, v0, 2, v2
	v_lshlrev_b32_e32 v2, 6, v0
	v_lshlrev_b32_e32 v3, 2, v17
	v_readlane_b32 s2, v254, 5
	v_lshlrev_b32_e32 v0, 2, v0
	v_lshl_add_u32 v69, v17, 4, 0
	v_add3_u32 v68, s2, v2, v3
	v_add_u32_e32 v2, 0, v0
	v_add_u32_e32 v70, 0xa000, v2
	v_readlane_b32 s2, v254, 6
	v_mov_b32_e32 v2, v1
	v_mov_b32_e32 v3, v1
	v_add_u32_e32 v72, s2, v0
	v_mov_b32_e32 v0, v1
	v_mov_b64_e32 v[4:5], v[2:3]
	v_add_u32_e32 v71, 0xa800, v69
	v_add_u32_e32 v73, 0x8000, v68
	s_mov_b32 s8, 0
	v_mov_b64_e32 v[2:3], v[0:1]
	s_waitcnt lgkmcnt(0)
	s_barrier
	v_mov_b32_e32 v80, v69
	v_mov_b32_e32 v82, v68
	v_mov_b32_e32 v83, v71
	v_mov_b32_e32 v85, v73
	v_add_u32_e32 v81, 0xffff6000, v70
	v_lshlrev_b32_e32 v81, 5, v81
	v_add_u32_e32 v81, 0xa000, v81
	v_add_u32_e32 v84, 0xa800, v81
.Lrwc_scan:
	ds_read_b128 v[20:23], v80 offset:8192
	ds_read_b128 v[24:27], v80 offset:24576
	ds_read_b128 v[12:15], v81 offset:0
	ds_read_b128 v[28:31], v80 offset:0
	ds_read_b128 v[32:35], v80 offset:16384
	ds_read_b128 v[36:39], v80 offset:32768
	ds_read_b128 v[40:43], v80 offset:8448
	ds_read_b128 v[44:47], v80 offset:24832
	ds_read_b128 v[48:51], v80 offset:256
	ds_read_b128 v[52:55], v80 offset:16640
	ds_read_b128 v[56:59], v80 offset:33024
	s_waitcnt lgkmcnt(10)
	v_pk_mul_f32 v[6:7], v[22:23], v[4:5]
	v_pk_fma_f32 v[6:7], v[20:21], v[2:3], v[6:7]
	s_waitcnt lgkmcnt(5)
	v_add_f32_e32 v0, v6, v7
	v_pk_mul_f32 v[10:11], v[26:27], v[12:13] op_sel_hi:[1,0]
	v_pk_mul_f32 v[8:9], v[24:25], v[12:13] op_sel_hi:[1,0]
	v_add_f32_dpp v0, v0, v0 quad_perm:[1,0,3,2] row_mask:0xf bank_mask:0xf bound_ctrl:1
	v_pk_fma_f32 v[10:11], v[30:31], v[4:5], v[10:11]
	v_pk_fma_f32 v[8:9], v[28:29], v[2:3], v[8:9]
	v_add_f32_dpp v0, v0, v0 quad_perm:[2,3,0,1] row_mask:0xf bank_mask:0xf bound_ctrl:1
	ds_read_b128 v[60:63], v80 offset:8704
	ds_read_b128 v[64:67], v80 offset:25088
	ds_read_b128 v[68:71], v80 offset:512
	ds_read_b128 v[72:75], v80 offset:16896
	ds_read_b128 v[76:79], v80 offset:33280
	v_add_f32_dpp v0, v0, v0 row_half_mirror row_mask:0xf bank_mask:0xf bound_ctrl:1
	s_nop 1
	v_add_f32_dpp v0, v0, v0 row_mirror row_mask:0xf bank_mask:0xf bound_ctrl:1
	v_pk_fma_f32 v[4:5], v[34:35], v[0:1], v[10:11] op_sel_hi:[1,0,1]
	s_waitcnt lgkmcnt(9)
	v_pk_mul_f32 v[6:7], v[42:43], v[4:5]
	v_pk_fma_f32 v[2:3], v[32:33], v[0:1], v[8:9] op_sel_hi:[1,0,1]
	v_pk_fma_f32 v[6:7], v[40:41], v[2:3], v[6:7]
	s_waitcnt lgkmcnt(5)
	v_add_f32_e32 v0, v6, v7
	v_pk_mul_f32 v[6:7], v[38:39], v[4:5]
	v_pk_fma_f32 v[6:7], v[36:37], v[2:3], v[6:7]
	v_add_f32_dpp v0, v0, v0 quad_perm:[1,0,3,2] row_mask:0xf bank_mask:0xf bound_ctrl:1
	v_pk_mul_f32 v[10:11], v[46:47], v[12:13] op_sel:[0,1] op_sel_hi:[1,1]
	v_pk_mul_f32 v[8:9], v[44:45], v[12:13] op_sel:[0,1] op_sel_hi:[1,1]
	v_add_f32_dpp v0, v0, v0 quad_perm:[2,3,0,1] row_mask:0xf bank_mask:0xf bound_ctrl:1
	ds_read_b128 v[20:23], v80 offset:8960
	ds_read_b128 v[24:27], v80 offset:25344
	ds_read_b128 v[28:31], v80 offset:768
	ds_read_b128 v[32:35], v80 offset:17152
	ds_read_b128 v[36:39], v80 offset:33536
	ds_read_b128 v[16:19], v81 offset:16
	v_add_f32_e32 v6, v6, v7
	ds_write_b32 v82, v6 offset:0
	v_add_f32_dpp v0, v0, v0 row_half_mirror row_mask:0xf bank_mask:0xf bound_ctrl:1
	v_pk_fma_f32 v[10:11], v[50:51], v[4:5], v[10:11]
	v_pk_fma_f32 v[8:9], v[48:49], v[2:3], v[8:9]
	v_add_f32_dpp v0, v0, v0 row_mirror row_mask:0xf bank_mask:0xf bound_ctrl:1
	v_pk_fma_f32 v[4:5], v[54:55], v[0:1], v[10:11] op_sel_hi:[1,0,1]
	s_waitcnt lgkmcnt(11)
	v_pk_mul_f32 v[6:7], v[62:63], v[4:5]
	v_pk_fma_f32 v[2:3], v[52:53], v[0:1], v[8:9] op_sel_hi:[1,0,1]
	v_pk_fma_f32 v[6:7], v[60:61], v[2:3], v[6:7]
	s_waitcnt lgkmcnt(7)
	v_add_f32_e32 v0, v6, v7
	v_pk_mul_f32 v[6:7], v[58:59], v[4:5]
	v_pk_fma_f32 v[6:7], v[56:57], v[2:3], v[6:7]
	v_add_f32_dpp v0, v0, v0 quad_perm:[1,0,3,2] row_mask:0xf bank_mask:0xf bound_ctrl:1
	v_pk_mul_f32 v[10:11], v[66:67], v[14:15] op_sel_hi:[1,0]
	v_pk_mul_f32 v[8:9], v[64:65], v[14:15] op_sel_hi:[1,0]
	v_add_f32_dpp v0, v0, v0 quad_perm:[2,3,0,1] row_mask:0xf bank_mask:0xf bound_ctrl:1
	ds_read_b128 v[40:43], v80 offset:9216
	ds_read_b128 v[44:47], v80 offset:25600
	ds_read_b128 v[48:51], v80 offset:1024
	ds_read_b128 v[52:55], v80 offset:17408
	ds_read_b128 v[56:59], v80 offset:33792
	v_add_f32_e32 v6, v6, v7
	ds_write_b32 v82, v6 offset:1024
	v_add_f32_dpp v0, v0, v0 row_half_mirror row_mask:0xf bank_mask:0xf bound_ctrl:1
	v_pk_fma_f32 v[10:11], v[70:71], v[4:5], v[10:11]
	v_pk_fma_f32 v[8:9], v[68:69], v[2:3], v[8:9]
	v_add_f32_dpp v0, v0, v0 row_mirror row_mask:0xf bank_mask:0xf bound_ctrl:1
	v_pk_fma_f32 v[4:5], v[74:75], v[0:1], v[10:11] op_sel_hi:[1,0,1]
	s_waitcnt lgkmcnt(12)
	v_pk_mul_f32 v[6:7], v[22:23], v[4:5]
	v_pk_fma_f32 v[2:3], v[72:73], v[0:1], v[8:9] op_sel_hi:[1,0,1]
	v_pk_fma_f32 v[6:7], v[20:21], v[2:3], v[6:7]
	s_waitcnt lgkmcnt(8)
; #define LAS __attribute__((address_space(3)))
; __device__ __forceinline__ void phase_rwc(const int wvs, const Params& p, LAS unsigned char* lds, int layer, int wg0) {
;     ...
; #pragma unroll 16
;       for (int t = 0; t < 32; ++t) {
;         const int tn = t + 2;
;         const f32x4 nw4 = *(const LAS f32x4*)(Wv + tn * 64), nkk4 = *(const LAS f32x4*)(Wv + 2048 + tn * 64), nb4 = *(const LAS f32x4*)(Wv + 4096 + tn * 64), nkd4 = *(const LAS f32x4*)(Wv + 6144 + tn * 64), nr4 = *(const LAS f32x4*)(Wv + 8192 + tn * 64);
;         const float nvv = Vv[tn * 16];
;         const f32x4 pa = S * kk4;
;         const f32x4 t1 = S * w4 + vv * kd4;
;         float sa = (pa[0] + pa[2]) + (pa[1] + pa[3]);
;         sa = row16_sum(sa);
;         S = t1 + sa * b4;
;         const f32x4 py = S * r4;
;         ypw[t * 256] = (py[0] + py[2]) + (py[1] + py[3]);
;         w4 = xw4; kk4 = xkk4; b4 = xb4; kd4 = xkd4; r4 = xr4; vv = xvv;
;         xw4 = nw4; xkk4 = nkk4; xb4 = nb4; xkd4 = nkd4; xr4 = nr4; xvv = nvv;
;       }
	v_add_f32_e32 v0, v6, v7
	v_pk_mul_f32 v[6:7], v[78:79], v[4:5]
	v_pk_fma_f32 v[6:7], v[76:77], v[2:3], v[6:7]
	v_add_f32_dpp v0, v0, v0 quad_perm:[1,0,3,2] row_mask:0xf bank_mask:0xf bound_ctrl:1
	v_pk_mul_f32 v[10:11], v[26:27], v[14:15] op_sel:[0,1] op_sel_hi:[1,1]
	v_pk_mul_f32 v[8:9], v[24:25], v[14:15] op_sel:[0,1] op_sel_hi:[1,1]
	v_add_f32_dpp v0, v0, v0 quad_perm:[2,3,0,1] row_mask:0xf bank_mask:0xf bound_ctrl:1
	ds_read_b128 v[60:63], v80 offset:9472
	ds_read_b128 v[64:67], v80 offset:25856
	ds_read_b128 v[68:71], v80 offset:1280
	ds_read_b128 v[72:75], v80 offset:17664
	ds_read_b128 v[76:79], v80 offset:34048
	v_add_f32_e32 v6, v6, v7
	ds_write_b32 v82, v6 offset:2048
	v_add_f32_dpp v0, v0, v0 row_half_mirror row_mask:0xf bank_mask:0xf bound_ctrl:1
	v_pk_fma_f32 v[10:11], v[30:31], v[4:5], v[10:11]
	v_pk_fma_f32 v[8:9], v[28:29], v[2:3], v[8:9]
	v_add_f32_dpp v0, v0, v0 row_mirror row_mask:0xf bank_mask:0xf bound_ctrl:1
	v_pk_fma_f32 v[4:5], v[34:35], v[0:1], v[10:11] op_sel_hi:[1,0,1]
	s_waitcnt lgkmcnt(11)
	v_pk_mul_f32 v[6:7], v[42:43], v[4:5]
	v_pk_fma_f32 v[2:3], v[32:33], v[0:1], v[8:9] op_sel_hi:[1,0,1]
	v_pk_fma_f32 v[6:7], v[40:41], v[2:3], v[6:7]
	s_waitcnt lgkmcnt(7)
	v_add_f32_e32 v0, v6, v7
	v_pk_mul_f32 v[6:7], v[38:39], v[4:5]
	v_pk_fma_f32 v[6:7], v[36:37], v[2:3], v[6:7]
	v_add_f32_dpp v0, v0, v0 quad_perm:[1,0,3,2] row_mask:0xf bank_mask:0xf bound_ctrl:1
	v_pk_mul_f32 v[10:11], v[46:47], v[16:17] op_sel_hi:[1,0]
	v_pk_mul_f32 v[8:9], v[44:45], v[16:17] op_sel_hi:[1,0]
	v_add_f32_dpp v0, v0, v0 quad_perm:[2,3,0,1] row_mask:0xf bank_mask:0xf bound_ctrl:1
	ds_read_b128 v[20:23], v80 offset:9728
	ds_read_b128 v[24:27], v80 offset:26112
	ds_read_b128 v[28:31], v80 offset:1536
	ds_read_b128 v[32:35], v80 offset:17920
	ds_read_b128 v[36:39], v80 offset:34304
	v_add_f32_e32 v6, v6, v7
	ds_write_b32 v82, v6 offset:3072
	v_add_f32_dpp v0, v0, v0 row_half_mirror row_mask:0xf bank_mask:0xf bound_ctrl:1
	v_pk_fma_f32 v[10:11], v[50:51], v[4:5], v[10:11]
	v_pk_fma_f32 v[8:9], v[48:49], v[2:3], v[8:9]
	v_add_f32_dpp v0, v0, v0 row_mirror row_mask:0xf bank_mask:0xf bound_ctrl:1
	v_pk_fma_f32 v[4:5], v[54:55], v[0:1], v[10:11] op_sel_hi:[1,0,1]
	s_waitcnt lgkmcnt(11)
	v_pk_mul_f32 v[6:7], v[62:63], v[4:5]
	v_pk_fma_f32 v[2:3], v[52:53], v[0:1], v[8:9] op_sel_hi:[1,0,1]
	v_pk_fma_f32 v[6:7], v[60:61], v[2:3], v[6:7]
	s_waitcnt lgkmcnt(7)
	v_add_f32_e32 v0, v6, v7
	v_pk_mul_f32 v[6:7], v[58:59], v[4:5]
	v_pk_fma_f32 v[6:7], v[56:57], v[2:3], v[6:7]
	v_add_f32_dpp v0, v0, v0 quad_perm:[1,0,3,2] row_mask:0xf bank_mask:0xf bound_ctrl:1
	v_pk_mul_f32 v[10:11], v[66:67], v[16:17] op_sel:[0,1] op_sel_hi:[1,1]
	v_pk_mul_f32 v[8:9], v[64:65], v[16:17] op_sel:[0,1] op_sel_hi:[1,1]
	v_add_f32_dpp v0, v0, v0 quad_perm:[2,3,0,1] row_mask:0xf bank_mask:0xf bound_ctrl:1
	ds_read_b128 v[40:43], v80 offset:9984
	ds_read_b128 v[44:47], v80 offset:26368
	ds_read_b128 v[48:51], v80 offset:1792
	ds_read_b128 v[52:55], v80 offset:18176
	ds_read_b128 v[56:59], v80 offset:34560
	ds_read_b128 v[12:15], v81 offset:32
	v_add_f32_e32 v6, v6, v7
	ds_write_b32 v82, v6 offset:4096
	v_add_f32_dpp v0, v0, v0 row_half_mirror row_mask:0xf bank_mask:0xf bound_ctrl:1
	v_pk_fma_f32 v[10:11], v[70:71], v[4:5], v[10:11]
	v_pk_fma_f32 v[8:9], v[68:69], v[2:3], v[8:9]
	v_add_f32_dpp v0, v0, v0 row_mirror row_mask:0xf bank_mask:0xf bound_ctrl:1
	v_pk_fma_f32 v[4:5], v[74:75], v[0:1], v[10:11] op_sel_hi:[1,0,1]
	s_waitcnt lgkmcnt(12)
	v_pk_mul_f32 v[6:7], v[22:23], v[4:5]
	v_pk_fma_f32 v[2:3], v[72:73], v[0:1], v[8:9] op_sel_hi:[1,0,1]
	v_pk_fma_f32 v[6:7], v[20:21], v[2:3], v[6:7]
	s_waitcnt lgkmcnt(8)
	v_add_f32_e32 v0, v6, v7
	v_pk_mul_f32 v[6:7], v[78:79], v[4:5]
	v_pk_fma_f32 v[6:7], v[76:77], v[2:3], v[6:7]
	v_add_f32_dpp v0, v0, v0 quad_perm:[1,0,3,2] row_mask:0xf bank_mask:0xf bound_ctrl:1
	v_pk_mul_f32 v[10:11], v[26:27], v[18:19] op_sel_hi:[1,0]
	v_pk_mul_f32 v[8:9], v[24:25], v[18:19] op_sel_hi:[1,0]
	v_add_f32_dpp v0, v0, v0 quad_perm:[2,3,0,1] row_mask:0xf bank_mask:0xf bound_ctrl:1
	ds_read_b128 v[60:63], v80 offset:10240
	ds_read_b128 v[64:67], v80 offset:26624
	ds_read_b128 v[68:71], v80 offset:2048
	ds_read_b128 v[72:75], v80 offset:18432
	ds_read_b128 v[76:79], v80 offset:34816
	v_add_f32_e32 v6, v6, v7
	ds_write_b32 v82, v6 offset:5120
	v_add_f32_dpp v0, v0, v0 row_half_mirror row_mask:0xf bank_mask:0xf bound_ctrl:1
	v_pk_fma_f32 v[10:11], v[30:31], v[4:5], v[10:11]
	v_pk_fma_f32 v[8:9], v[28:29], v[2:3], v[8:9]
	v_add_f32_dpp v0, v0, v0 row_mirror row_mask:0xf bank_mask:0xf bound_ctrl:1
	v_pk_fma_f32 v[4:5], v[34:35], v[0:1], v[10:11] op_sel_hi:[1,0,1]
	s_waitcnt lgkmcnt(12)
	v_pk_mul_f32 v[6:7], v[42:43], v[4:5]
	v_pk_fma_f32 v[2:3], v[32:33], v[0:1], v[8:9] op_sel_hi:[1,0,1]
	v_pk_fma_f32 v[6:7], v[40:41], v[2:3], v[6:7]
	s_waitcnt lgkmcnt(8)
	v_add_f32_e32 v0, v6, v7
	v_pk_mul_f32 v[6:7], v[38:39], v[4:5]
	v_pk_fma_f32 v[6:7], v[36:37], v[2:3], v[6:7]
	v_add_f32_dpp v0, v0, v0 quad_perm:[1,0,3,2] row_mask:0xf bank_mask:0xf bound_ctrl:1
	v_pk_mul_f32 v[10:11], v[46:47], v[18:19] op_sel:[0,1] op_sel_hi:[1,1]
	v_pk_mul_f32 v[8:9], v[44:45], v[18:19] op_sel:[0,1] op_sel_hi:[1,1]
	v_add_f32_dpp v0, v0, v0 quad_perm:[2,3,0,1] row_mask:0xf bank_mask:0xf bound_ctrl:1
	ds_read_b128 v[20:23], v80 offset:10496
	ds_read_b128 v[24:27], v80 offset:26880
	ds_read_b128 v[28:31], v80 offset:2304
	ds_read_b128 v[32:35], v80 offset:18688
	ds_read_b128 v[36:39], v80 offset:35072
	v_add_f32_e32 v6, v6, v7
	ds_write_b32 v82, v6 offset:6144
	v_add_f32_dpp v0, v0, v0 row_half_mirror row_mask:0xf bank_mask:0xf bound_ctrl:1
	v_pk_fma_f32 v[10:11], v[50:51], v[4:5], v[10:11]
	v_pk_fma_f32 v[8:9], v[48:49], v[2:3], v[8:9]
	v_add_f32_dpp v0, v0, v0 row_mirror row_mask:0xf bank_mask:0xf bound_ctrl:1
	v_pk_fma_f32 v[4:5], v[54:55], v[0:1], v[10:11] op_sel_hi:[1,0,1]
	s_waitcnt lgkmcnt(11)
; #define LAS __attribute__((address_space(3)))
; __device__ __forceinline__ void phase_rwc(const int wvs, const Params& p, LAS unsigned char* lds, int layer, int wg0) {
;     ...
; #pragma unroll 16
;       for (int t = 0; t < 32; ++t) {
;         const int tn = t + 2;
;         const f32x4 nw4 = *(const LAS f32x4*)(Wv + tn * 64), nkk4 = *(const LAS f32x4*)(Wv + 2048 + tn * 64), nb4 = *(const LAS f32x4*)(Wv + 4096 + tn * 64), nkd4 = *(const LAS f32x4*)(Wv + 6144 + tn * 64), nr4 = *(const LAS f32x4*)(Wv + 8192 + tn * 64);
;         const float nvv = Vv[tn * 16];
;         const f32x4 pa = S * kk4;
;         const f32x4 t1 = S * w4 + vv * kd4;
;         float sa = (pa[0] + pa[2]) + (pa[1] + pa[3]);
;         sa = row16_sum(sa);
;         S = t1 + sa * b4;
;         const f32x4 py = S * r4;
;         ypw[t * 256] = (py[0] + py[2]) + (py[1] + py[3]);
;         w4 = xw4; kk4 = xkk4; b4 = xb4; kd4 = xkd4; r4 = xr4; vv = xvv;
;         xw4 = nw4; xkk4 = nkk4; xb4 = nb4; xkd4 = nkd4; xr4 = nr4; xvv = nvv;
;       }
	v_pk_mul_f32 v[6:7], v[62:63], v[4:5]
	v_pk_fma_f32 v[2:3], v[52:53], v[0:1], v[8:9] op_sel_hi:[1,0,1]
	v_pk_fma_f32 v[6:7], v[60:61], v[2:3], v[6:7]
	s_waitcnt lgkmcnt(7)
	v_add_f32_e32 v0, v6, v7
	v_pk_mul_f32 v[6:7], v[58:59], v[4:5]
	v_pk_fma_f32 v[6:7], v[56:57], v[2:3], v[6:7]
	v_add_f32_dpp v0, v0, v0 quad_perm:[1,0,3,2] row_mask:0xf bank_mask:0xf bound_ctrl:1
	v_pk_mul_f32 v[10:11], v[66:67], v[12:13] op_sel_hi:[1,0]
	v_pk_mul_f32 v[8:9], v[64:65], v[12:13] op_sel_hi:[1,0]
	v_add_f32_dpp v0, v0, v0 quad_perm:[2,3,0,1] row_mask:0xf bank_mask:0xf bound_ctrl:1
	ds_read_b128 v[40:43], v80 offset:10752
	ds_read_b128 v[44:47], v80 offset:27136
	ds_read_b128 v[48:51], v80 offset:2560
	ds_read_b128 v[52:55], v80 offset:18944
	ds_read_b128 v[56:59], v80 offset:35328
	v_add_f32_e32 v6, v6, v7
	ds_write_b32 v82, v6 offset:7168
	v_add_f32_dpp v0, v0, v0 row_half_mirror row_mask:0xf bank_mask:0xf bound_ctrl:1
	v_pk_fma_f32 v[10:11], v[70:71], v[4:5], v[10:11]
	v_pk_fma_f32 v[8:9], v[68:69], v[2:3], v[8:9]
	v_add_f32_dpp v0, v0, v0 row_mirror row_mask:0xf bank_mask:0xf bound_ctrl:1
	v_pk_fma_f32 v[4:5], v[74:75], v[0:1], v[10:11] op_sel_hi:[1,0,1]
	s_waitcnt lgkmcnt(11)
	v_pk_mul_f32 v[6:7], v[22:23], v[4:5]
	v_pk_fma_f32 v[2:3], v[72:73], v[0:1], v[8:9] op_sel_hi:[1,0,1]
	v_pk_fma_f32 v[6:7], v[20:21], v[2:3], v[6:7]
	s_waitcnt lgkmcnt(7)
	v_add_f32_e32 v0, v6, v7
	v_pk_mul_f32 v[6:7], v[78:79], v[4:5]
	v_pk_fma_f32 v[6:7], v[76:77], v[2:3], v[6:7]
	v_add_f32_dpp v0, v0, v0 quad_perm:[1,0,3,2] row_mask:0xf bank_mask:0xf bound_ctrl:1
	v_pk_mul_f32 v[10:11], v[26:27], v[12:13] op_sel:[0,1] op_sel_hi:[1,1]
	v_pk_mul_f32 v[8:9], v[24:25], v[12:13] op_sel:[0,1] op_sel_hi:[1,1]
	v_add_f32_dpp v0, v0, v0 quad_perm:[2,3,0,1] row_mask:0xf bank_mask:0xf bound_ctrl:1
	ds_read_b128 v[60:63], v80 offset:11008
	ds_read_b128 v[64:67], v80 offset:27392
	ds_read_b128 v[68:71], v80 offset:2816
	ds_read_b128 v[72:75], v80 offset:19200
	ds_read_b128 v[76:79], v80 offset:35584
	ds_read_b128 v[16:19], v81 offset:48
	v_add_f32_e32 v6, v6, v7
	ds_write_b32 v82, v6 offset:8192
	v_add_f32_dpp v0, v0, v0 row_half_mirror row_mask:0xf bank_mask:0xf bound_ctrl:1
	v_pk_fma_f32 v[10:11], v[30:31], v[4:5], v[10:11]
	v_pk_fma_f32 v[8:9], v[28:29], v[2:3], v[8:9]
	v_add_f32_dpp v0, v0, v0 row_mirror row_mask:0xf bank_mask:0xf bound_ctrl:1
	v_pk_fma_f32 v[4:5], v[34:35], v[0:1], v[10:11] op_sel_hi:[1,0,1]
	s_waitcnt lgkmcnt(12)
	v_pk_mul_f32 v[6:7], v[42:43], v[4:5]
	v_pk_fma_f32 v[2:3], v[32:33], v[0:1], v[8:9] op_sel_hi:[1,0,1]
	v_pk_fma_f32 v[6:7], v[40:41], v[2:3], v[6:7]
	s_waitcnt lgkmcnt(8)
	v_add_f32_e32 v0, v6, v7
	v_pk_mul_f32 v[6:7], v[38:39], v[4:5]
	v_pk_fma_f32 v[6:7], v[36:37], v[2:3], v[6:7]
	v_add_f32_dpp v0, v0, v0 quad_perm:[1,0,3,2] row_mask:0xf bank_mask:0xf bound_ctrl:1
	v_pk_mul_f32 v[10:11], v[46:47], v[14:15] op_sel_hi:[1,0]
	v_pk_mul_f32 v[8:9], v[44:45], v[14:15] op_sel_hi:[1,0]
	v_add_f32_dpp v0, v0, v0 quad_perm:[2,3,0,1] row_mask:0xf bank_mask:0xf bound_ctrl:1
	ds_read_b128 v[20:23], v80 offset:11264
	ds_read_b128 v[24:27], v80 offset:27648
	ds_read_b128 v[28:31], v80 offset:3072
	ds_read_b128 v[32:35], v80 offset:19456
	ds_read_b128 v[36:39], v80 offset:35840
	v_add_f32_e32 v6, v6, v7
	ds_write_b32 v82, v6 offset:9216
	v_add_f32_dpp v0, v0, v0 row_half_mirror row_mask:0xf bank_mask:0xf bound_ctrl:1
	v_pk_fma_f32 v[10:11], v[50:51], v[4:5], v[10:11]
	v_pk_fma_f32 v[8:9], v[48:49], v[2:3], v[8:9]
	v_add_f32_dpp v0, v0, v0 row_mirror row_mask:0xf bank_mask:0xf bound_ctrl:1
	v_pk_fma_f32 v[4:5], v[54:55], v[0:1], v[10:11] op_sel_hi:[1,0,1]
	s_waitcnt lgkmcnt(12)
	v_pk_mul_f32 v[6:7], v[62:63], v[4:5]
	v_pk_fma_f32 v[2:3], v[52:53], v[0:1], v[8:9] op_sel_hi:[1,0,1]
	v_pk_fma_f32 v[6:7], v[60:61], v[2:3], v[6:7]
	s_waitcnt lgkmcnt(8)
	v_add_f32_e32 v0, v6, v7
	v_pk_mul_f32 v[6:7], v[58:59], v[4:5]
	v_pk_fma_f32 v[6:7], v[56:57], v[2:3], v[6:7]
	v_add_f32_dpp v0, v0, v0 quad_perm:[1,0,3,2] row_mask:0xf bank_mask:0xf bound_ctrl:1
	v_pk_mul_f32 v[10:11], v[66:67], v[14:15] op_sel:[0,1] op_sel_hi:[1,1]
	v_pk_mul_f32 v[8:9], v[64:65], v[14:15] op_sel:[0,1] op_sel_hi:[1,1]
	v_add_f32_dpp v0, v0, v0 quad_perm:[2,3,0,1] row_mask:0xf bank_mask:0xf bound_ctrl:1
	ds_read_b128 v[40:43], v80 offset:11520
	ds_read_b128 v[44:47], v80 offset:27904
	ds_read_b128 v[48:51], v80 offset:3328
	ds_read_b128 v[52:55], v80 offset:19712
	ds_read_b128 v[56:59], v80 offset:36096
	v_add_f32_e32 v6, v6, v7
	ds_write_b32 v82, v6 offset:10240
	v_add_f32_dpp v0, v0, v0 row_half_mirror row_mask:0xf bank_mask:0xf bound_ctrl:1
	v_pk_fma_f32 v[10:11], v[70:71], v[4:5], v[10:11]
	v_pk_fma_f32 v[8:9], v[68:69], v[2:3], v[8:9]
	v_add_f32_dpp v0, v0, v0 row_mirror row_mask:0xf bank_mask:0xf bound_ctrl:1
	v_pk_fma_f32 v[4:5], v[74:75], v[0:1], v[10:11] op_sel_hi:[1,0,1]
	s_waitcnt lgkmcnt(11)
	v_pk_mul_f32 v[6:7], v[22:23], v[4:5]
	v_pk_fma_f32 v[2:3], v[72:73], v[0:1], v[8:9] op_sel_hi:[1,0,1]
	v_pk_fma_f32 v[6:7], v[20:21], v[2:3], v[6:7]
	s_waitcnt lgkmcnt(7)
	v_add_f32_e32 v0, v6, v7
	v_pk_mul_f32 v[6:7], v[78:79], v[4:5]
	v_pk_fma_f32 v[6:7], v[76:77], v[2:3], v[6:7]
	v_add_f32_dpp v0, v0, v0 quad_perm:[1,0,3,2] row_mask:0xf bank_mask:0xf bound_ctrl:1
	v_pk_mul_f32 v[10:11], v[26:27], v[16:17] op_sel_hi:[1,0]
	v_pk_mul_f32 v[8:9], v[24:25], v[16:17] op_sel_hi:[1,0]
	v_add_f32_dpp v0, v0, v0 quad_perm:[2,3,0,1] row_mask:0xf bank_mask:0xf bound_ctrl:1
	ds_read_b128 v[60:63], v80 offset:11776
	ds_read_b128 v[64:67], v80 offset:28160
	ds_read_b128 v[68:71], v80 offset:3584
	ds_read_b128 v[72:75], v80 offset:19968
	ds_read_b128 v[76:79], v80 offset:36352
	v_add_f32_e32 v6, v6, v7
	ds_write_b32 v82, v6 offset:11264
	v_add_f32_dpp v0, v0, v0 row_half_mirror row_mask:0xf bank_mask:0xf bound_ctrl:1
	v_pk_fma_f32 v[10:11], v[30:31], v[4:5], v[10:11]
	v_pk_fma_f32 v[8:9], v[28:29], v[2:3], v[8:9]
	v_add_f32_dpp v0, v0, v0 row_mirror row_mask:0xf bank_mask:0xf bound_ctrl:1
	v_pk_fma_f32 v[4:5], v[34:35], v[0:1], v[10:11] op_sel_hi:[1,0,1]
	s_waitcnt lgkmcnt(11)
; #define LAS __attribute__((address_space(3)))
; __device__ __forceinline__ void phase_rwc(const int wvs, const Params& p, LAS unsigned char* lds, int layer, int wg0) {
;     ...
; #pragma unroll 16
;       for (int t = 0; t < 32; ++t) {
;         const int tn = t + 2;
;         const f32x4 nw4 = *(const LAS f32x4*)(Wv + tn * 64), nkk4 = *(const LAS f32x4*)(Wv + 2048 + tn * 64), nb4 = *(const LAS f32x4*)(Wv + 4096 + tn * 64), nkd4 = *(const LAS f32x4*)(Wv + 6144 + tn * 64), nr4 = *(const LAS f32x4*)(Wv + 8192 + tn * 64);
;         const float nvv = Vv[tn * 16];
;         const f32x4 pa = S * kk4;
;         const f32x4 t1 = S * w4 + vv * kd4;
;         float sa = (pa[0] + pa[2]) + (pa[1] + pa[3]);
;         sa = row16_sum(sa);
;         S = t1 + sa * b4;
;         const f32x4 py = S * r4;
;         ypw[t * 256] = (py[0] + py[2]) + (py[1] + py[3]);
;         w4 = xw4; kk4 = xkk4; b4 = xb4; kd4 = xkd4; r4 = xr4; vv = xvv;
;         xw4 = nw4; xkk4 = nkk4; xb4 = nb4; xkd4 = nkd4; xr4 = nr4; xvv = nvv;
;       }
	v_pk_mul_f32 v[6:7], v[42:43], v[4:5]
	v_pk_fma_f32 v[2:3], v[32:33], v[0:1], v[8:9] op_sel_hi:[1,0,1]
	v_pk_fma_f32 v[6:7], v[40:41], v[2:3], v[6:7]
	s_waitcnt lgkmcnt(7)
	v_add_f32_e32 v0, v6, v7
	v_pk_mul_f32 v[6:7], v[38:39], v[4:5]
	v_pk_fma_f32 v[6:7], v[36:37], v[2:3], v[6:7]
	v_add_f32_dpp v0, v0, v0 quad_perm:[1,0,3,2] row_mask:0xf bank_mask:0xf bound_ctrl:1
	v_pk_mul_f32 v[10:11], v[46:47], v[16:17] op_sel:[0,1] op_sel_hi:[1,1]
	v_pk_mul_f32 v[8:9], v[44:45], v[16:17] op_sel:[0,1] op_sel_hi:[1,1]
	v_add_f32_dpp v0, v0, v0 quad_perm:[2,3,0,1] row_mask:0xf bank_mask:0xf bound_ctrl:1
	ds_read_b128 v[20:23], v80 offset:12032
	ds_read_b128 v[24:27], v80 offset:28416
	ds_read_b128 v[28:31], v80 offset:3840
	ds_read_b128 v[32:35], v80 offset:20224
	ds_read_b128 v[36:39], v80 offset:36608
	ds_read_b128 v[12:15], v81 offset:64
	v_add_f32_e32 v6, v6, v7
	ds_write_b32 v82, v6 offset:12288
	v_add_f32_dpp v0, v0, v0 row_half_mirror row_mask:0xf bank_mask:0xf bound_ctrl:1
	v_pk_fma_f32 v[10:11], v[50:51], v[4:5], v[10:11]
	v_pk_fma_f32 v[8:9], v[48:49], v[2:3], v[8:9]
	v_add_f32_dpp v0, v0, v0 row_mirror row_mask:0xf bank_mask:0xf bound_ctrl:1
	v_pk_fma_f32 v[4:5], v[54:55], v[0:1], v[10:11] op_sel_hi:[1,0,1]
	s_waitcnt lgkmcnt(12)
	v_pk_mul_f32 v[6:7], v[62:63], v[4:5]
	v_pk_fma_f32 v[2:3], v[52:53], v[0:1], v[8:9] op_sel_hi:[1,0,1]
	v_pk_fma_f32 v[6:7], v[60:61], v[2:3], v[6:7]
	s_waitcnt lgkmcnt(8)
	v_add_f32_e32 v0, v6, v7
	v_pk_mul_f32 v[6:7], v[58:59], v[4:5]
	v_pk_fma_f32 v[6:7], v[56:57], v[2:3], v[6:7]
	v_add_f32_dpp v0, v0, v0 quad_perm:[1,0,3,2] row_mask:0xf bank_mask:0xf bound_ctrl:1
	v_pk_mul_f32 v[10:11], v[66:67], v[18:19] op_sel_hi:[1,0]
	v_pk_mul_f32 v[8:9], v[64:65], v[18:19] op_sel_hi:[1,0]
	v_add_f32_dpp v0, v0, v0 quad_perm:[2,3,0,1] row_mask:0xf bank_mask:0xf bound_ctrl:1
	ds_read_b128 v[40:43], v80 offset:12288
	ds_read_b128 v[44:47], v80 offset:28672
	ds_read_b128 v[48:51], v80 offset:4096
	ds_read_b128 v[52:55], v80 offset:20480
	ds_read_b128 v[56:59], v80 offset:36864
	v_add_f32_e32 v6, v6, v7
	ds_write_b32 v82, v6 offset:13312
	v_add_f32_dpp v0, v0, v0 row_half_mirror row_mask:0xf bank_mask:0xf bound_ctrl:1
	v_pk_fma_f32 v[10:11], v[70:71], v[4:5], v[10:11]
	v_pk_fma_f32 v[8:9], v[68:69], v[2:3], v[8:9]
	v_add_f32_dpp v0, v0, v0 row_mirror row_mask:0xf bank_mask:0xf bound_ctrl:1
	v_pk_fma_f32 v[4:5], v[74:75], v[0:1], v[10:11] op_sel_hi:[1,0,1]
	s_waitcnt lgkmcnt(12)
	v_pk_mul_f32 v[6:7], v[22:23], v[4:5]
	v_pk_fma_f32 v[2:3], v[72:73], v[0:1], v[8:9] op_sel_hi:[1,0,1]
	v_pk_fma_f32 v[6:7], v[20:21], v[2:3], v[6:7]
	s_waitcnt lgkmcnt(8)
	v_add_f32_e32 v0, v6, v7
	v_pk_mul_f32 v[6:7], v[78:79], v[4:5]
	v_pk_fma_f32 v[6:7], v[76:77], v[2:3], v[6:7]
	v_add_f32_dpp v0, v0, v0 quad_perm:[1,0,3,2] row_mask:0xf bank_mask:0xf bound_ctrl:1
	v_pk_mul_f32 v[10:11], v[26:27], v[18:19] op_sel:[0,1] op_sel_hi:[1,1]
	v_pk_mul_f32 v[8:9], v[24:25], v[18:19] op_sel:[0,1] op_sel_hi:[1,1]
	v_add_f32_dpp v0, v0, v0 quad_perm:[2,3,0,1] row_mask:0xf bank_mask:0xf bound_ctrl:1
	ds_read_b128 v[60:63], v80 offset:12544
	ds_read_b128 v[64:67], v80 offset:28928
	ds_read_b128 v[68:71], v80 offset:4352
	ds_read_b128 v[72:75], v80 offset:20736
	ds_read_b128 v[76:79], v80 offset:37120
	v_add_f32_e32 v6, v6, v7
	ds_write_b32 v82, v6 offset:14336
	v_add_f32_dpp v0, v0, v0 row_half_mirror row_mask:0xf bank_mask:0xf bound_ctrl:1
	v_pk_fma_f32 v[10:11], v[30:31], v[4:5], v[10:11]
	v_pk_fma_f32 v[8:9], v[28:29], v[2:3], v[8:9]
	v_add_f32_dpp v0, v0, v0 row_mirror row_mask:0xf bank_mask:0xf bound_ctrl:1
	v_pk_fma_f32 v[4:5], v[34:35], v[0:1], v[10:11] op_sel_hi:[1,0,1]
	s_waitcnt lgkmcnt(11)
	v_pk_mul_f32 v[6:7], v[42:43], v[4:5]
	v_pk_fma_f32 v[2:3], v[32:33], v[0:1], v[8:9] op_sel_hi:[1,0,1]
	v_pk_fma_f32 v[6:7], v[40:41], v[2:3], v[6:7]
	s_waitcnt lgkmcnt(7)
	v_add_f32_e32 v0, v6, v7
	v_pk_mul_f32 v[6:7], v[38:39], v[4:5]
	v_pk_fma_f32 v[6:7], v[36:37], v[2:3], v[6:7]
	v_add_f32_dpp v0, v0, v0 quad_perm:[1,0,3,2] row_mask:0xf bank_mask:0xf bound_ctrl:1
	v_pk_mul_f32 v[10:11], v[46:47], v[12:13] op_sel_hi:[1,0]
	v_pk_mul_f32 v[8:9], v[44:45], v[12:13] op_sel_hi:[1,0]
	v_add_f32_dpp v0, v0, v0 quad_perm:[2,3,0,1] row_mask:0xf bank_mask:0xf bound_ctrl:1
	ds_read_b128 v[20:23], v80 offset:12800
	ds_read_b128 v[24:27], v80 offset:29184
	ds_read_b128 v[28:31], v80 offset:4608
	ds_read_b128 v[32:35], v80 offset:20992
	ds_read_b128 v[36:39], v80 offset:37376
	v_add_f32_e32 v6, v6, v7
	ds_write_b32 v82, v6 offset:15360
	v_add_f32_dpp v0, v0, v0 row_half_mirror row_mask:0xf bank_mask:0xf bound_ctrl:1
	v_pk_fma_f32 v[10:11], v[50:51], v[4:5], v[10:11]
	v_pk_fma_f32 v[8:9], v[48:49], v[2:3], v[8:9]
	v_add_f32_dpp v0, v0, v0 row_mirror row_mask:0xf bank_mask:0xf bound_ctrl:1
	v_pk_fma_f32 v[4:5], v[54:55], v[0:1], v[10:11] op_sel_hi:[1,0,1]
	s_waitcnt lgkmcnt(11)
	v_pk_mul_f32 v[6:7], v[62:63], v[4:5]
	v_pk_fma_f32 v[2:3], v[52:53], v[0:1], v[8:9] op_sel_hi:[1,0,1]
	v_pk_fma_f32 v[6:7], v[60:61], v[2:3], v[6:7]
	s_waitcnt lgkmcnt(7)
	v_add_f32_e32 v0, v6, v7
	v_pk_mul_f32 v[6:7], v[58:59], v[4:5]
	v_pk_fma_f32 v[6:7], v[56:57], v[2:3], v[6:7]
	v_add_f32_dpp v0, v0, v0 quad_perm:[1,0,3,2] row_mask:0xf bank_mask:0xf bound_ctrl:1
	v_pk_mul_f32 v[10:11], v[66:67], v[12:13] op_sel:[0,1] op_sel_hi:[1,1]
	v_pk_mul_f32 v[8:9], v[64:65], v[12:13] op_sel:[0,1] op_sel_hi:[1,1]
	v_add_f32_dpp v0, v0, v0 quad_perm:[2,3,0,1] row_mask:0xf bank_mask:0xf bound_ctrl:1
	ds_read_b128 v[40:43], v80 offset:13056
	ds_read_b128 v[44:47], v80 offset:29440
	ds_read_b128 v[48:51], v80 offset:4864
	ds_read_b128 v[52:55], v80 offset:21248
	ds_read_b128 v[56:59], v80 offset:37632
	ds_read_b128 v[16:19], v81 offset:80
	v_add_f32_e32 v6, v6, v7
	ds_write_b32 v82, v6 offset:16384
	v_add_f32_dpp v0, v0, v0 row_half_mirror row_mask:0xf bank_mask:0xf bound_ctrl:1
	v_pk_fma_f32 v[10:11], v[70:71], v[4:5], v[10:11]
	v_pk_fma_f32 v[8:9], v[68:69], v[2:3], v[8:9]
	v_add_f32_dpp v0, v0, v0 row_mirror row_mask:0xf bank_mask:0xf bound_ctrl:1
	v_pk_fma_f32 v[4:5], v[74:75], v[0:1], v[10:11] op_sel_hi:[1,0,1]
	s_waitcnt lgkmcnt(12)
; #define LAS __attribute__((address_space(3)))
; __device__ __forceinline__ void phase_rwc(const int wvs, const Params& p, LAS unsigned char* lds, int layer, int wg0) {
;     ...
; #pragma unroll 16
;       for (int t = 0; t < 32; ++t) {
;         const int tn = t + 2;
;         const f32x4 nw4 = *(const LAS f32x4*)(Wv + tn * 64), nkk4 = *(const LAS f32x4*)(Wv + 2048 + tn * 64), nb4 = *(const LAS f32x4*)(Wv + 4096 + tn * 64), nkd4 = *(const LAS f32x4*)(Wv + 6144 + tn * 64), nr4 = *(const LAS f32x4*)(Wv + 8192 + tn * 64);
;         const float nvv = Vv[tn * 16];
;         const f32x4 pa = S * kk4;
;         const f32x4 t1 = S * w4 + vv * kd4;
;         float sa = (pa[0] + pa[2]) + (pa[1] + pa[3]);
;         sa = row16_sum(sa);
;         S = t1 + sa * b4;
;         const f32x4 py = S * r4;
;         ypw[t * 256] = (py[0] + py[2]) + (py[1] + py[3]);
;         w4 = xw4; kk4 = xkk4; b4 = xb4; kd4 = xkd4; r4 = xr4; vv = xvv;
;         xw4 = nw4; xkk4 = nkk4; xb4 = nb4; xkd4 = nkd4; xr4 = nr4; xvv = nvv;
;       }
	v_pk_mul_f32 v[6:7], v[22:23], v[4:5]
	v_pk_fma_f32 v[2:3], v[72:73], v[0:1], v[8:9] op_sel_hi:[1,0,1]
	v_pk_fma_f32 v[6:7], v[20:21], v[2:3], v[6:7]
	s_waitcnt lgkmcnt(8)
	v_add_f32_e32 v0, v6, v7
	v_pk_mul_f32 v[6:7], v[78:79], v[4:5]
	v_pk_fma_f32 v[6:7], v[76:77], v[2:3], v[6:7]
	v_add_f32_dpp v0, v0, v0 quad_perm:[1,0,3,2] row_mask:0xf bank_mask:0xf bound_ctrl:1
	v_pk_mul_f32 v[10:11], v[26:27], v[14:15] op_sel_hi:[1,0]
	v_pk_mul_f32 v[8:9], v[24:25], v[14:15] op_sel_hi:[1,0]
	v_add_f32_dpp v0, v0, v0 quad_perm:[2,3,0,1] row_mask:0xf bank_mask:0xf bound_ctrl:1
	ds_read_b128 v[60:63], v80 offset:13312
	ds_read_b128 v[64:67], v80 offset:29696
	ds_read_b128 v[68:71], v80 offset:5120
	ds_read_b128 v[72:75], v80 offset:21504
	ds_read_b128 v[76:79], v80 offset:37888
	v_add_f32_e32 v6, v6, v7
	ds_write_b32 v82, v6 offset:17408
	v_add_f32_dpp v0, v0, v0 row_half_mirror row_mask:0xf bank_mask:0xf bound_ctrl:1
	v_pk_fma_f32 v[10:11], v[30:31], v[4:5], v[10:11]
	v_pk_fma_f32 v[8:9], v[28:29], v[2:3], v[8:9]
	v_add_f32_dpp v0, v0, v0 row_mirror row_mask:0xf bank_mask:0xf bound_ctrl:1
	v_pk_fma_f32 v[4:5], v[34:35], v[0:1], v[10:11] op_sel_hi:[1,0,1]
	s_waitcnt lgkmcnt(12)
	v_pk_mul_f32 v[6:7], v[42:43], v[4:5]
	v_pk_fma_f32 v[2:3], v[32:33], v[0:1], v[8:9] op_sel_hi:[1,0,1]
	v_pk_fma_f32 v[6:7], v[40:41], v[2:3], v[6:7]
	s_waitcnt lgkmcnt(8)
	v_add_f32_e32 v0, v6, v7
	v_pk_mul_f32 v[6:7], v[38:39], v[4:5]
	v_pk_fma_f32 v[6:7], v[36:37], v[2:3], v[6:7]
	v_add_f32_dpp v0, v0, v0 quad_perm:[1,0,3,2] row_mask:0xf bank_mask:0xf bound_ctrl:1
	v_pk_mul_f32 v[10:11], v[46:47], v[14:15] op_sel:[0,1] op_sel_hi:[1,1]
	v_pk_mul_f32 v[8:9], v[44:45], v[14:15] op_sel:[0,1] op_sel_hi:[1,1]
	v_add_f32_dpp v0, v0, v0 quad_perm:[2,3,0,1] row_mask:0xf bank_mask:0xf bound_ctrl:1
	ds_read_b128 v[20:23], v80 offset:13568
	ds_read_b128 v[24:27], v80 offset:29952
	ds_read_b128 v[28:31], v80 offset:5376
	ds_read_b128 v[32:35], v80 offset:21760
	ds_read_b128 v[36:39], v80 offset:38144
	v_add_f32_e32 v6, v6, v7
	ds_write_b32 v82, v6 offset:18432
	v_add_f32_dpp v0, v0, v0 row_half_mirror row_mask:0xf bank_mask:0xf bound_ctrl:1
	v_pk_fma_f32 v[10:11], v[50:51], v[4:5], v[10:11]
	v_pk_fma_f32 v[8:9], v[48:49], v[2:3], v[8:9]
	v_add_f32_dpp v0, v0, v0 row_mirror row_mask:0xf bank_mask:0xf bound_ctrl:1
	v_pk_fma_f32 v[4:5], v[54:55], v[0:1], v[10:11] op_sel_hi:[1,0,1]
	s_waitcnt lgkmcnt(11)
	v_pk_mul_f32 v[6:7], v[62:63], v[4:5]
	v_pk_fma_f32 v[2:3], v[52:53], v[0:1], v[8:9] op_sel_hi:[1,0,1]
	v_pk_fma_f32 v[6:7], v[60:61], v[2:3], v[6:7]
	s_waitcnt lgkmcnt(7)
	v_add_f32_e32 v0, v6, v7
	v_pk_mul_f32 v[6:7], v[58:59], v[4:5]
	v_pk_fma_f32 v[6:7], v[56:57], v[2:3], v[6:7]
	v_add_f32_dpp v0, v0, v0 quad_perm:[1,0,3,2] row_mask:0xf bank_mask:0xf bound_ctrl:1
	v_pk_mul_f32 v[10:11], v[66:67], v[16:17] op_sel_hi:[1,0]
	v_pk_mul_f32 v[8:9], v[64:65], v[16:17] op_sel_hi:[1,0]
	v_add_f32_dpp v0, v0, v0 quad_perm:[2,3,0,1] row_mask:0xf bank_mask:0xf bound_ctrl:1
	ds_read_b128 v[40:43], v80 offset:13824
	ds_read_b128 v[44:47], v80 offset:30208
	ds_read_b128 v[48:51], v80 offset:5632
	ds_read_b128 v[52:55], v80 offset:22016
	ds_read_b128 v[56:59], v80 offset:38400
	v_add_f32_e32 v6, v6, v7
	ds_write_b32 v82, v6 offset:19456
	v_add_f32_dpp v0, v0, v0 row_half_mirror row_mask:0xf bank_mask:0xf bound_ctrl:1
	v_pk_fma_f32 v[10:11], v[70:71], v[4:5], v[10:11]
	v_pk_fma_f32 v[8:9], v[68:69], v[2:3], v[8:9]
	v_add_f32_dpp v0, v0, v0 row_mirror row_mask:0xf bank_mask:0xf bound_ctrl:1
	v_pk_fma_f32 v[4:5], v[74:75], v[0:1], v[10:11] op_sel_hi:[1,0,1]
	s_waitcnt lgkmcnt(11)
	v_pk_mul_f32 v[6:7], v[22:23], v[4:5]
	v_pk_fma_f32 v[2:3], v[72:73], v[0:1], v[8:9] op_sel_hi:[1,0,1]
	v_pk_fma_f32 v[6:7], v[20:21], v[2:3], v[6:7]
	s_waitcnt lgkmcnt(7)
	v_add_f32_e32 v0, v6, v7
	v_pk_mul_f32 v[6:7], v[78:79], v[4:5]
	v_pk_fma_f32 v[6:7], v[76:77], v[2:3], v[6:7]
	v_add_f32_dpp v0, v0, v0 quad_perm:[1,0,3,2] row_mask:0xf bank_mask:0xf bound_ctrl:1
	v_pk_mul_f32 v[10:11], v[26:27], v[16:17] op_sel:[0,1] op_sel_hi:[1,1]
	v_pk_mul_f32 v[8:9], v[24:25], v[16:17] op_sel:[0,1] op_sel_hi:[1,1]
	v_add_f32_dpp v0, v0, v0 quad_perm:[2,3,0,1] row_mask:0xf bank_mask:0xf bound_ctrl:1
	ds_read_b128 v[60:63], v80 offset:14080
	ds_read_b128 v[64:67], v80 offset:30464
	ds_read_b128 v[68:71], v80 offset:5888
	ds_read_b128 v[72:75], v80 offset:22272
	ds_read_b128 v[76:79], v80 offset:38656
	ds_read_b128 v[12:15], v81 offset:96
	v_add_f32_e32 v6, v6, v7
	ds_write_b32 v82, v6 offset:20480
	v_add_f32_dpp v0, v0, v0 row_half_mirror row_mask:0xf bank_mask:0xf bound_ctrl:1
	v_pk_fma_f32 v[10:11], v[30:31], v[4:5], v[10:11]
	v_pk_fma_f32 v[8:9], v[28:29], v[2:3], v[8:9]
	v_add_f32_dpp v0, v0, v0 row_mirror row_mask:0xf bank_mask:0xf bound_ctrl:1
	v_pk_fma_f32 v[4:5], v[34:35], v[0:1], v[10:11] op_sel_hi:[1,0,1]
	s_waitcnt lgkmcnt(12)
	v_pk_mul_f32 v[6:7], v[42:43], v[4:5]
	v_pk_fma_f32 v[2:3], v[32:33], v[0:1], v[8:9] op_sel_hi:[1,0,1]
	v_pk_fma_f32 v[6:7], v[40:41], v[2:3], v[6:7]
	s_waitcnt lgkmcnt(8)
	v_add_f32_e32 v0, v6, v7
	v_pk_mul_f32 v[6:7], v[38:39], v[4:5]
	v_pk_fma_f32 v[6:7], v[36:37], v[2:3], v[6:7]
	v_add_f32_dpp v0, v0, v0 quad_perm:[1,0,3,2] row_mask:0xf bank_mask:0xf bound_ctrl:1
	v_pk_mul_f32 v[10:11], v[46:47], v[18:19] op_sel_hi:[1,0]
	v_pk_mul_f32 v[8:9], v[44:45], v[18:19] op_sel_hi:[1,0]
	v_add_f32_dpp v0, v0, v0 quad_perm:[2,3,0,1] row_mask:0xf bank_mask:0xf bound_ctrl:1
	ds_read_b128 v[20:23], v80 offset:14336
	ds_read_b128 v[24:27], v80 offset:30720
	ds_read_b128 v[28:31], v80 offset:6144
	ds_read_b128 v[32:35], v80 offset:22528
	ds_read_b128 v[36:39], v80 offset:38912
	v_add_f32_e32 v6, v6, v7
	ds_write_b32 v82, v6 offset:21504
	v_add_f32_dpp v0, v0, v0 row_half_mirror row_mask:0xf bank_mask:0xf bound_ctrl:1
	v_pk_fma_f32 v[10:11], v[50:51], v[4:5], v[10:11]
	v_pk_fma_f32 v[8:9], v[48:49], v[2:3], v[8:9]
	v_add_f32_dpp v0, v0, v0 row_mirror row_mask:0xf bank_mask:0xf bound_ctrl:1
	v_pk_fma_f32 v[4:5], v[54:55], v[0:1], v[10:11] op_sel_hi:[1,0,1]
	s_waitcnt lgkmcnt(12)
; #define LAS __attribute__((address_space(3)))
; __device__ __forceinline__ void phase_rwc(const int wvs, const Params& p, LAS unsigned char* lds, int layer, int wg0) {
;     ...
; #pragma unroll 16
;       for (int t = 0; t < 32; ++t) {
;         const int tn = t + 2;
;         const f32x4 nw4 = *(const LAS f32x4*)(Wv + tn * 64), nkk4 = *(const LAS f32x4*)(Wv + 2048 + tn * 64), nb4 = *(const LAS f32x4*)(Wv + 4096 + tn * 64), nkd4 = *(const LAS f32x4*)(Wv + 6144 + tn * 64), nr4 = *(const LAS f32x4*)(Wv + 8192 + tn * 64);
;         const float nvv = Vv[tn * 16];
;         const f32x4 pa = S * kk4;
;         const f32x4 t1 = S * w4 + vv * kd4;
;         float sa = (pa[0] + pa[2]) + (pa[1] + pa[3]);
;         sa = row16_sum(sa);
;         S = t1 + sa * b4;
;         const f32x4 py = S * r4;
;         ypw[t * 256] = (py[0] + py[2]) + (py[1] + py[3]);
;         w4 = xw4; kk4 = xkk4; b4 = xb4; kd4 = xkd4; r4 = xr4; vv = xvv;
;         xw4 = nw4; xkk4 = nkk4; xb4 = nb4; xkd4 = nkd4; xr4 = nr4; xvv = nvv;
;       }
	v_pk_mul_f32 v[6:7], v[62:63], v[4:5]
	v_pk_fma_f32 v[2:3], v[52:53], v[0:1], v[8:9] op_sel_hi:[1,0,1]
	v_pk_fma_f32 v[6:7], v[60:61], v[2:3], v[6:7]
	s_waitcnt lgkmcnt(8)
	v_add_f32_e32 v0, v6, v7
	v_pk_mul_f32 v[6:7], v[58:59], v[4:5]
	v_pk_fma_f32 v[6:7], v[56:57], v[2:3], v[6:7]
	v_add_f32_dpp v0, v0, v0 quad_perm:[1,0,3,2] row_mask:0xf bank_mask:0xf bound_ctrl:1
	v_pk_mul_f32 v[10:11], v[66:67], v[18:19] op_sel:[0,1] op_sel_hi:[1,1]
	v_pk_mul_f32 v[8:9], v[64:65], v[18:19] op_sel:[0,1] op_sel_hi:[1,1]
	v_add_f32_dpp v0, v0, v0 quad_perm:[2,3,0,1] row_mask:0xf bank_mask:0xf bound_ctrl:1
	ds_read_b128 v[40:43], v80 offset:14592
	ds_read_b128 v[44:47], v80 offset:30976
	ds_read_b128 v[48:51], v80 offset:6400
	ds_read_b128 v[52:55], v80 offset:22784
	ds_read_b128 v[56:59], v80 offset:39168
	v_add_f32_e32 v6, v6, v7
	ds_write_b32 v82, v6 offset:22528
	v_add_f32_dpp v0, v0, v0 row_half_mirror row_mask:0xf bank_mask:0xf bound_ctrl:1
	v_pk_fma_f32 v[10:11], v[70:71], v[4:5], v[10:11]
	v_pk_fma_f32 v[8:9], v[68:69], v[2:3], v[8:9]
	v_add_f32_dpp v0, v0, v0 row_mirror row_mask:0xf bank_mask:0xf bound_ctrl:1
	v_pk_fma_f32 v[4:5], v[74:75], v[0:1], v[10:11] op_sel_hi:[1,0,1]
	s_waitcnt lgkmcnt(11)
	v_pk_mul_f32 v[6:7], v[22:23], v[4:5]
	v_pk_fma_f32 v[2:3], v[72:73], v[0:1], v[8:9] op_sel_hi:[1,0,1]
	v_pk_fma_f32 v[6:7], v[20:21], v[2:3], v[6:7]
	s_waitcnt lgkmcnt(7)
	v_add_f32_e32 v0, v6, v7
	v_pk_mul_f32 v[6:7], v[78:79], v[4:5]
	v_pk_fma_f32 v[6:7], v[76:77], v[2:3], v[6:7]
	v_add_f32_dpp v0, v0, v0 quad_perm:[1,0,3,2] row_mask:0xf bank_mask:0xf bound_ctrl:1
	v_pk_mul_f32 v[10:11], v[26:27], v[12:13] op_sel_hi:[1,0]
	v_pk_mul_f32 v[8:9], v[24:25], v[12:13] op_sel_hi:[1,0]
	v_add_f32_dpp v0, v0, v0 quad_perm:[2,3,0,1] row_mask:0xf bank_mask:0xf bound_ctrl:1
	ds_read_b128 v[60:63], v80 offset:14848
	ds_read_b128 v[64:67], v80 offset:31232
	ds_read_b128 v[68:71], v80 offset:6656
	ds_read_b128 v[72:75], v80 offset:23040
	ds_read_b128 v[76:79], v80 offset:39424
	v_add_f32_e32 v6, v6, v7
	ds_write_b32 v82, v6 offset:23552
	v_add_f32_dpp v0, v0, v0 row_half_mirror row_mask:0xf bank_mask:0xf bound_ctrl:1
	v_pk_fma_f32 v[10:11], v[30:31], v[4:5], v[10:11]
	v_pk_fma_f32 v[8:9], v[28:29], v[2:3], v[8:9]
	v_add_f32_dpp v0, v0, v0 row_mirror row_mask:0xf bank_mask:0xf bound_ctrl:1
	v_pk_fma_f32 v[4:5], v[34:35], v[0:1], v[10:11] op_sel_hi:[1,0,1]
	s_waitcnt lgkmcnt(11)
	v_pk_mul_f32 v[6:7], v[42:43], v[4:5]
	v_pk_fma_f32 v[2:3], v[32:33], v[0:1], v[8:9] op_sel_hi:[1,0,1]
	v_pk_fma_f32 v[6:7], v[40:41], v[2:3], v[6:7]
	s_waitcnt lgkmcnt(7)
	v_add_f32_e32 v0, v6, v7
	v_pk_mul_f32 v[6:7], v[38:39], v[4:5]
	v_pk_fma_f32 v[6:7], v[36:37], v[2:3], v[6:7]
	v_add_f32_dpp v0, v0, v0 quad_perm:[1,0,3,2] row_mask:0xf bank_mask:0xf bound_ctrl:1
	v_pk_mul_f32 v[10:11], v[46:47], v[12:13] op_sel:[0,1] op_sel_hi:[1,1]
	v_pk_mul_f32 v[8:9], v[44:45], v[12:13] op_sel:[0,1] op_sel_hi:[1,1]
	v_add_f32_dpp v0, v0, v0 quad_perm:[2,3,0,1] row_mask:0xf bank_mask:0xf bound_ctrl:1
	ds_read_b128 v[20:23], v80 offset:15104
	ds_read_b128 v[24:27], v80 offset:31488
	ds_read_b128 v[28:31], v80 offset:6912
	ds_read_b128 v[32:35], v80 offset:23296
	ds_read_b128 v[36:39], v80 offset:39680
	ds_read_b128 v[16:19], v81 offset:112
	v_add_f32_e32 v6, v6, v7
	ds_write_b32 v82, v6 offset:24576
	v_add_f32_dpp v0, v0, v0 row_half_mirror row_mask:0xf bank_mask:0xf bound_ctrl:1
	v_pk_fma_f32 v[10:11], v[50:51], v[4:5], v[10:11]
	v_pk_fma_f32 v[8:9], v[48:49], v[2:3], v[8:9]
	v_add_f32_dpp v0, v0, v0 row_mirror row_mask:0xf bank_mask:0xf bound_ctrl:1
	v_pk_fma_f32 v[4:5], v[54:55], v[0:1], v[10:11] op_sel_hi:[1,0,1]
	s_waitcnt lgkmcnt(12)
	v_pk_mul_f32 v[6:7], v[62:63], v[4:5]
	v_pk_fma_f32 v[2:3], v[52:53], v[0:1], v[8:9] op_sel_hi:[1,0,1]
	v_pk_fma_f32 v[6:7], v[60:61], v[2:3], v[6:7]
	s_waitcnt lgkmcnt(8)
	v_add_f32_e32 v0, v6, v7
	v_pk_mul_f32 v[6:7], v[58:59], v[4:5]
	v_pk_fma_f32 v[6:7], v[56:57], v[2:3], v[6:7]
	v_add_f32_dpp v0, v0, v0 quad_perm:[1,0,3,2] row_mask:0xf bank_mask:0xf bound_ctrl:1
	v_pk_mul_f32 v[10:11], v[66:67], v[14:15] op_sel_hi:[1,0]
	v_pk_mul_f32 v[8:9], v[64:65], v[14:15] op_sel_hi:[1,0]
	v_add_f32_dpp v0, v0, v0 quad_perm:[2,3,0,1] row_mask:0xf bank_mask:0xf bound_ctrl:1
	ds_read_b128 v[40:43], v80 offset:15360
	ds_read_b128 v[44:47], v80 offset:31744
	ds_read_b128 v[48:51], v80 offset:7168
	ds_read_b128 v[52:55], v80 offset:23552
	ds_read_b128 v[56:59], v80 offset:39936
	v_add_f32_e32 v6, v6, v7
	ds_write_b32 v82, v6 offset:25600
	v_add_f32_dpp v0, v0, v0 row_half_mirror row_mask:0xf bank_mask:0xf bound_ctrl:1
	v_pk_fma_f32 v[10:11], v[70:71], v[4:5], v[10:11]
	v_pk_fma_f32 v[8:9], v[68:69], v[2:3], v[8:9]
	v_add_f32_dpp v0, v0, v0 row_mirror row_mask:0xf bank_mask:0xf bound_ctrl:1
	v_pk_fma_f32 v[4:5], v[74:75], v[0:1], v[10:11] op_sel_hi:[1,0,1]
	s_waitcnt lgkmcnt(12)
	v_pk_mul_f32 v[6:7], v[22:23], v[4:5]
	v_pk_fma_f32 v[2:3], v[72:73], v[0:1], v[8:9] op_sel_hi:[1,0,1]
	v_pk_fma_f32 v[6:7], v[20:21], v[2:3], v[6:7]
	s_waitcnt lgkmcnt(8)
	v_add_f32_e32 v0, v6, v7
	v_pk_mul_f32 v[6:7], v[78:79], v[4:5]
	v_pk_fma_f32 v[6:7], v[76:77], v[2:3], v[6:7]
	v_add_f32_dpp v0, v0, v0 quad_perm:[1,0,3,2] row_mask:0xf bank_mask:0xf bound_ctrl:1
	v_pk_mul_f32 v[10:11], v[26:27], v[14:15] op_sel:[0,1] op_sel_hi:[1,1]
	v_pk_mul_f32 v[8:9], v[24:25], v[14:15] op_sel:[0,1] op_sel_hi:[1,1]
	v_add_f32_dpp v0, v0, v0 quad_perm:[2,3,0,1] row_mask:0xf bank_mask:0xf bound_ctrl:1
	ds_read_b128 v[60:63], v80 offset:15616
	ds_read_b128 v[64:67], v80 offset:32000
	ds_read_b128 v[68:71], v80 offset:7424
	ds_read_b128 v[72:75], v80 offset:23808
	ds_read_b128 v[76:79], v80 offset:40192
	v_add_f32_e32 v6, v6, v7
	ds_write_b32 v82, v6 offset:26624
	v_add_f32_dpp v0, v0, v0 row_half_mirror row_mask:0xf bank_mask:0xf bound_ctrl:1
	v_pk_fma_f32 v[10:11], v[30:31], v[4:5], v[10:11]
	v_pk_fma_f32 v[8:9], v[28:29], v[2:3], v[8:9]
	v_add_f32_dpp v0, v0, v0 row_mirror row_mask:0xf bank_mask:0xf bound_ctrl:1
	v_pk_fma_f32 v[4:5], v[34:35], v[0:1], v[10:11] op_sel_hi:[1,0,1]
	s_waitcnt lgkmcnt(11)
; #define LAS __attribute__((address_space(3)))
; __device__ __forceinline__ void phase_rwc(const int wvs, const Params& p, LAS unsigned char* lds, int layer, int wg0) {
;     ...
; #pragma unroll 16
;       for (int t = 0; t < 32; ++t) {
;         const int tn = t + 2;
;         const f32x4 nw4 = *(const LAS f32x4*)(Wv + tn * 64), nkk4 = *(const LAS f32x4*)(Wv + 2048 + tn * 64), nb4 = *(const LAS f32x4*)(Wv + 4096 + tn * 64), nkd4 = *(const LAS f32x4*)(Wv + 6144 + tn * 64), nr4 = *(const LAS f32x4*)(Wv + 8192 + tn * 64);
;         const float nvv = Vv[tn * 16];
;         const f32x4 pa = S * kk4;
;         const f32x4 t1 = S * w4 + vv * kd4;
;         float sa = (pa[0] + pa[2]) + (pa[1] + pa[3]);
;         sa = row16_sum(sa);
;         S = t1 + sa * b4;
;         const f32x4 py = S * r4;
;         ypw[t * 256] = (py[0] + py[2]) + (py[1] + py[3]);
;         w4 = xw4; kk4 = xkk4; b4 = xb4; kd4 = xkd4; r4 = xr4; vv = xvv;
;         xw4 = nw4; xkk4 = nkk4; xb4 = nb4; xkd4 = nkd4; xr4 = nr4; xvv = nvv;
;       }
;       __syncthreads();
	v_pk_mul_f32 v[6:7], v[42:43], v[4:5]
	v_pk_fma_f32 v[2:3], v[32:33], v[0:1], v[8:9] op_sel_hi:[1,0,1]
	v_pk_fma_f32 v[6:7], v[40:41], v[2:3], v[6:7]
	s_waitcnt lgkmcnt(7)
	v_add_f32_e32 v0, v6, v7
	v_pk_mul_f32 v[6:7], v[38:39], v[4:5]
	v_pk_fma_f32 v[6:7], v[36:37], v[2:3], v[6:7]
	v_add_f32_dpp v0, v0, v0 quad_perm:[1,0,3,2] row_mask:0xf bank_mask:0xf bound_ctrl:1
	v_pk_mul_f32 v[10:11], v[46:47], v[16:17] op_sel_hi:[1,0]
	v_pk_mul_f32 v[8:9], v[44:45], v[16:17] op_sel_hi:[1,0]
	v_add_f32_dpp v0, v0, v0 quad_perm:[2,3,0,1] row_mask:0xf bank_mask:0xf bound_ctrl:1
	ds_read_b128 v[20:23], v80 offset:15872
	ds_read_b128 v[24:27], v80 offset:32256
	ds_read_b128 v[28:31], v80 offset:7680
	ds_read_b128 v[32:35], v80 offset:24064
	ds_read_b128 v[36:39], v80 offset:40448
	v_add_f32_e32 v6, v6, v7
	ds_write_b32 v82, v6 offset:27648
	v_add_f32_dpp v0, v0, v0 row_half_mirror row_mask:0xf bank_mask:0xf bound_ctrl:1
	v_pk_fma_f32 v[10:11], v[50:51], v[4:5], v[10:11]
	v_pk_fma_f32 v[8:9], v[48:49], v[2:3], v[8:9]
	v_add_f32_dpp v0, v0, v0 row_mirror row_mask:0xf bank_mask:0xf bound_ctrl:1
	v_pk_fma_f32 v[4:5], v[54:55], v[0:1], v[10:11] op_sel_hi:[1,0,1]
	s_waitcnt lgkmcnt(11)
	v_pk_mul_f32 v[6:7], v[62:63], v[4:5]
	v_pk_fma_f32 v[2:3], v[52:53], v[0:1], v[8:9] op_sel_hi:[1,0,1]
	v_pk_fma_f32 v[6:7], v[60:61], v[2:3], v[6:7]
	s_waitcnt lgkmcnt(7)
	v_add_f32_e32 v0, v6, v7
	v_pk_mul_f32 v[6:7], v[58:59], v[4:5]
	v_pk_fma_f32 v[6:7], v[56:57], v[2:3], v[6:7]
	v_add_f32_dpp v0, v0, v0 quad_perm:[1,0,3,2] row_mask:0xf bank_mask:0xf bound_ctrl:1
	v_pk_mul_f32 v[10:11], v[66:67], v[16:17] op_sel:[0,1] op_sel_hi:[1,1]
	v_pk_mul_f32 v[8:9], v[64:65], v[16:17] op_sel:[0,1] op_sel_hi:[1,1]
	v_add_f32_dpp v0, v0, v0 quad_perm:[2,3,0,1] row_mask:0xf bank_mask:0xf bound_ctrl:1
	ds_read_b128 v[40:43], v80 offset:16128
	ds_read_b128 v[44:47], v80 offset:32512
	ds_read_b128 v[48:51], v80 offset:7936
	ds_read_b128 v[52:55], v80 offset:24320
	ds_read_b128 v[56:59], v80 offset:40704
	v_add_f32_e32 v6, v6, v7
	ds_write_b32 v82, v6 offset:28672
	v_add_f32_dpp v0, v0, v0 row_half_mirror row_mask:0xf bank_mask:0xf bound_ctrl:1
	v_pk_fma_f32 v[10:11], v[70:71], v[4:5], v[10:11]
	v_pk_fma_f32 v[8:9], v[68:69], v[2:3], v[8:9]
	v_add_f32_dpp v0, v0, v0 row_mirror row_mask:0xf bank_mask:0xf bound_ctrl:1
	v_pk_fma_f32 v[4:5], v[74:75], v[0:1], v[10:11] op_sel_hi:[1,0,1]
	s_waitcnt lgkmcnt(11)
	v_pk_mul_f32 v[6:7], v[22:23], v[4:5]
	v_pk_fma_f32 v[2:3], v[72:73], v[0:1], v[8:9] op_sel_hi:[1,0,1]
	v_pk_fma_f32 v[6:7], v[20:21], v[2:3], v[6:7]
	s_waitcnt lgkmcnt(7)
	v_add_f32_e32 v0, v6, v7
	v_pk_mul_f32 v[6:7], v[78:79], v[4:5]
	v_pk_fma_f32 v[6:7], v[76:77], v[2:3], v[6:7]
	v_add_f32_dpp v0, v0, v0 quad_perm:[1,0,3,2] row_mask:0xf bank_mask:0xf bound_ctrl:1
	v_pk_mul_f32 v[10:11], v[26:27], v[18:19] op_sel_hi:[1,0]
	v_pk_mul_f32 v[8:9], v[24:25], v[18:19] op_sel_hi:[1,0]
	v_add_f32_dpp v0, v0, v0 quad_perm:[2,3,0,1] row_mask:0xf bank_mask:0xf bound_ctrl:1
	v_add_f32_e32 v6, v6, v7
	ds_write_b32 v82, v6 offset:29696
	v_add_f32_dpp v0, v0, v0 row_half_mirror row_mask:0xf bank_mask:0xf bound_ctrl:1
	v_pk_fma_f32 v[10:11], v[30:31], v[4:5], v[10:11]
	v_pk_fma_f32 v[8:9], v[28:29], v[2:3], v[8:9]
	v_add_f32_dpp v0, v0, v0 row_mirror row_mask:0xf bank_mask:0xf bound_ctrl:1
	v_pk_fma_f32 v[4:5], v[34:35], v[0:1], v[10:11] op_sel_hi:[1,0,1]
	s_waitcnt lgkmcnt(6)
	v_pk_mul_f32 v[6:7], v[42:43], v[4:5]
	v_pk_fma_f32 v[2:3], v[32:33], v[0:1], v[8:9] op_sel_hi:[1,0,1]
	v_pk_fma_f32 v[6:7], v[40:41], v[2:3], v[6:7]
	s_waitcnt lgkmcnt(2)
	v_add_f32_e32 v0, v6, v7
	v_pk_mul_f32 v[6:7], v[38:39], v[4:5]
	v_pk_fma_f32 v[6:7], v[36:37], v[2:3], v[6:7]
	v_add_f32_dpp v0, v0, v0 quad_perm:[1,0,3,2] row_mask:0xf bank_mask:0xf bound_ctrl:1
	v_pk_mul_f32 v[10:11], v[46:47], v[18:19] op_sel:[0,1] op_sel_hi:[1,1]
	v_pk_mul_f32 v[8:9], v[44:45], v[18:19] op_sel:[0,1] op_sel_hi:[1,1]
	v_add_f32_dpp v0, v0, v0 quad_perm:[2,3,0,1] row_mask:0xf bank_mask:0xf bound_ctrl:1
	v_add_f32_e32 v6, v6, v7
	ds_write_b32 v82, v6 offset:30720
	v_add_f32_dpp v0, v0, v0 row_half_mirror row_mask:0xf bank_mask:0xf bound_ctrl:1
	v_pk_fma_f32 v[10:11], v[50:51], v[4:5], v[10:11]
	v_pk_fma_f32 v[8:9], v[48:49], v[2:3], v[8:9]
	v_add_f32_dpp v0, v0, v0 row_mirror row_mask:0xf bank_mask:0xf bound_ctrl:1
	v_pk_fma_f32 v[4:5], v[54:55], v[0:1], v[10:11] op_sel_hi:[1,0,1]
	v_pk_fma_f32 v[2:3], v[52:53], v[0:1], v[8:9] op_sel_hi:[1,0,1]
	v_pk_mul_f32 v[6:7], v[58:59], v[4:5]
	v_pk_fma_f32 v[6:7], v[56:57], v[2:3], v[6:7]
	s_nop 0
	v_add_f32_e32 v6, v6, v7
	ds_write_b32 v82, v6 offset:31744
	s_waitcnt lgkmcnt(0)
	s_barrier
; #define LAS __attribute__((address_space(3)))
; __device__ __forceinline__ void phase_rwc(const int wvs, const Params& p, LAS unsigned char* lds, int layer, int wg0) {
;     ...
;     for (int blk = 0; blk < NBLK; ++blk) {
;       LAS float* Wv = (LAS float*)(lds + (blk & 1) * BUFSZ) + kg * 4; LAS float* Vv = (LAS float*)(lds + (blk & 1) * BUFSZ) + 5 * 2048 + rowl;
;       LAS float* ypw = (LAS float*)(lds + YOFF + (blk & 1) * YSZ) + rowl * 16 + kg;
;       asm volatile("" : "+v"(Wv), "+v"(Vv), "+v"(ypw));
;       f32x4 w4 = *(const LAS f32x4*)(Wv), kk4 = *(const LAS f32x4*)(Wv + 2048), b4 = *(const LAS f32x4*)(Wv + 4096), kd4 = *(const LAS f32x4*)(Wv + 6144), r4 = *(const LAS f32x4*)(Wv + 8192); float vv = Vv[0];
;       f32x4 xw4 = *(const LAS f32x4*)(Wv + 64), xkk4 = *(const LAS f32x4*)(Wv + 2048 + 64), xb4 = *(const LAS f32x4*)(Wv + 4096 + 64), xkd4 = *(const LAS f32x4*)(Wv + 6144 + 64), xr4 = *(const LAS f32x4*)(Wv + 8192 + 64); float xvv = Vv[16];
; #pragma unroll 16
;       for (int t = 0; t < 32; ++t) {
;         const int tn = t + 2;
;         const f32x4 nw4 = *(const LAS f32x4*)(Wv + tn * 64), nkk4 = *(const LAS f32x4*)(Wv + 2048 + tn * 64), nb4 = *(const LAS f32x4*)(Wv + 4096 + tn * 64), nkd4 = *(const LAS f32x4*)(Wv + 6144 + tn * 64), nr4 = *(const LAS f32x4*)(Wv + 8192 + tn * 64);
;         const float nvv = Vv[tn * 16];
;         const f32x4 pa = S * kk4;
;         const f32x4 t1 = S * w4 + vv * kd4;
;         float sa = (pa[0] + pa[2]) + (pa[1] + pa[3]);
;         sa = row16_sum(sa);
;         S = t1 + sa * b4;
;         const f32x4 py = S * r4;
;         ypw[t * 256] = (py[0] + py[2]) + (py[1] + py[3]);
;         w4 = xw4; kk4 = xkk4; b4 = xb4; kd4 = xkd4; r4 = xr4; vv = xvv;
;         xw4 = nw4; xkk4 = nkk4; xb4 = nb4; xkd4 = nkd4; xr4 = nr4; xvv = nvv;
;       }
	ds_read_b128 v[20:23], v83 offset:8192
	ds_read_b128 v[24:27], v83 offset:24576
	ds_read_b128 v[12:15], v84 offset:0
	ds_read_b128 v[28:31], v83 offset:0
	ds_read_b128 v[32:35], v83 offset:16384
	ds_read_b128 v[36:39], v83 offset:32768
	ds_read_b128 v[40:43], v83 offset:8448
	ds_read_b128 v[44:47], v83 offset:24832
	ds_read_b128 v[48:51], v83 offset:256
	ds_read_b128 v[52:55], v83 offset:16640
	ds_read_b128 v[56:59], v83 offset:33024
	s_waitcnt lgkmcnt(10)
	v_pk_mul_f32 v[6:7], v[22:23], v[4:5]
	v_pk_fma_f32 v[6:7], v[20:21], v[2:3], v[6:7]
	s_waitcnt lgkmcnt(5)
	v_add_f32_e32 v0, v6, v7
	v_pk_mul_f32 v[10:11], v[26:27], v[12:13] op_sel_hi:[1,0]
	v_pk_mul_f32 v[8:9], v[24:25], v[12:13] op_sel_hi:[1,0]
	v_add_f32_dpp v0, v0, v0 quad_perm:[1,0,3,2] row_mask:0xf bank_mask:0xf bound_ctrl:1
	v_pk_fma_f32 v[10:11], v[30:31], v[4:5], v[10:11]
	v_pk_fma_f32 v[8:9], v[28:29], v[2:3], v[8:9]
	v_add_f32_dpp v0, v0, v0 quad_perm:[2,3,0,1] row_mask:0xf bank_mask:0xf bound_ctrl:1
	ds_read_b128 v[60:63], v83 offset:8704
	ds_read_b128 v[64:67], v83 offset:25088
	ds_read_b128 v[68:71], v83 offset:512
	ds_read_b128 v[72:75], v83 offset:16896
	ds_read_b128 v[76:79], v83 offset:33280
	v_add_f32_dpp v0, v0, v0 row_half_mirror row_mask:0xf bank_mask:0xf bound_ctrl:1
	s_nop 1
	v_add_f32_dpp v0, v0, v0 row_mirror row_mask:0xf bank_mask:0xf bound_ctrl:1
	v_pk_fma_f32 v[4:5], v[34:35], v[0:1], v[10:11] op_sel_hi:[1,0,1]
	s_waitcnt lgkmcnt(9)
	v_pk_mul_f32 v[6:7], v[42:43], v[4:5]
	v_pk_fma_f32 v[2:3], v[32:33], v[0:1], v[8:9] op_sel_hi:[1,0,1]
	v_pk_fma_f32 v[6:7], v[40:41], v[2:3], v[6:7]
	s_waitcnt lgkmcnt(5)
	v_add_f32_e32 v0, v6, v7
	v_pk_mul_f32 v[6:7], v[38:39], v[4:5]
	v_pk_fma_f32 v[6:7], v[36:37], v[2:3], v[6:7]
	v_add_f32_dpp v0, v0, v0 quad_perm:[1,0,3,2] row_mask:0xf bank_mask:0xf bound_ctrl:1
	v_pk_mul_f32 v[10:11], v[46:47], v[12:13] op_sel:[0,1] op_sel_hi:[1,1]
	v_pk_mul_f32 v[8:9], v[44:45], v[12:13] op_sel:[0,1] op_sel_hi:[1,1]
	v_add_f32_dpp v0, v0, v0 quad_perm:[2,3,0,1] row_mask:0xf bank_mask:0xf bound_ctrl:1
	ds_read_b128 v[20:23], v83 offset:8960
	ds_read_b128 v[24:27], v83 offset:25344
	ds_read_b128 v[28:31], v83 offset:768
	ds_read_b128 v[32:35], v83 offset:17152
	ds_read_b128 v[36:39], v83 offset:33536
	ds_read_b128 v[16:19], v84 offset:16
	v_add_f32_e32 v6, v6, v7
	ds_write_b32 v85, v6 offset:0
	v_add_f32_dpp v0, v0, v0 row_half_mirror row_mask:0xf bank_mask:0xf bound_ctrl:1
	v_pk_fma_f32 v[10:11], v[50:51], v[4:5], v[10:11]
	v_pk_fma_f32 v[8:9], v[48:49], v[2:3], v[8:9]
	v_add_f32_dpp v0, v0, v0 row_mirror row_mask:0xf bank_mask:0xf bound_ctrl:1
	v_pk_fma_f32 v[4:5], v[54:55], v[0:1], v[10:11] op_sel_hi:[1,0,1]
	s_waitcnt lgkmcnt(11)
	v_pk_mul_f32 v[6:7], v[62:63], v[4:5]
	v_pk_fma_f32 v[2:3], v[52:53], v[0:1], v[8:9] op_sel_hi:[1,0,1]
	v_pk_fma_f32 v[6:7], v[60:61], v[2:3], v[6:7]
	s_waitcnt lgkmcnt(7)
	v_add_f32_e32 v0, v6, v7
	v_pk_mul_f32 v[6:7], v[58:59], v[4:5]
	v_pk_fma_f32 v[6:7], v[56:57], v[2:3], v[6:7]
	v_add_f32_dpp v0, v0, v0 quad_perm:[1,0,3,2] row_mask:0xf bank_mask:0xf bound_ctrl:1
	v_pk_mul_f32 v[10:11], v[66:67], v[14:15] op_sel_hi:[1,0]
	v_pk_mul_f32 v[8:9], v[64:65], v[14:15] op_sel_hi:[1,0]
	v_add_f32_dpp v0, v0, v0 quad_perm:[2,3,0,1] row_mask:0xf bank_mask:0xf bound_ctrl:1
	ds_read_b128 v[40:43], v83 offset:9216
	ds_read_b128 v[44:47], v83 offset:25600
	ds_read_b128 v[48:51], v83 offset:1024
	ds_read_b128 v[52:55], v83 offset:17408
	ds_read_b128 v[56:59], v83 offset:33792
	v_add_f32_e32 v6, v6, v7
	ds_write_b32 v85, v6 offset:1024
	v_add_f32_dpp v0, v0, v0 row_half_mirror row_mask:0xf bank_mask:0xf bound_ctrl:1
	v_pk_fma_f32 v[10:11], v[70:71], v[4:5], v[10:11]
	v_pk_fma_f32 v[8:9], v[68:69], v[2:3], v[8:9]
	v_add_f32_dpp v0, v0, v0 row_mirror row_mask:0xf bank_mask:0xf bound_ctrl:1
	v_pk_fma_f32 v[4:5], v[74:75], v[0:1], v[10:11] op_sel_hi:[1,0,1]
	s_waitcnt lgkmcnt(12)
	v_pk_mul_f32 v[6:7], v[22:23], v[4:5]
	v_pk_fma_f32 v[2:3], v[72:73], v[0:1], v[8:9] op_sel_hi:[1,0,1]
	v_pk_fma_f32 v[6:7], v[20:21], v[2:3], v[6:7]
	s_waitcnt lgkmcnt(8)
	v_add_f32_e32 v0, v6, v7
	v_pk_mul_f32 v[6:7], v[78:79], v[4:5]
	v_pk_fma_f32 v[6:7], v[76:77], v[2:3], v[6:7]
	v_add_f32_dpp v0, v0, v0 quad_perm:[1,0,3,2] row_mask:0xf bank_mask:0xf bound_ctrl:1
	v_pk_mul_f32 v[10:11], v[26:27], v[14:15] op_sel:[0,1] op_sel_hi:[1,1]
	v_pk_mul_f32 v[8:9], v[24:25], v[14:15] op_sel:[0,1] op_sel_hi:[1,1]
	v_add_f32_dpp v0, v0, v0 quad_perm:[2,3,0,1] row_mask:0xf bank_mask:0xf bound_ctrl:1
	ds_read_b128 v[60:63], v83 offset:9472
	ds_read_b128 v[64:67], v83 offset:25856
	ds_read_b128 v[68:71], v83 offset:1280
	ds_read_b128 v[72:75], v83 offset:17664
	ds_read_b128 v[76:79], v83 offset:34048
	v_add_f32_e32 v6, v6, v7
	ds_write_b32 v85, v6 offset:2048
	v_add_f32_dpp v0, v0, v0 row_half_mirror row_mask:0xf bank_mask:0xf bound_ctrl:1
	v_pk_fma_f32 v[10:11], v[30:31], v[4:5], v[10:11]
	v_pk_fma_f32 v[8:9], v[28:29], v[2:3], v[8:9]
	v_add_f32_dpp v0, v0, v0 row_mirror row_mask:0xf bank_mask:0xf bound_ctrl:1
	v_pk_fma_f32 v[4:5], v[34:35], v[0:1], v[10:11] op_sel_hi:[1,0,1]
	s_waitcnt lgkmcnt(11)
	v_pk_mul_f32 v[6:7], v[42:43], v[4:5]
	v_pk_fma_f32 v[2:3], v[32:33], v[0:1], v[8:9] op_sel_hi:[1,0,1]
	v_pk_fma_f32 v[6:7], v[40:41], v[2:3], v[6:7]
	s_waitcnt lgkmcnt(7)
; #define LAS __attribute__((address_space(3)))
; __device__ __forceinline__ void phase_rwc(const int wvs, const Params& p, LAS unsigned char* lds, int layer, int wg0) {
;     ...
; #pragma unroll 16
;       for (int t = 0; t < 32; ++t) {
;         const int tn = t + 2;
;         const f32x4 nw4 = *(const LAS f32x4*)(Wv + tn * 64), nkk4 = *(const LAS f32x4*)(Wv + 2048 + tn * 64), nb4 = *(const LAS f32x4*)(Wv + 4096 + tn * 64), nkd4 = *(const LAS f32x4*)(Wv + 6144 + tn * 64), nr4 = *(const LAS f32x4*)(Wv + 8192 + tn * 64);
;         const float nvv = Vv[tn * 16];
;         const f32x4 pa = S * kk4;
;         const f32x4 t1 = S * w4 + vv * kd4;
;         float sa = (pa[0] + pa[2]) + (pa[1] + pa[3]);
;         sa = row16_sum(sa);
;         S = t1 + sa * b4;
;         const f32x4 py = S * r4;
;         ypw[t * 256] = (py[0] + py[2]) + (py[1] + py[3]);
;         w4 = xw4; kk4 = xkk4; b4 = xb4; kd4 = xkd4; r4 = xr4; vv = xvv;
;         xw4 = nw4; xkk4 = nkk4; xb4 = nb4; xkd4 = nkd4; xr4 = nr4; xvv = nvv;
;       }
	v_add_f32_e32 v0, v6, v7
	v_pk_mul_f32 v[6:7], v[38:39], v[4:5]
	v_pk_fma_f32 v[6:7], v[36:37], v[2:3], v[6:7]
	v_add_f32_dpp v0, v0, v0 quad_perm:[1,0,3,2] row_mask:0xf bank_mask:0xf bound_ctrl:1
	v_pk_mul_f32 v[10:11], v[46:47], v[16:17] op_sel_hi:[1,0]
	v_pk_mul_f32 v[8:9], v[44:45], v[16:17] op_sel_hi:[1,0]
	v_add_f32_dpp v0, v0, v0 quad_perm:[2,3,0,1] row_mask:0xf bank_mask:0xf bound_ctrl:1
	ds_read_b128 v[20:23], v83 offset:9728
	ds_read_b128 v[24:27], v83 offset:26112
	ds_read_b128 v[28:31], v83 offset:1536
	ds_read_b128 v[32:35], v83 offset:17920
	ds_read_b128 v[36:39], v83 offset:34304
	v_add_f32_e32 v6, v6, v7
	ds_write_b32 v85, v6 offset:3072
	v_add_f32_dpp v0, v0, v0 row_half_mirror row_mask:0xf bank_mask:0xf bound_ctrl:1
	v_pk_fma_f32 v[10:11], v[50:51], v[4:5], v[10:11]
	v_pk_fma_f32 v[8:9], v[48:49], v[2:3], v[8:9]
	v_add_f32_dpp v0, v0, v0 row_mirror row_mask:0xf bank_mask:0xf bound_ctrl:1
	v_pk_fma_f32 v[4:5], v[54:55], v[0:1], v[10:11] op_sel_hi:[1,0,1]
	s_waitcnt lgkmcnt(11)
	v_pk_mul_f32 v[6:7], v[62:63], v[4:5]
	v_pk_fma_f32 v[2:3], v[52:53], v[0:1], v[8:9] op_sel_hi:[1,0,1]
	v_pk_fma_f32 v[6:7], v[60:61], v[2:3], v[6:7]
	s_waitcnt lgkmcnt(7)
	v_add_f32_e32 v0, v6, v7
	v_pk_mul_f32 v[6:7], v[58:59], v[4:5]
	v_pk_fma_f32 v[6:7], v[56:57], v[2:3], v[6:7]
	v_add_f32_dpp v0, v0, v0 quad_perm:[1,0,3,2] row_mask:0xf bank_mask:0xf bound_ctrl:1
	v_pk_mul_f32 v[10:11], v[66:67], v[16:17] op_sel:[0,1] op_sel_hi:[1,1]
	v_pk_mul_f32 v[8:9], v[64:65], v[16:17] op_sel:[0,1] op_sel_hi:[1,1]
	v_add_f32_dpp v0, v0, v0 quad_perm:[2,3,0,1] row_mask:0xf bank_mask:0xf bound_ctrl:1
	ds_read_b128 v[40:43], v83 offset:9984
	ds_read_b128 v[44:47], v83 offset:26368
	ds_read_b128 v[48:51], v83 offset:1792
	ds_read_b128 v[52:55], v83 offset:18176
	ds_read_b128 v[56:59], v83 offset:34560
	ds_read_b128 v[12:15], v84 offset:32
	v_add_f32_e32 v6, v6, v7
	ds_write_b32 v85, v6 offset:4096
	v_add_f32_dpp v0, v0, v0 row_half_mirror row_mask:0xf bank_mask:0xf bound_ctrl:1
	v_pk_fma_f32 v[10:11], v[70:71], v[4:5], v[10:11]
	v_pk_fma_f32 v[8:9], v[68:69], v[2:3], v[8:9]
	v_add_f32_dpp v0, v0, v0 row_mirror row_mask:0xf bank_mask:0xf bound_ctrl:1
	v_pk_fma_f32 v[4:5], v[74:75], v[0:1], v[10:11] op_sel_hi:[1,0,1]
	s_waitcnt lgkmcnt(12)
	v_pk_mul_f32 v[6:7], v[22:23], v[4:5]
	v_pk_fma_f32 v[2:3], v[72:73], v[0:1], v[8:9] op_sel_hi:[1,0,1]
	v_pk_fma_f32 v[6:7], v[20:21], v[2:3], v[6:7]
	s_waitcnt lgkmcnt(8)
	v_add_f32_e32 v0, v6, v7
	v_pk_mul_f32 v[6:7], v[78:79], v[4:5]
	v_pk_fma_f32 v[6:7], v[76:77], v[2:3], v[6:7]
	v_add_f32_dpp v0, v0, v0 quad_perm:[1,0,3,2] row_mask:0xf bank_mask:0xf bound_ctrl:1
	v_pk_mul_f32 v[10:11], v[26:27], v[18:19] op_sel_hi:[1,0]
	v_pk_mul_f32 v[8:9], v[24:25], v[18:19] op_sel_hi:[1,0]
	v_add_f32_dpp v0, v0, v0 quad_perm:[2,3,0,1] row_mask:0xf bank_mask:0xf bound_ctrl:1
	ds_read_b128 v[60:63], v83 offset:10240
	ds_read_b128 v[64:67], v83 offset:26624
	ds_read_b128 v[68:71], v83 offset:2048
	ds_read_b128 v[72:75], v83 offset:18432
	ds_read_b128 v[76:79], v83 offset:34816
	v_add_f32_e32 v6, v6, v7
	ds_write_b32 v85, v6 offset:5120
	v_add_f32_dpp v0, v0, v0 row_half_mirror row_mask:0xf bank_mask:0xf bound_ctrl:1
	v_pk_fma_f32 v[10:11], v[30:31], v[4:5], v[10:11]
	v_pk_fma_f32 v[8:9], v[28:29], v[2:3], v[8:9]
	v_add_f32_dpp v0, v0, v0 row_mirror row_mask:0xf bank_mask:0xf bound_ctrl:1
	v_pk_fma_f32 v[4:5], v[34:35], v[0:1], v[10:11] op_sel_hi:[1,0,1]
	s_waitcnt lgkmcnt(12)
	v_pk_mul_f32 v[6:7], v[42:43], v[4:5]
	v_pk_fma_f32 v[2:3], v[32:33], v[0:1], v[8:9] op_sel_hi:[1,0,1]
	v_pk_fma_f32 v[6:7], v[40:41], v[2:3], v[6:7]
	s_waitcnt lgkmcnt(8)
	v_add_f32_e32 v0, v6, v7
	v_pk_mul_f32 v[6:7], v[38:39], v[4:5]
	v_pk_fma_f32 v[6:7], v[36:37], v[2:3], v[6:7]
	v_add_f32_dpp v0, v0, v0 quad_perm:[1,0,3,2] row_mask:0xf bank_mask:0xf bound_ctrl:1
	v_pk_mul_f32 v[10:11], v[46:47], v[18:19] op_sel:[0,1] op_sel_hi:[1,1]
	v_pk_mul_f32 v[8:9], v[44:45], v[18:19] op_sel:[0,1] op_sel_hi:[1,1]
	v_add_f32_dpp v0, v0, v0 quad_perm:[2,3,0,1] row_mask:0xf bank_mask:0xf bound_ctrl:1
	ds_read_b128 v[20:23], v83 offset:10496
	ds_read_b128 v[24:27], v83 offset:26880
	ds_read_b128 v[28:31], v83 offset:2304
	ds_read_b128 v[32:35], v83 offset:18688
	ds_read_b128 v[36:39], v83 offset:35072
	v_add_f32_e32 v6, v6, v7
	ds_write_b32 v85, v6 offset:6144
	v_add_f32_dpp v0, v0, v0 row_half_mirror row_mask:0xf bank_mask:0xf bound_ctrl:1
	v_pk_fma_f32 v[10:11], v[50:51], v[4:5], v[10:11]
	v_pk_fma_f32 v[8:9], v[48:49], v[2:3], v[8:9]
	v_add_f32_dpp v0, v0, v0 row_mirror row_mask:0xf bank_mask:0xf bound_ctrl:1
	v_pk_fma_f32 v[4:5], v[54:55], v[0:1], v[10:11] op_sel_hi:[1,0,1]
	s_waitcnt lgkmcnt(11)
	v_pk_mul_f32 v[6:7], v[62:63], v[4:5]
	v_pk_fma_f32 v[2:3], v[52:53], v[0:1], v[8:9] op_sel_hi:[1,0,1]
	v_pk_fma_f32 v[6:7], v[60:61], v[2:3], v[6:7]
	s_waitcnt lgkmcnt(7)
	v_add_f32_e32 v0, v6, v7
	v_pk_mul_f32 v[6:7], v[58:59], v[4:5]
	v_pk_fma_f32 v[6:7], v[56:57], v[2:3], v[6:7]
	v_add_f32_dpp v0, v0, v0 quad_perm:[1,0,3,2] row_mask:0xf bank_mask:0xf bound_ctrl:1
	v_pk_mul_f32 v[10:11], v[66:67], v[12:13] op_sel_hi:[1,0]
	v_pk_mul_f32 v[8:9], v[64:65], v[12:13] op_sel_hi:[1,0]
	v_add_f32_dpp v0, v0, v0 quad_perm:[2,3,0,1] row_mask:0xf bank_mask:0xf bound_ctrl:1
	ds_read_b128 v[40:43], v83 offset:10752
	ds_read_b128 v[44:47], v83 offset:27136
	ds_read_b128 v[48:51], v83 offset:2560
	ds_read_b128 v[52:55], v83 offset:18944
	ds_read_b128 v[56:59], v83 offset:35328
	v_add_f32_e32 v6, v6, v7
	ds_write_b32 v85, v6 offset:7168
	v_add_f32_dpp v0, v0, v0 row_half_mirror row_mask:0xf bank_mask:0xf bound_ctrl:1
	v_pk_fma_f32 v[10:11], v[70:71], v[4:5], v[10:11]
	v_pk_fma_f32 v[8:9], v[68:69], v[2:3], v[8:9]
	v_add_f32_dpp v0, v0, v0 row_mirror row_mask:0xf bank_mask:0xf bound_ctrl:1
	v_pk_fma_f32 v[4:5], v[74:75], v[0:1], v[10:11] op_sel_hi:[1,0,1]
	s_waitcnt lgkmcnt(11)
; #define LAS __attribute__((address_space(3)))
; __device__ __forceinline__ void phase_rwc(const int wvs, const Params& p, LAS unsigned char* lds, int layer, int wg0) {
;     ...
; #pragma unroll 16
;       for (int t = 0; t < 32; ++t) {
;         const int tn = t + 2;
;         const f32x4 nw4 = *(const LAS f32x4*)(Wv + tn * 64), nkk4 = *(const LAS f32x4*)(Wv + 2048 + tn * 64), nb4 = *(const LAS f32x4*)(Wv + 4096 + tn * 64), nkd4 = *(const LAS f32x4*)(Wv + 6144 + tn * 64), nr4 = *(const LAS f32x4*)(Wv + 8192 + tn * 64);
;         const float nvv = Vv[tn * 16];
;         const f32x4 pa = S * kk4;
;         const f32x4 t1 = S * w4 + vv * kd4;
;         float sa = (pa[0] + pa[2]) + (pa[1] + pa[3]);
;         sa = row16_sum(sa);
;         S = t1 + sa * b4;
;         const f32x4 py = S * r4;
;         ypw[t * 256] = (py[0] + py[2]) + (py[1] + py[3]);
;         w4 = xw4; kk4 = xkk4; b4 = xb4; kd4 = xkd4; r4 = xr4; vv = xvv;
;         xw4 = nw4; xkk4 = nkk4; xb4 = nb4; xkd4 = nkd4; xr4 = nr4; xvv = nvv;
;       }
	v_pk_mul_f32 v[6:7], v[22:23], v[4:5]
	v_pk_fma_f32 v[2:3], v[72:73], v[0:1], v[8:9] op_sel_hi:[1,0,1]
	v_pk_fma_f32 v[6:7], v[20:21], v[2:3], v[6:7]
	s_waitcnt lgkmcnt(7)
	v_add_f32_e32 v0, v6, v7
	v_pk_mul_f32 v[6:7], v[78:79], v[4:5]
	v_pk_fma_f32 v[6:7], v[76:77], v[2:3], v[6:7]
	v_add_f32_dpp v0, v0, v0 quad_perm:[1,0,3,2] row_mask:0xf bank_mask:0xf bound_ctrl:1
	v_pk_mul_f32 v[10:11], v[26:27], v[12:13] op_sel:[0,1] op_sel_hi:[1,1]
	v_pk_mul_f32 v[8:9], v[24:25], v[12:13] op_sel:[0,1] op_sel_hi:[1,1]
	v_add_f32_dpp v0, v0, v0 quad_perm:[2,3,0,1] row_mask:0xf bank_mask:0xf bound_ctrl:1
	ds_read_b128 v[60:63], v83 offset:11008
	ds_read_b128 v[64:67], v83 offset:27392
	ds_read_b128 v[68:71], v83 offset:2816
	ds_read_b128 v[72:75], v83 offset:19200
	ds_read_b128 v[76:79], v83 offset:35584
	ds_read_b128 v[16:19], v84 offset:48
	v_add_f32_e32 v6, v6, v7
	ds_write_b32 v85, v6 offset:8192
	v_add_f32_dpp v0, v0, v0 row_half_mirror row_mask:0xf bank_mask:0xf bound_ctrl:1
	v_pk_fma_f32 v[10:11], v[30:31], v[4:5], v[10:11]
	v_pk_fma_f32 v[8:9], v[28:29], v[2:3], v[8:9]
	v_add_f32_dpp v0, v0, v0 row_mirror row_mask:0xf bank_mask:0xf bound_ctrl:1
	v_pk_fma_f32 v[4:5], v[34:35], v[0:1], v[10:11] op_sel_hi:[1,0,1]
	s_waitcnt lgkmcnt(12)
	v_pk_mul_f32 v[6:7], v[42:43], v[4:5]
	v_pk_fma_f32 v[2:3], v[32:33], v[0:1], v[8:9] op_sel_hi:[1,0,1]
	v_pk_fma_f32 v[6:7], v[40:41], v[2:3], v[6:7]
	s_waitcnt lgkmcnt(8)
	v_add_f32_e32 v0, v6, v7
	v_pk_mul_f32 v[6:7], v[38:39], v[4:5]
	v_pk_fma_f32 v[6:7], v[36:37], v[2:3], v[6:7]
	v_add_f32_dpp v0, v0, v0 quad_perm:[1,0,3,2] row_mask:0xf bank_mask:0xf bound_ctrl:1
	v_pk_mul_f32 v[10:11], v[46:47], v[14:15] op_sel_hi:[1,0]
	v_pk_mul_f32 v[8:9], v[44:45], v[14:15] op_sel_hi:[1,0]
	v_add_f32_dpp v0, v0, v0 quad_perm:[2,3,0,1] row_mask:0xf bank_mask:0xf bound_ctrl:1
	ds_read_b128 v[20:23], v83 offset:11264
	ds_read_b128 v[24:27], v83 offset:27648
	ds_read_b128 v[28:31], v83 offset:3072
	ds_read_b128 v[32:35], v83 offset:19456
	ds_read_b128 v[36:39], v83 offset:35840
	v_add_f32_e32 v6, v6, v7
	ds_write_b32 v85, v6 offset:9216
	v_add_f32_dpp v0, v0, v0 row_half_mirror row_mask:0xf bank_mask:0xf bound_ctrl:1
	v_pk_fma_f32 v[10:11], v[50:51], v[4:5], v[10:11]
	v_pk_fma_f32 v[8:9], v[48:49], v[2:3], v[8:9]
	v_add_f32_dpp v0, v0, v0 row_mirror row_mask:0xf bank_mask:0xf bound_ctrl:1
	v_pk_fma_f32 v[4:5], v[54:55], v[0:1], v[10:11] op_sel_hi:[1,0,1]
	s_waitcnt lgkmcnt(12)
	v_pk_mul_f32 v[6:7], v[62:63], v[4:5]
	v_pk_fma_f32 v[2:3], v[52:53], v[0:1], v[8:9] op_sel_hi:[1,0,1]
	v_pk_fma_f32 v[6:7], v[60:61], v[2:3], v[6:7]
	s_waitcnt lgkmcnt(8)
	v_add_f32_e32 v0, v6, v7
	v_pk_mul_f32 v[6:7], v[58:59], v[4:5]
	v_pk_fma_f32 v[6:7], v[56:57], v[2:3], v[6:7]
	v_add_f32_dpp v0, v0, v0 quad_perm:[1,0,3,2] row_mask:0xf bank_mask:0xf bound_ctrl:1
	v_pk_mul_f32 v[10:11], v[66:67], v[14:15] op_sel:[0,1] op_sel_hi:[1,1]
	v_pk_mul_f32 v[8:9], v[64:65], v[14:15] op_sel:[0,1] op_sel_hi:[1,1]
	v_add_f32_dpp v0, v0, v0 quad_perm:[2,3,0,1] row_mask:0xf bank_mask:0xf bound_ctrl:1
	ds_read_b128 v[40:43], v83 offset:11520
	ds_read_b128 v[44:47], v83 offset:27904
	ds_read_b128 v[48:51], v83 offset:3328
	ds_read_b128 v[52:55], v83 offset:19712
	ds_read_b128 v[56:59], v83 offset:36096
	v_add_f32_e32 v6, v6, v7
	ds_write_b32 v85, v6 offset:10240
	v_add_f32_dpp v0, v0, v0 row_half_mirror row_mask:0xf bank_mask:0xf bound_ctrl:1
	v_pk_fma_f32 v[10:11], v[70:71], v[4:5], v[10:11]
	v_pk_fma_f32 v[8:9], v[68:69], v[2:3], v[8:9]
	v_add_f32_dpp v0, v0, v0 row_mirror row_mask:0xf bank_mask:0xf bound_ctrl:1
	v_pk_fma_f32 v[4:5], v[74:75], v[0:1], v[10:11] op_sel_hi:[1,0,1]
	s_waitcnt lgkmcnt(11)
	v_pk_mul_f32 v[6:7], v[22:23], v[4:5]
	v_pk_fma_f32 v[2:3], v[72:73], v[0:1], v[8:9] op_sel_hi:[1,0,1]
	v_pk_fma_f32 v[6:7], v[20:21], v[2:3], v[6:7]
	s_waitcnt lgkmcnt(7)
	v_add_f32_e32 v0, v6, v7
	v_pk_mul_f32 v[6:7], v[78:79], v[4:5]
	v_pk_fma_f32 v[6:7], v[76:77], v[2:3], v[6:7]
	v_add_f32_dpp v0, v0, v0 quad_perm:[1,0,3,2] row_mask:0xf bank_mask:0xf bound_ctrl:1
	v_pk_mul_f32 v[10:11], v[26:27], v[16:17] op_sel_hi:[1,0]
	v_pk_mul_f32 v[8:9], v[24:25], v[16:17] op_sel_hi:[1,0]
	v_add_f32_dpp v0, v0, v0 quad_perm:[2,3,0,1] row_mask:0xf bank_mask:0xf bound_ctrl:1
	ds_read_b128 v[60:63], v83 offset:11776
	ds_read_b128 v[64:67], v83 offset:28160
	ds_read_b128 v[68:71], v83 offset:3584
	ds_read_b128 v[72:75], v83 offset:19968
	ds_read_b128 v[76:79], v83 offset:36352
	v_add_f32_e32 v6, v6, v7
	ds_write_b32 v85, v6 offset:11264
	v_add_f32_dpp v0, v0, v0 row_half_mirror row_mask:0xf bank_mask:0xf bound_ctrl:1
	v_pk_fma_f32 v[10:11], v[30:31], v[4:5], v[10:11]
	v_pk_fma_f32 v[8:9], v[28:29], v[2:3], v[8:9]
	v_add_f32_dpp v0, v0, v0 row_mirror row_mask:0xf bank_mask:0xf bound_ctrl:1
	v_pk_fma_f32 v[4:5], v[34:35], v[0:1], v[10:11] op_sel_hi:[1,0,1]
	s_waitcnt lgkmcnt(11)
	v_pk_mul_f32 v[6:7], v[42:43], v[4:5]
	v_pk_fma_f32 v[2:3], v[32:33], v[0:1], v[8:9] op_sel_hi:[1,0,1]
	v_pk_fma_f32 v[6:7], v[40:41], v[2:3], v[6:7]
	s_waitcnt lgkmcnt(7)
	v_add_f32_e32 v0, v6, v7
	v_pk_mul_f32 v[6:7], v[38:39], v[4:5]
	v_pk_fma_f32 v[6:7], v[36:37], v[2:3], v[6:7]
	v_add_f32_dpp v0, v0, v0 quad_perm:[1,0,3,2] row_mask:0xf bank_mask:0xf bound_ctrl:1
	v_pk_mul_f32 v[10:11], v[46:47], v[16:17] op_sel:[0,1] op_sel_hi:[1,1]
	v_pk_mul_f32 v[8:9], v[44:45], v[16:17] op_sel:[0,1] op_sel_hi:[1,1]
	v_add_f32_dpp v0, v0, v0 quad_perm:[2,3,0,1] row_mask:0xf bank_mask:0xf bound_ctrl:1
	ds_read_b128 v[20:23], v83 offset:12032
	ds_read_b128 v[24:27], v83 offset:28416
	ds_read_b128 v[28:31], v83 offset:3840
	ds_read_b128 v[32:35], v83 offset:20224
	ds_read_b128 v[36:39], v83 offset:36608
	ds_read_b128 v[12:15], v84 offset:64
	v_add_f32_e32 v6, v6, v7
	ds_write_b32 v85, v6 offset:12288
	v_add_f32_dpp v0, v0, v0 row_half_mirror row_mask:0xf bank_mask:0xf bound_ctrl:1
	v_pk_fma_f32 v[10:11], v[50:51], v[4:5], v[10:11]
	v_pk_fma_f32 v[8:9], v[48:49], v[2:3], v[8:9]
	v_add_f32_dpp v0, v0, v0 row_mirror row_mask:0xf bank_mask:0xf bound_ctrl:1
	v_pk_fma_f32 v[4:5], v[54:55], v[0:1], v[10:11] op_sel_hi:[1,0,1]
	s_waitcnt lgkmcnt(12)
; #define LAS __attribute__((address_space(3)))
; __device__ __forceinline__ void phase_rwc(const int wvs, const Params& p, LAS unsigned char* lds, int layer, int wg0) {
;     ...
; #pragma unroll 16
;       for (int t = 0; t < 32; ++t) {
;         const int tn = t + 2;
;         const f32x4 nw4 = *(const LAS f32x4*)(Wv + tn * 64), nkk4 = *(const LAS f32x4*)(Wv + 2048 + tn * 64), nb4 = *(const LAS f32x4*)(Wv + 4096 + tn * 64), nkd4 = *(const LAS f32x4*)(Wv + 6144 + tn * 64), nr4 = *(const LAS f32x4*)(Wv + 8192 + tn * 64);
;         const float nvv = Vv[tn * 16];
;         const f32x4 pa = S * kk4;
;         const f32x4 t1 = S * w4 + vv * kd4;
;         float sa = (pa[0] + pa[2]) + (pa[1] + pa[3]);
;         sa = row16_sum(sa);
;         S = t1 + sa * b4;
;         const f32x4 py = S * r4;
;         ypw[t * 256] = (py[0] + py[2]) + (py[1] + py[3]);
;         w4 = xw4; kk4 = xkk4; b4 = xb4; kd4 = xkd4; r4 = xr4; vv = xvv;
;         xw4 = nw4; xkk4 = nkk4; xb4 = nb4; xkd4 = nkd4; xr4 = nr4; xvv = nvv;
;       }
	v_pk_mul_f32 v[6:7], v[62:63], v[4:5]
	v_pk_fma_f32 v[2:3], v[52:53], v[0:1], v[8:9] op_sel_hi:[1,0,1]
	v_pk_fma_f32 v[6:7], v[60:61], v[2:3], v[6:7]
	s_waitcnt lgkmcnt(8)
	v_add_f32_e32 v0, v6, v7
	v_pk_mul_f32 v[6:7], v[58:59], v[4:5]
	v_pk_fma_f32 v[6:7], v[56:57], v[2:3], v[6:7]
	v_add_f32_dpp v0, v0, v0 quad_perm:[1,0,3,2] row_mask:0xf bank_mask:0xf bound_ctrl:1
	v_pk_mul_f32 v[10:11], v[66:67], v[18:19] op_sel_hi:[1,0]
	v_pk_mul_f32 v[8:9], v[64:65], v[18:19] op_sel_hi:[1,0]
	v_add_f32_dpp v0, v0, v0 quad_perm:[2,3,0,1] row_mask:0xf bank_mask:0xf bound_ctrl:1
	ds_read_b128 v[40:43], v83 offset:12288
	ds_read_b128 v[44:47], v83 offset:28672
	ds_read_b128 v[48:51], v83 offset:4096
	ds_read_b128 v[52:55], v83 offset:20480
	ds_read_b128 v[56:59], v83 offset:36864
	v_add_f32_e32 v6, v6, v7
	ds_write_b32 v85, v6 offset:13312
	v_add_f32_dpp v0, v0, v0 row_half_mirror row_mask:0xf bank_mask:0xf bound_ctrl:1
	v_pk_fma_f32 v[10:11], v[70:71], v[4:5], v[10:11]
	v_pk_fma_f32 v[8:9], v[68:69], v[2:3], v[8:9]
	v_add_f32_dpp v0, v0, v0 row_mirror row_mask:0xf bank_mask:0xf bound_ctrl:1
	v_pk_fma_f32 v[4:5], v[74:75], v[0:1], v[10:11] op_sel_hi:[1,0,1]
	s_waitcnt lgkmcnt(12)
	v_pk_mul_f32 v[6:7], v[22:23], v[4:5]
	v_pk_fma_f32 v[2:3], v[72:73], v[0:1], v[8:9] op_sel_hi:[1,0,1]
	v_pk_fma_f32 v[6:7], v[20:21], v[2:3], v[6:7]
	s_waitcnt lgkmcnt(8)
	v_add_f32_e32 v0, v6, v7
	v_pk_mul_f32 v[6:7], v[78:79], v[4:5]
	v_pk_fma_f32 v[6:7], v[76:77], v[2:3], v[6:7]
	v_add_f32_dpp v0, v0, v0 quad_perm:[1,0,3,2] row_mask:0xf bank_mask:0xf bound_ctrl:1
	v_pk_mul_f32 v[10:11], v[26:27], v[18:19] op_sel:[0,1] op_sel_hi:[1,1]
	v_pk_mul_f32 v[8:9], v[24:25], v[18:19] op_sel:[0,1] op_sel_hi:[1,1]
	v_add_f32_dpp v0, v0, v0 quad_perm:[2,3,0,1] row_mask:0xf bank_mask:0xf bound_ctrl:1
	ds_read_b128 v[60:63], v83 offset:12544
	ds_read_b128 v[64:67], v83 offset:28928
	ds_read_b128 v[68:71], v83 offset:4352
	ds_read_b128 v[72:75], v83 offset:20736
	ds_read_b128 v[76:79], v83 offset:37120
	v_add_f32_e32 v6, v6, v7
	ds_write_b32 v85, v6 offset:14336
	v_add_f32_dpp v0, v0, v0 row_half_mirror row_mask:0xf bank_mask:0xf bound_ctrl:1
	v_pk_fma_f32 v[10:11], v[30:31], v[4:5], v[10:11]
	v_pk_fma_f32 v[8:9], v[28:29], v[2:3], v[8:9]
	v_add_f32_dpp v0, v0, v0 row_mirror row_mask:0xf bank_mask:0xf bound_ctrl:1
	v_pk_fma_f32 v[4:5], v[34:35], v[0:1], v[10:11] op_sel_hi:[1,0,1]
	s_waitcnt lgkmcnt(11)
	v_pk_mul_f32 v[6:7], v[42:43], v[4:5]
	v_pk_fma_f32 v[2:3], v[32:33], v[0:1], v[8:9] op_sel_hi:[1,0,1]
	v_pk_fma_f32 v[6:7], v[40:41], v[2:3], v[6:7]
	s_waitcnt lgkmcnt(7)
	v_add_f32_e32 v0, v6, v7
	v_pk_mul_f32 v[6:7], v[38:39], v[4:5]
	v_pk_fma_f32 v[6:7], v[36:37], v[2:3], v[6:7]
	v_add_f32_dpp v0, v0, v0 quad_perm:[1,0,3,2] row_mask:0xf bank_mask:0xf bound_ctrl:1
	v_pk_mul_f32 v[10:11], v[46:47], v[12:13] op_sel_hi:[1,0]
	v_pk_mul_f32 v[8:9], v[44:45], v[12:13] op_sel_hi:[1,0]
	v_add_f32_dpp v0, v0, v0 quad_perm:[2,3,0,1] row_mask:0xf bank_mask:0xf bound_ctrl:1
	ds_read_b128 v[20:23], v83 offset:12800
	ds_read_b128 v[24:27], v83 offset:29184
	ds_read_b128 v[28:31], v83 offset:4608
	ds_read_b128 v[32:35], v83 offset:20992
	ds_read_b128 v[36:39], v83 offset:37376
	v_add_f32_e32 v6, v6, v7
	ds_write_b32 v85, v6 offset:15360
	v_add_f32_dpp v0, v0, v0 row_half_mirror row_mask:0xf bank_mask:0xf bound_ctrl:1
	v_pk_fma_f32 v[10:11], v[50:51], v[4:5], v[10:11]
	v_pk_fma_f32 v[8:9], v[48:49], v[2:3], v[8:9]
	v_add_f32_dpp v0, v0, v0 row_mirror row_mask:0xf bank_mask:0xf bound_ctrl:1
	v_pk_fma_f32 v[4:5], v[54:55], v[0:1], v[10:11] op_sel_hi:[1,0,1]
	s_waitcnt lgkmcnt(11)
	v_pk_mul_f32 v[6:7], v[62:63], v[4:5]
	v_pk_fma_f32 v[2:3], v[52:53], v[0:1], v[8:9] op_sel_hi:[1,0,1]
	v_pk_fma_f32 v[6:7], v[60:61], v[2:3], v[6:7]
	s_waitcnt lgkmcnt(7)
	v_add_f32_e32 v0, v6, v7
	v_pk_mul_f32 v[6:7], v[58:59], v[4:5]
	v_pk_fma_f32 v[6:7], v[56:57], v[2:3], v[6:7]
	v_add_f32_dpp v0, v0, v0 quad_perm:[1,0,3,2] row_mask:0xf bank_mask:0xf bound_ctrl:1
	v_pk_mul_f32 v[10:11], v[66:67], v[12:13] op_sel:[0,1] op_sel_hi:[1,1]
	v_pk_mul_f32 v[8:9], v[64:65], v[12:13] op_sel:[0,1] op_sel_hi:[1,1]
	v_add_f32_dpp v0, v0, v0 quad_perm:[2,3,0,1] row_mask:0xf bank_mask:0xf bound_ctrl:1
	ds_read_b128 v[40:43], v83 offset:13056
	ds_read_b128 v[44:47], v83 offset:29440
	ds_read_b128 v[48:51], v83 offset:4864
	ds_read_b128 v[52:55], v83 offset:21248
	ds_read_b128 v[56:59], v83 offset:37632
	ds_read_b128 v[16:19], v84 offset:80
	v_add_f32_e32 v6, v6, v7
	ds_write_b32 v85, v6 offset:16384
	v_add_f32_dpp v0, v0, v0 row_half_mirror row_mask:0xf bank_mask:0xf bound_ctrl:1
	v_pk_fma_f32 v[10:11], v[70:71], v[4:5], v[10:11]
	v_pk_fma_f32 v[8:9], v[68:69], v[2:3], v[8:9]
	v_add_f32_dpp v0, v0, v0 row_mirror row_mask:0xf bank_mask:0xf bound_ctrl:1
	v_pk_fma_f32 v[4:5], v[74:75], v[0:1], v[10:11] op_sel_hi:[1,0,1]
	s_waitcnt lgkmcnt(12)
	v_pk_mul_f32 v[6:7], v[22:23], v[4:5]
	v_pk_fma_f32 v[2:3], v[72:73], v[0:1], v[8:9] op_sel_hi:[1,0,1]
	v_pk_fma_f32 v[6:7], v[20:21], v[2:3], v[6:7]
	s_waitcnt lgkmcnt(8)
	v_add_f32_e32 v0, v6, v7
	v_pk_mul_f32 v[6:7], v[78:79], v[4:5]
	v_pk_fma_f32 v[6:7], v[76:77], v[2:3], v[6:7]
	v_add_f32_dpp v0, v0, v0 quad_perm:[1,0,3,2] row_mask:0xf bank_mask:0xf bound_ctrl:1
	v_pk_mul_f32 v[10:11], v[26:27], v[14:15] op_sel_hi:[1,0]
	v_pk_mul_f32 v[8:9], v[24:25], v[14:15] op_sel_hi:[1,0]
	v_add_f32_dpp v0, v0, v0 quad_perm:[2,3,0,1] row_mask:0xf bank_mask:0xf bound_ctrl:1
	ds_read_b128 v[60:63], v83 offset:13312
	ds_read_b128 v[64:67], v83 offset:29696
	ds_read_b128 v[68:71], v83 offset:5120
	ds_read_b128 v[72:75], v83 offset:21504
	ds_read_b128 v[76:79], v83 offset:37888
	v_add_f32_e32 v6, v6, v7
	ds_write_b32 v85, v6 offset:17408
	v_add_f32_dpp v0, v0, v0 row_half_mirror row_mask:0xf bank_mask:0xf bound_ctrl:1
	v_pk_fma_f32 v[10:11], v[30:31], v[4:5], v[10:11]
	v_pk_fma_f32 v[8:9], v[28:29], v[2:3], v[8:9]
	v_add_f32_dpp v0, v0, v0 row_mirror row_mask:0xf bank_mask:0xf bound_ctrl:1
	v_pk_fma_f32 v[4:5], v[34:35], v[0:1], v[10:11] op_sel_hi:[1,0,1]
	s_waitcnt lgkmcnt(12)
; #define LAS __attribute__((address_space(3)))
; __device__ __forceinline__ void phase_rwc(const int wvs, const Params& p, LAS unsigned char* lds, int layer, int wg0) {
;     ...
; #pragma unroll 16
;       for (int t = 0; t < 32; ++t) {
;         const int tn = t + 2;
;         const f32x4 nw4 = *(const LAS f32x4*)(Wv + tn * 64), nkk4 = *(const LAS f32x4*)(Wv + 2048 + tn * 64), nb4 = *(const LAS f32x4*)(Wv + 4096 + tn * 64), nkd4 = *(const LAS f32x4*)(Wv + 6144 + tn * 64), nr4 = *(const LAS f32x4*)(Wv + 8192 + tn * 64);
;         const float nvv = Vv[tn * 16];
;         const f32x4 pa = S * kk4;
;         const f32x4 t1 = S * w4 + vv * kd4;
;         float sa = (pa[0] + pa[2]) + (pa[1] + pa[3]);
;         sa = row16_sum(sa);
;         S = t1 + sa * b4;
;         const f32x4 py = S * r4;
;         ypw[t * 256] = (py[0] + py[2]) + (py[1] + py[3]);
;         w4 = xw4; kk4 = xkk4; b4 = xb4; kd4 = xkd4; r4 = xr4; vv = xvv;
;         xw4 = nw4; xkk4 = nkk4; xb4 = nb4; xkd4 = nkd4; xr4 = nr4; xvv = nvv;
;       }
	v_pk_mul_f32 v[6:7], v[42:43], v[4:5]
	v_pk_fma_f32 v[2:3], v[32:33], v[0:1], v[8:9] op_sel_hi:[1,0,1]
	v_pk_fma_f32 v[6:7], v[40:41], v[2:3], v[6:7]
	s_waitcnt lgkmcnt(8)
	v_add_f32_e32 v0, v6, v7
	v_pk_mul_f32 v[6:7], v[38:39], v[4:5]
	v_pk_fma_f32 v[6:7], v[36:37], v[2:3], v[6:7]
	v_add_f32_dpp v0, v0, v0 quad_perm:[1,0,3,2] row_mask:0xf bank_mask:0xf bound_ctrl:1
	v_pk_mul_f32 v[10:11], v[46:47], v[14:15] op_sel:[0,1] op_sel_hi:[1,1]
	v_pk_mul_f32 v[8:9], v[44:45], v[14:15] op_sel:[0,1] op_sel_hi:[1,1]
	v_add_f32_dpp v0, v0, v0 quad_perm:[2,3,0,1] row_mask:0xf bank_mask:0xf bound_ctrl:1
	ds_read_b128 v[20:23], v83 offset:13568
	ds_read_b128 v[24:27], v83 offset:29952
	ds_read_b128 v[28:31], v83 offset:5376
	ds_read_b128 v[32:35], v83 offset:21760
	ds_read_b128 v[36:39], v83 offset:38144
	v_add_f32_e32 v6, v6, v7
	ds_write_b32 v85, v6 offset:18432
	v_add_f32_dpp v0, v0, v0 row_half_mirror row_mask:0xf bank_mask:0xf bound_ctrl:1
	v_pk_fma_f32 v[10:11], v[50:51], v[4:5], v[10:11]
	v_pk_fma_f32 v[8:9], v[48:49], v[2:3], v[8:9]
	v_add_f32_dpp v0, v0, v0 row_mirror row_mask:0xf bank_mask:0xf bound_ctrl:1
	v_pk_fma_f32 v[4:5], v[54:55], v[0:1], v[10:11] op_sel_hi:[1,0,1]
	s_waitcnt lgkmcnt(11)
	v_pk_mul_f32 v[6:7], v[62:63], v[4:5]
	v_pk_fma_f32 v[2:3], v[52:53], v[0:1], v[8:9] op_sel_hi:[1,0,1]
	v_pk_fma_f32 v[6:7], v[60:61], v[2:3], v[6:7]
	s_waitcnt lgkmcnt(7)
	v_add_f32_e32 v0, v6, v7
	v_pk_mul_f32 v[6:7], v[58:59], v[4:5]
	v_pk_fma_f32 v[6:7], v[56:57], v[2:3], v[6:7]
	v_add_f32_dpp v0, v0, v0 quad_perm:[1,0,3,2] row_mask:0xf bank_mask:0xf bound_ctrl:1
	v_pk_mul_f32 v[10:11], v[66:67], v[16:17] op_sel_hi:[1,0]
	v_pk_mul_f32 v[8:9], v[64:65], v[16:17] op_sel_hi:[1,0]
	v_add_f32_dpp v0, v0, v0 quad_perm:[2,3,0,1] row_mask:0xf bank_mask:0xf bound_ctrl:1
	ds_read_b128 v[40:43], v83 offset:13824
	ds_read_b128 v[44:47], v83 offset:30208
	ds_read_b128 v[48:51], v83 offset:5632
	ds_read_b128 v[52:55], v83 offset:22016
	ds_read_b128 v[56:59], v83 offset:38400
	v_add_f32_e32 v6, v6, v7
	ds_write_b32 v85, v6 offset:19456
	v_add_f32_dpp v0, v0, v0 row_half_mirror row_mask:0xf bank_mask:0xf bound_ctrl:1
	v_pk_fma_f32 v[10:11], v[70:71], v[4:5], v[10:11]
	v_pk_fma_f32 v[8:9], v[68:69], v[2:3], v[8:9]
	v_add_f32_dpp v0, v0, v0 row_mirror row_mask:0xf bank_mask:0xf bound_ctrl:1
	v_pk_fma_f32 v[4:5], v[74:75], v[0:1], v[10:11] op_sel_hi:[1,0,1]
	s_waitcnt lgkmcnt(11)
	v_pk_mul_f32 v[6:7], v[22:23], v[4:5]
	v_pk_fma_f32 v[2:3], v[72:73], v[0:1], v[8:9] op_sel_hi:[1,0,1]
	v_pk_fma_f32 v[6:7], v[20:21], v[2:3], v[6:7]
	s_waitcnt lgkmcnt(7)
	v_add_f32_e32 v0, v6, v7
	v_pk_mul_f32 v[6:7], v[78:79], v[4:5]
	v_pk_fma_f32 v[6:7], v[76:77], v[2:3], v[6:7]
	v_add_f32_dpp v0, v0, v0 quad_perm:[1,0,3,2] row_mask:0xf bank_mask:0xf bound_ctrl:1
	v_pk_mul_f32 v[10:11], v[26:27], v[16:17] op_sel:[0,1] op_sel_hi:[1,1]
	v_pk_mul_f32 v[8:9], v[24:25], v[16:17] op_sel:[0,1] op_sel_hi:[1,1]
	v_add_f32_dpp v0, v0, v0 quad_perm:[2,3,0,1] row_mask:0xf bank_mask:0xf bound_ctrl:1
	ds_read_b128 v[60:63], v83 offset:14080
	ds_read_b128 v[64:67], v83 offset:30464
	ds_read_b128 v[68:71], v83 offset:5888
	ds_read_b128 v[72:75], v83 offset:22272
	ds_read_b128 v[76:79], v83 offset:38656
	ds_read_b128 v[12:15], v84 offset:96
	v_add_f32_e32 v6, v6, v7
	ds_write_b32 v85, v6 offset:20480
	v_add_f32_dpp v0, v0, v0 row_half_mirror row_mask:0xf bank_mask:0xf bound_ctrl:1
	v_pk_fma_f32 v[10:11], v[30:31], v[4:5], v[10:11]
	v_pk_fma_f32 v[8:9], v[28:29], v[2:3], v[8:9]
	v_add_f32_dpp v0, v0, v0 row_mirror row_mask:0xf bank_mask:0xf bound_ctrl:1
	v_pk_fma_f32 v[4:5], v[34:35], v[0:1], v[10:11] op_sel_hi:[1,0,1]
	s_waitcnt lgkmcnt(12)
	v_pk_mul_f32 v[6:7], v[42:43], v[4:5]
	v_pk_fma_f32 v[2:3], v[32:33], v[0:1], v[8:9] op_sel_hi:[1,0,1]
	v_pk_fma_f32 v[6:7], v[40:41], v[2:3], v[6:7]
	s_waitcnt lgkmcnt(8)
	v_add_f32_e32 v0, v6, v7
	v_pk_mul_f32 v[6:7], v[38:39], v[4:5]
	v_pk_fma_f32 v[6:7], v[36:37], v[2:3], v[6:7]
	v_add_f32_dpp v0, v0, v0 quad_perm:[1,0,3,2] row_mask:0xf bank_mask:0xf bound_ctrl:1
	v_pk_mul_f32 v[10:11], v[46:47], v[18:19] op_sel_hi:[1,0]
	v_pk_mul_f32 v[8:9], v[44:45], v[18:19] op_sel_hi:[1,0]
	v_add_f32_dpp v0, v0, v0 quad_perm:[2,3,0,1] row_mask:0xf bank_mask:0xf bound_ctrl:1
	ds_read_b128 v[20:23], v83 offset:14336
	ds_read_b128 v[24:27], v83 offset:30720
	ds_read_b128 v[28:31], v83 offset:6144
	ds_read_b128 v[32:35], v83 offset:22528
	ds_read_b128 v[36:39], v83 offset:38912
	v_add_f32_e32 v6, v6, v7
	ds_write_b32 v85, v6 offset:21504
	v_add_f32_dpp v0, v0, v0 row_half_mirror row_mask:0xf bank_mask:0xf bound_ctrl:1
	v_pk_fma_f32 v[10:11], v[50:51], v[4:5], v[10:11]
	v_pk_fma_f32 v[8:9], v[48:49], v[2:3], v[8:9]
	v_add_f32_dpp v0, v0, v0 row_mirror row_mask:0xf bank_mask:0xf bound_ctrl:1
	v_pk_fma_f32 v[4:5], v[54:55], v[0:1], v[10:11] op_sel_hi:[1,0,1]
	s_waitcnt lgkmcnt(12)
	v_pk_mul_f32 v[6:7], v[62:63], v[4:5]
	v_pk_fma_f32 v[2:3], v[52:53], v[0:1], v[8:9] op_sel_hi:[1,0,1]
	v_pk_fma_f32 v[6:7], v[60:61], v[2:3], v[6:7]
	s_waitcnt lgkmcnt(8)
	v_add_f32_e32 v0, v6, v7
	v_pk_mul_f32 v[6:7], v[58:59], v[4:5]
	v_pk_fma_f32 v[6:7], v[56:57], v[2:3], v[6:7]
	v_add_f32_dpp v0, v0, v0 quad_perm:[1,0,3,2] row_mask:0xf bank_mask:0xf bound_ctrl:1
	v_pk_mul_f32 v[10:11], v[66:67], v[18:19] op_sel:[0,1] op_sel_hi:[1,1]
	v_pk_mul_f32 v[8:9], v[64:65], v[18:19] op_sel:[0,1] op_sel_hi:[1,1]
	v_add_f32_dpp v0, v0, v0 quad_perm:[2,3,0,1] row_mask:0xf bank_mask:0xf bound_ctrl:1
	ds_read_b128 v[40:43], v83 offset:14592
	ds_read_b128 v[44:47], v83 offset:30976
	ds_read_b128 v[48:51], v83 offset:6400
	ds_read_b128 v[52:55], v83 offset:22784
	ds_read_b128 v[56:59], v83 offset:39168
	v_add_f32_e32 v6, v6, v7
	ds_write_b32 v85, v6 offset:22528
	v_add_f32_dpp v0, v0, v0 row_half_mirror row_mask:0xf bank_mask:0xf bound_ctrl:1
	v_pk_fma_f32 v[10:11], v[70:71], v[4:5], v[10:11]
	v_pk_fma_f32 v[8:9], v[68:69], v[2:3], v[8:9]
	v_add_f32_dpp v0, v0, v0 row_mirror row_mask:0xf bank_mask:0xf bound_ctrl:1
	v_pk_fma_f32 v[4:5], v[74:75], v[0:1], v[10:11] op_sel_hi:[1,0,1]
	s_waitcnt lgkmcnt(11)
; #define LAS __attribute__((address_space(3)))
; __device__ __forceinline__ void phase_rwc(const int wvs, const Params& p, LAS unsigned char* lds, int layer, int wg0) {
;     ...
; #pragma unroll 16
;       for (int t = 0; t < 32; ++t) {
;         const int tn = t + 2;
;         const f32x4 nw4 = *(const LAS f32x4*)(Wv + tn * 64), nkk4 = *(const LAS f32x4*)(Wv + 2048 + tn * 64), nb4 = *(const LAS f32x4*)(Wv + 4096 + tn * 64), nkd4 = *(const LAS f32x4*)(Wv + 6144 + tn * 64), nr4 = *(const LAS f32x4*)(Wv + 8192 + tn * 64);
;         const float nvv = Vv[tn * 16];
;         const f32x4 pa = S * kk4;
;         const f32x4 t1 = S * w4 + vv * kd4;
;         float sa = (pa[0] + pa[2]) + (pa[1] + pa[3]);
;         sa = row16_sum(sa);
;         S = t1 + sa * b4;
;         const f32x4 py = S * r4;
;         ypw[t * 256] = (py[0] + py[2]) + (py[1] + py[3]);
;         w4 = xw4; kk4 = xkk4; b4 = xb4; kd4 = xkd4; r4 = xr4; vv = xvv;
;         xw4 = nw4; xkk4 = nkk4; xb4 = nb4; xkd4 = nkd4; xr4 = nr4; xvv = nvv;
;       }
	v_pk_mul_f32 v[6:7], v[22:23], v[4:5]
	v_pk_fma_f32 v[2:3], v[72:73], v[0:1], v[8:9] op_sel_hi:[1,0,1]
	v_pk_fma_f32 v[6:7], v[20:21], v[2:3], v[6:7]
	s_waitcnt lgkmcnt(7)
	v_add_f32_e32 v0, v6, v7
	v_pk_mul_f32 v[6:7], v[78:79], v[4:5]
	v_pk_fma_f32 v[6:7], v[76:77], v[2:3], v[6:7]
	v_add_f32_dpp v0, v0, v0 quad_perm:[1,0,3,2] row_mask:0xf bank_mask:0xf bound_ctrl:1
	v_pk_mul_f32 v[10:11], v[26:27], v[12:13] op_sel_hi:[1,0]
	v_pk_mul_f32 v[8:9], v[24:25], v[12:13] op_sel_hi:[1,0]
	v_add_f32_dpp v0, v0, v0 quad_perm:[2,3,0,1] row_mask:0xf bank_mask:0xf bound_ctrl:1
	ds_read_b128 v[60:63], v83 offset:14848
	ds_read_b128 v[64:67], v83 offset:31232
	ds_read_b128 v[68:71], v83 offset:6656
	ds_read_b128 v[72:75], v83 offset:23040
	ds_read_b128 v[76:79], v83 offset:39424
	v_add_f32_e32 v6, v6, v7
	ds_write_b32 v85, v6 offset:23552
	v_add_f32_dpp v0, v0, v0 row_half_mirror row_mask:0xf bank_mask:0xf bound_ctrl:1
	v_pk_fma_f32 v[10:11], v[30:31], v[4:5], v[10:11]
	v_pk_fma_f32 v[8:9], v[28:29], v[2:3], v[8:9]
	v_add_f32_dpp v0, v0, v0 row_mirror row_mask:0xf bank_mask:0xf bound_ctrl:1
	v_pk_fma_f32 v[4:5], v[34:35], v[0:1], v[10:11] op_sel_hi:[1,0,1]
	s_waitcnt lgkmcnt(11)
	v_pk_mul_f32 v[6:7], v[42:43], v[4:5]
	v_pk_fma_f32 v[2:3], v[32:33], v[0:1], v[8:9] op_sel_hi:[1,0,1]
	v_pk_fma_f32 v[6:7], v[40:41], v[2:3], v[6:7]
	s_waitcnt lgkmcnt(7)
	v_add_f32_e32 v0, v6, v7
	v_pk_mul_f32 v[6:7], v[38:39], v[4:5]
	v_pk_fma_f32 v[6:7], v[36:37], v[2:3], v[6:7]
	v_add_f32_dpp v0, v0, v0 quad_perm:[1,0,3,2] row_mask:0xf bank_mask:0xf bound_ctrl:1
	v_pk_mul_f32 v[10:11], v[46:47], v[12:13] op_sel:[0,1] op_sel_hi:[1,1]
	v_pk_mul_f32 v[8:9], v[44:45], v[12:13] op_sel:[0,1] op_sel_hi:[1,1]
	v_add_f32_dpp v0, v0, v0 quad_perm:[2,3,0,1] row_mask:0xf bank_mask:0xf bound_ctrl:1
	ds_read_b128 v[20:23], v83 offset:15104
	ds_read_b128 v[24:27], v83 offset:31488
	ds_read_b128 v[28:31], v83 offset:6912
	ds_read_b128 v[32:35], v83 offset:23296
	ds_read_b128 v[36:39], v83 offset:39680
	ds_read_b128 v[16:19], v84 offset:112
	v_add_f32_e32 v6, v6, v7
	ds_write_b32 v85, v6 offset:24576
	v_add_f32_dpp v0, v0, v0 row_half_mirror row_mask:0xf bank_mask:0xf bound_ctrl:1
	v_pk_fma_f32 v[10:11], v[50:51], v[4:5], v[10:11]
	v_pk_fma_f32 v[8:9], v[48:49], v[2:3], v[8:9]
	v_add_f32_dpp v0, v0, v0 row_mirror row_mask:0xf bank_mask:0xf bound_ctrl:1
	v_pk_fma_f32 v[4:5], v[54:55], v[0:1], v[10:11] op_sel_hi:[1,0,1]
	s_waitcnt lgkmcnt(12)
	v_pk_mul_f32 v[6:7], v[62:63], v[4:5]
	v_pk_fma_f32 v[2:3], v[52:53], v[0:1], v[8:9] op_sel_hi:[1,0,1]
	v_pk_fma_f32 v[6:7], v[60:61], v[2:3], v[6:7]
	s_waitcnt lgkmcnt(8)
	v_add_f32_e32 v0, v6, v7
	v_pk_mul_f32 v[6:7], v[58:59], v[4:5]
	v_pk_fma_f32 v[6:7], v[56:57], v[2:3], v[6:7]
	v_add_f32_dpp v0, v0, v0 quad_perm:[1,0,3,2] row_mask:0xf bank_mask:0xf bound_ctrl:1
	v_pk_mul_f32 v[10:11], v[66:67], v[14:15] op_sel_hi:[1,0]
	v_pk_mul_f32 v[8:9], v[64:65], v[14:15] op_sel_hi:[1,0]
	v_add_f32_dpp v0, v0, v0 quad_perm:[2,3,0,1] row_mask:0xf bank_mask:0xf bound_ctrl:1
	ds_read_b128 v[40:43], v83 offset:15360
	ds_read_b128 v[44:47], v83 offset:31744
	ds_read_b128 v[48:51], v83 offset:7168
	ds_read_b128 v[52:55], v83 offset:23552
	ds_read_b128 v[56:59], v83 offset:39936
	v_add_f32_e32 v6, v6, v7
	ds_write_b32 v85, v6 offset:25600
	v_add_f32_dpp v0, v0, v0 row_half_mirror row_mask:0xf bank_mask:0xf bound_ctrl:1
	v_pk_fma_f32 v[10:11], v[70:71], v[4:5], v[10:11]
	v_pk_fma_f32 v[8:9], v[68:69], v[2:3], v[8:9]
	v_add_f32_dpp v0, v0, v0 row_mirror row_mask:0xf bank_mask:0xf bound_ctrl:1
	v_pk_fma_f32 v[4:5], v[74:75], v[0:1], v[10:11] op_sel_hi:[1,0,1]
	s_waitcnt lgkmcnt(12)
	v_pk_mul_f32 v[6:7], v[22:23], v[4:5]
	v_pk_fma_f32 v[2:3], v[72:73], v[0:1], v[8:9] op_sel_hi:[1,0,1]
	v_pk_fma_f32 v[6:7], v[20:21], v[2:3], v[6:7]
	s_waitcnt lgkmcnt(8)
	v_add_f32_e32 v0, v6, v7
	v_pk_mul_f32 v[6:7], v[78:79], v[4:5]
	v_pk_fma_f32 v[6:7], v[76:77], v[2:3], v[6:7]
	v_add_f32_dpp v0, v0, v0 quad_perm:[1,0,3,2] row_mask:0xf bank_mask:0xf bound_ctrl:1
	v_pk_mul_f32 v[10:11], v[26:27], v[14:15] op_sel:[0,1] op_sel_hi:[1,1]
	v_pk_mul_f32 v[8:9], v[24:25], v[14:15] op_sel:[0,1] op_sel_hi:[1,1]
	v_add_f32_dpp v0, v0, v0 quad_perm:[2,3,0,1] row_mask:0xf bank_mask:0xf bound_ctrl:1
	ds_read_b128 v[60:63], v83 offset:15616
	ds_read_b128 v[64:67], v83 offset:32000
	ds_read_b128 v[68:71], v83 offset:7424
	ds_read_b128 v[72:75], v83 offset:23808
	ds_read_b128 v[76:79], v83 offset:40192
	v_add_f32_e32 v6, v6, v7
	ds_write_b32 v85, v6 offset:26624
	v_add_f32_dpp v0, v0, v0 row_half_mirror row_mask:0xf bank_mask:0xf bound_ctrl:1
	v_pk_fma_f32 v[10:11], v[30:31], v[4:5], v[10:11]
	v_pk_fma_f32 v[8:9], v[28:29], v[2:3], v[8:9]
	v_add_f32_dpp v0, v0, v0 row_mirror row_mask:0xf bank_mask:0xf bound_ctrl:1
	v_pk_fma_f32 v[4:5], v[34:35], v[0:1], v[10:11] op_sel_hi:[1,0,1]
	s_waitcnt lgkmcnt(11)
; #define LAS __attribute__((address_space(3)))
; __device__ __forceinline__ void phase_rwc(const int wvs, const Params& p, LAS unsigned char* lds, int layer, int wg0) {
;     ...
; #pragma unroll 16
;       for (int t = 0; t < 32; ++t) {
;         const int tn = t + 2;
;         const f32x4 nw4 = *(const LAS f32x4*)(Wv + tn * 64), nkk4 = *(const LAS f32x4*)(Wv + 2048 + tn * 64), nb4 = *(const LAS f32x4*)(Wv + 4096 + tn * 64), nkd4 = *(const LAS f32x4*)(Wv + 6144 + tn * 64), nr4 = *(const LAS f32x4*)(Wv + 8192 + tn * 64);
;         const float nvv = Vv[tn * 16];
;         const f32x4 pa = S * kk4;
;         const f32x4 t1 = S * w4 + vv * kd4;
;         float sa = (pa[0] + pa[2]) + (pa[1] + pa[3]);
;         sa = row16_sum(sa);
;         S = t1 + sa * b4;
;         const f32x4 py = S * r4;
;         ypw[t * 256] = (py[0] + py[2]) + (py[1] + py[3]);
;         w4 = xw4; kk4 = xkk4; b4 = xb4; kd4 = xkd4; r4 = xr4; vv = xvv;
;         xw4 = nw4; xkk4 = nkk4; xb4 = nb4; xkd4 = nkd4; xr4 = nr4; xvv = nvv;
;       }
;       __syncthreads();
	v_pk_mul_f32 v[6:7], v[42:43], v[4:5]
	v_pk_fma_f32 v[2:3], v[32:33], v[0:1], v[8:9] op_sel_hi:[1,0,1]
	v_pk_fma_f32 v[6:7], v[40:41], v[2:3], v[6:7]
	s_waitcnt lgkmcnt(7)
	v_add_f32_e32 v0, v6, v7
	v_pk_mul_f32 v[6:7], v[38:39], v[4:5]
	v_pk_fma_f32 v[6:7], v[36:37], v[2:3], v[6:7]
	v_add_f32_dpp v0, v0, v0 quad_perm:[1,0,3,2] row_mask:0xf bank_mask:0xf bound_ctrl:1
	v_pk_mul_f32 v[10:11], v[46:47], v[16:17] op_sel_hi:[1,0]
	v_pk_mul_f32 v[8:9], v[44:45], v[16:17] op_sel_hi:[1,0]
	v_add_f32_dpp v0, v0, v0 quad_perm:[2,3,0,1] row_mask:0xf bank_mask:0xf bound_ctrl:1
	ds_read_b128 v[20:23], v83 offset:15872
	ds_read_b128 v[24:27], v83 offset:32256
	ds_read_b128 v[28:31], v83 offset:7680
	ds_read_b128 v[32:35], v83 offset:24064
	ds_read_b128 v[36:39], v83 offset:40448
	v_add_f32_e32 v6, v6, v7
	ds_write_b32 v85, v6 offset:27648
	v_add_f32_dpp v0, v0, v0 row_half_mirror row_mask:0xf bank_mask:0xf bound_ctrl:1
	v_pk_fma_f32 v[10:11], v[50:51], v[4:5], v[10:11]
	v_pk_fma_f32 v[8:9], v[48:49], v[2:3], v[8:9]
	v_add_f32_dpp v0, v0, v0 row_mirror row_mask:0xf bank_mask:0xf bound_ctrl:1
	v_pk_fma_f32 v[4:5], v[54:55], v[0:1], v[10:11] op_sel_hi:[1,0,1]
	s_waitcnt lgkmcnt(11)
	v_pk_mul_f32 v[6:7], v[62:63], v[4:5]
	v_pk_fma_f32 v[2:3], v[52:53], v[0:1], v[8:9] op_sel_hi:[1,0,1]
	v_pk_fma_f32 v[6:7], v[60:61], v[2:3], v[6:7]
	s_waitcnt lgkmcnt(7)
	v_add_f32_e32 v0, v6, v7
	v_pk_mul_f32 v[6:7], v[58:59], v[4:5]
	v_pk_fma_f32 v[6:7], v[56:57], v[2:3], v[6:7]
	v_add_f32_dpp v0, v0, v0 quad_perm:[1,0,3,2] row_mask:0xf bank_mask:0xf bound_ctrl:1
	v_pk_mul_f32 v[10:11], v[66:67], v[16:17] op_sel:[0,1] op_sel_hi:[1,1]
	v_pk_mul_f32 v[8:9], v[64:65], v[16:17] op_sel:[0,1] op_sel_hi:[1,1]
	v_add_f32_dpp v0, v0, v0 quad_perm:[2,3,0,1] row_mask:0xf bank_mask:0xf bound_ctrl:1
	ds_read_b128 v[40:43], v83 offset:16128
	ds_read_b128 v[44:47], v83 offset:32512
	ds_read_b128 v[48:51], v83 offset:7936
	ds_read_b128 v[52:55], v83 offset:24320
	ds_read_b128 v[56:59], v83 offset:40704
	v_add_f32_e32 v6, v6, v7
	ds_write_b32 v85, v6 offset:28672
	v_add_f32_dpp v0, v0, v0 row_half_mirror row_mask:0xf bank_mask:0xf bound_ctrl:1
	v_pk_fma_f32 v[10:11], v[70:71], v[4:5], v[10:11]
	v_pk_fma_f32 v[8:9], v[68:69], v[2:3], v[8:9]
	v_add_f32_dpp v0, v0, v0 row_mirror row_mask:0xf bank_mask:0xf bound_ctrl:1
	v_pk_fma_f32 v[4:5], v[74:75], v[0:1], v[10:11] op_sel_hi:[1,0,1]
	s_waitcnt lgkmcnt(11)
	v_pk_mul_f32 v[6:7], v[22:23], v[4:5]
	v_pk_fma_f32 v[2:3], v[72:73], v[0:1], v[8:9] op_sel_hi:[1,0,1]
	v_pk_fma_f32 v[6:7], v[20:21], v[2:3], v[6:7]
	s_waitcnt lgkmcnt(7)
	v_add_f32_e32 v0, v6, v7
	v_pk_mul_f32 v[6:7], v[78:79], v[4:5]
	v_pk_fma_f32 v[6:7], v[76:77], v[2:3], v[6:7]
	v_add_f32_dpp v0, v0, v0 quad_perm:[1,0,3,2] row_mask:0xf bank_mask:0xf bound_ctrl:1
	v_pk_mul_f32 v[10:11], v[26:27], v[18:19] op_sel_hi:[1,0]
	v_pk_mul_f32 v[8:9], v[24:25], v[18:19] op_sel_hi:[1,0]
	v_add_f32_dpp v0, v0, v0 quad_perm:[2,3,0,1] row_mask:0xf bank_mask:0xf bound_ctrl:1
	v_add_f32_e32 v6, v6, v7
	ds_write_b32 v85, v6 offset:29696
	v_add_f32_dpp v0, v0, v0 row_half_mirror row_mask:0xf bank_mask:0xf bound_ctrl:1
	v_pk_fma_f32 v[10:11], v[30:31], v[4:5], v[10:11]
	v_pk_fma_f32 v[8:9], v[28:29], v[2:3], v[8:9]
	v_add_f32_dpp v0, v0, v0 row_mirror row_mask:0xf bank_mask:0xf bound_ctrl:1
	v_pk_fma_f32 v[4:5], v[34:35], v[0:1], v[10:11] op_sel_hi:[1,0,1]
	s_waitcnt lgkmcnt(6)
	v_pk_mul_f32 v[6:7], v[42:43], v[4:5]
	v_pk_fma_f32 v[2:3], v[32:33], v[0:1], v[8:9] op_sel_hi:[1,0,1]
	v_pk_fma_f32 v[6:7], v[40:41], v[2:3], v[6:7]
	s_waitcnt lgkmcnt(2)
	v_add_f32_e32 v0, v6, v7
	v_pk_mul_f32 v[6:7], v[38:39], v[4:5]
	v_pk_fma_f32 v[6:7], v[36:37], v[2:3], v[6:7]
	v_add_f32_dpp v0, v0, v0 quad_perm:[1,0,3,2] row_mask:0xf bank_mask:0xf bound_ctrl:1
	v_pk_mul_f32 v[10:11], v[46:47], v[18:19] op_sel:[0,1] op_sel_hi:[1,1]
	v_pk_mul_f32 v[8:9], v[44:45], v[18:19] op_sel:[0,1] op_sel_hi:[1,1]
	v_add_f32_dpp v0, v0, v0 quad_perm:[2,3,0,1] row_mask:0xf bank_mask:0xf bound_ctrl:1
	v_add_f32_e32 v6, v6, v7
	ds_write_b32 v85, v6 offset:30720
	v_add_f32_dpp v0, v0, v0 row_half_mirror row_mask:0xf bank_mask:0xf bound_ctrl:1
	v_pk_fma_f32 v[10:11], v[50:51], v[4:5], v[10:11]
	v_pk_fma_f32 v[8:9], v[48:49], v[2:3], v[8:9]
	v_add_f32_dpp v0, v0, v0 row_mirror row_mask:0xf bank_mask:0xf bound_ctrl:1
	v_pk_fma_f32 v[4:5], v[54:55], v[0:1], v[10:11] op_sel_hi:[1,0,1]
	v_pk_fma_f32 v[2:3], v[52:53], v[0:1], v[8:9] op_sel_hi:[1,0,1]
	v_pk_mul_f32 v[6:7], v[58:59], v[4:5]
	v_pk_fma_f32 v[6:7], v[56:57], v[2:3], v[6:7]
	s_nop 0
	v_add_f32_e32 v6, v6, v7
	ds_write_b32 v85, v6 offset:31744
	s_add_i32 s8, s8, 2
	s_cmpk_eq_i32 s8, 0x88
	s_waitcnt lgkmcnt(0)
	s_barrier
	s_cbranch_scc0 .Lrwc_scan

; __device__ __forceinline__ void phase_rwc(const int wvs, const Params& p, LAS unsigned char* lds, int layer, int wg0) {
;     ...
;     RW_LOAD(0) RW_DERIVE(0) RW_LOAD(1)
.LBB0_1275:
	v_ashrrev_i32_e32 v11, 31, v10
	v_lshl_add_u64 v[10:11], s[16:17], 0, v[10:11]
	v_mov_b64_e32 v[32:33], s[24:25]
	v_mad_u64_u32 v[32:33], s[44:45], v10, s68, v[32:33]
	v_mov_b32_e32 v10, v33
	v_mad_u64_u32 v[10:11], s[44:45], v11, s68, v[10:11]
	v_mov_b32_e32 v33, v10
	v_lshl_add_u64 v[10:11], s[12:13], 1, v[32:33]
	s_lshl_b32 s44, s48, 5
	s_mov_b32 s45, s31
	v_lshl_add_u64 v[32:33], v[10:11], 0, s[44:45]
	v_lshlrev_b32_e32 v10, 1, v25
	v_and_b32_e32 v58, 14, v10
	v_lshlrev_b32_e32 v10, 1, v58
	v_mov_b32_e32 v11, v1
	v_lshl_add_u64 v[32:33], v[32:33], 0, v[10:11]
	global_load_dword v11, v[32:33], off offset:1536
	s_waitcnt vmcnt(8)
	v_cvt_f32_f16_e32 v32, v26
	v_cvt_f32_f16_sdwa v26, v26 dst_sel:DWORD dst_unused:UNUSED_PAD src0_sel:WORD_1
	v_cvt_f32_f16_sdwa v41, v22 dst_sel:DWORD dst_unused:UNUSED_PAD src0_sel:WORD_1
	v_cvt_f32_f16_e32 v40, v22
	v_cvt_f32_f16_sdwa v37, v28 dst_sel:DWORD dst_unused:UNUSED_PAD src0_sel:WORD_1
	v_mul_f32_e32 v22, 0xbfb8aa3b, v26
	v_cvt_f32_f16_e32 v36, v28
	v_exp_f32_e32 v33, v22
	v_cvt_f32_f16_e32 v22, v27
	v_cvt_f32_f16_sdwa v26, v27 dst_sel:DWORD dst_unused:UNUSED_PAD src0_sel:WORD_1
	v_cvt_f32_f16_sdwa v51, v29 dst_sel:DWORD dst_unused:UNUSED_PAD src0_sel:WORD_1
	v_cvt_f32_f16_e32 v50, v29
	s_waitcnt vmcnt(7)
	v_cvt_f32_f16_sdwa v49, v30 dst_sel:DWORD dst_unused:UNUSED_PAD src0_sel:WORD_1
	v_cvt_f32_f16_e32 v48, v30
	v_cvt_f32_f16_sdwa v57, v31 dst_sel:DWORD dst_unused:UNUSED_PAD src0_sel:WORD_1
	v_cvt_f32_f16_e32 v56, v31
	v_pk_mul_f32 v[34:35], v[2:3], v[36:37]
	v_mul_f32_e32 v22, 0xbfb8aa3b, v22
	s_waitcnt vmcnt(6)
	v_pk_mul_f32 v[44:45], v[24:25], v[34:35] op_sel_hi:[0,1]
	v_exp_f32_e32 v34, v22
	v_mul_f32_e32 v22, 0xbfb8aa3b, v26
	v_cvt_f32_f16_sdwa v43, v23 dst_sel:DWORD dst_unused:UNUSED_PAD src0_sel:WORD_1
	v_cvt_f32_f16_e32 v42, v23
	v_exp_f32_e32 v35, v22
	v_pk_mul_f32 v[22:23], v[4:5], v[50:51]
	v_mul_f32_e32 v28, 0xbfb8aa3b, v32
	v_pk_mul_f32 v[46:47], v[24:25], v[22:23] op_sel_hi:[0,1]
	v_xor_b32_e32 v22, 0x80000000, v48
	v_xor_b32_e32 v23, 0x80000000, v49
	v_xor_b32_e32 v26, 0x80000000, v56
	v_xor_b32_e32 v27, 0x80000000, v57
	v_exp_f32_e32 v32, v28
	v_pk_mul_f32 v[28:29], v[46:47], v[26:27]
	v_pk_mul_f32 v[26:27], v[44:45], v[22:23]
	v_pk_add_f32 v[22:23], v[48:49], -1.0 op_sel_hi:[1,0]
	v_lshlrev_b32_e32 v55, 2, v39
	v_pk_fma_f32 v[22:23], v[6:7], v[22:23], 1.0 op_sel_hi:[1,1,0]
	v_pk_add_f32 v[30:31], v[56:57], -1.0 op_sel_hi:[1,0]
	v_pk_mul_f32 v[48:49], v[22:23], v[36:37]
	s_waitcnt vmcnt(3)
	v_cvt_f32_f16_e32 v23, v14
	v_cvt_f32_f16_sdwa v14, v14 dst_sel:DWORD dst_unused:UNUSED_PAD src0_sel:WORD_1
	v_and_b32_e32 v22, 0xffffffc0, v55
	v_pk_fma_f32 v[30:31], v[8:9], v[30:31], 1.0 op_sel_hi:[1,1,0]
	v_lshlrev_b32_e32 v22, 2, v22
	v_pk_mul_f32 v[50:51], v[30:31], v[50:51]
	v_add3_u32 v55, 0, v38, v22
	v_cvt_f32_f16_sdwa v31, v12 dst_sel:DWORD dst_unused:UNUSED_PAD src0_sel:WORD_1
	v_cvt_f32_f16_e32 v30, v12
	v_mul_f32_e32 v12, 0xbfb8aa3b, v14
	ds_write_b128 v55, v[32:35]
	ds_write_b128 v55, v[44:47] offset:8192
	ds_write_b128 v55, v[26:29] offset:16384
	ds_write_b128 v55, v[48:51] offset:24576
	ds_write_b128 v55, v[40:43] offset:32768
	v_cvt_f32_f16_sdwa v41, v18 dst_sel:DWORD dst_unused:UNUSED_PAD src0_sel:WORD_1
	v_cvt_f32_f16_e32 v40, v18
	v_exp_f32_e32 v27, v12
	v_cvt_f32_f16_e32 v12, v15
	v_cvt_f32_f16_sdwa v14, v15 dst_sel:DWORD dst_unused:UNUSED_PAD src0_sel:WORD_1
	v_mul_f32_e32 v18, 0xbfb8aa3b, v23
	v_cvt_f32_f16_sdwa v45, v19 dst_sel:DWORD dst_unused:UNUSED_PAD src0_sel:WORD_1
	v_cvt_f32_f16_e32 v44, v19
	s_waitcnt vmcnt(2)
	v_cvt_f32_f16_sdwa v43, v20 dst_sel:DWORD dst_unused:UNUSED_PAD src0_sel:WORD_1
	v_cvt_f32_f16_e32 v42, v20
	v_exp_f32_e32 v26, v18
	v_pk_mul_f32 v[28:29], v[2:3], v[40:41]
	v_cvt_f32_f16_sdwa v19, v21 dst_sel:DWORD dst_unused:UNUSED_PAD src0_sel:WORD_1
	v_cvt_f32_f16_e32 v18, v21
	v_mul_f32_e32 v12, 0xbfb8aa3b, v12
	s_waitcnt vmcnt(1)
	v_pk_mul_f32 v[34:35], v[16:17], v[28:29] op_sel_hi:[0,1]
	v_exp_f32_e32 v28, v12
	v_mul_f32_e32 v12, 0xbfb8aa3b, v14
	v_exp_f32_e32 v29, v12
	v_cvt_f32_f16_sdwa v33, v13 dst_sel:DWORD dst_unused:UNUSED_PAD src0_sel:WORD_1
	v_cvt_f32_f16_e32 v32, v13
	v_pk_mul_f32 v[12:13], v[4:5], v[44:45]
	v_xor_b32_e32 v14, 0x80000000, v18
	v_pk_mul_f32 v[36:37], v[16:17], v[12:13] op_sel_hi:[0,1]
	v_xor_b32_e32 v12, 0x80000000, v42
	v_xor_b32_e32 v13, 0x80000000, v43
	v_xor_b32_e32 v15, 0x80000000, v19
	v_pk_add_f32 v[20:21], v[42:43], -1.0 op_sel_hi:[1,0]
	v_pk_add_f32 v[18:19], v[18:19], -1.0 op_sel_hi:[1,0]
	v_pk_mul_f32 v[12:13], v[34:35], v[12:13]
	v_pk_fma_f32 v[18:19], v[8:9], v[18:19], 1.0 op_sel_hi:[1,1,0]
	v_pk_fma_f32 v[42:43], v[6:7], v[20:21], 1.0 op_sel_hi:[1,1,0]
	v_pk_mul_f32 v[14:15], v[36:37], v[14:15]
	v_pk_mul_f32 v[20:21], v[18:19], v[44:45]
	v_pk_mul_f32 v[18:19], v[42:43], v[40:41]
	ds_write_b128 v55, v[26:29] offset:4096
	ds_write_b128 v55, v[34:37] offset:12288
	ds_write_b128 v55, v[12:15] offset:20480
	ds_write_b128 v55, v[18:21] offset:28672
	s_waitcnt vmcnt(0)
	v_cvt_f32_f16_e32 v12, v11
	v_cvt_f32_f16_sdwa v13, v11 dst_sel:DWORD dst_unused:UNUSED_PAD src0_sel:WORD_1
	v_lshl_or_b32 v14, v58, 5, v54
	v_lshl_add_u32 v56, v14, 2, 0
	v_add_u32_e32 v56, 0xa000, v56
	s_mov_b64 s[44:45], -1
	s_and_b64 vcc, exec, s[22:23]
	ds_write_b128 v55, v[30:33] offset:36864
	ds_write2_b32 v56, v12, v13 offset1:32
	s_cbranch_vccz .LBB0_1281
	s_movk_i32 s2, 0xdff
	v_cmp_lt_u32_e32 vcc, s2, v39
	s_and_saveexec_b64 s[44:45], vcc
	s_xor_b64 s[44:45], exec, s[44:45]
	v_sub_u32_e32 v12, 0x11df, v52
	s_andn2_saveexec_b64 s[44:45], s[44:45]
	v_sub_u32_e32 v12, 0xdf, v52
	s_or_b64 exec, exec, s[44:45]
	s_mov_b64 s[44:45], 0

; __device__ __forceinline__ void phase_rwc(const int wvs, const Params& p, LAS unsigned char* lds, int layer, int wg0) {
;     ...
;     RW_LOAD(0) RW_DERIVE(0) RW_LOAD(1)
;     __syncthreads();
; #pragma unroll 2
;     for (int blk = 0; blk < NBLK; ++blk) {
;       if (blk + 1 < NBLK) RW_DERIVE((blk + 1) & 1)
;       if (blk + 2 < NBLK) RW_LOAD(blk + 2)
.LBB0_1302:
	s_waitcnt vmcnt(9)
	v_cvt_f32_f16_sdwa v21, v28 dst_sel:DWORD dst_unused:UNUSED_PAD src0_sel:WORD_1
	v_cvt_f32_f16_e32 v20, v28
	s_waitcnt vmcnt(7)
	v_cvt_f32_f16_sdwa v51, v36 dst_sel:DWORD dst_unused:UNUSED_PAD src0_sel:WORD_1
	v_cvt_f32_f16_e32 v50, v36
	v_cvt_f32_f16_sdwa v69, v37 dst_sel:DWORD dst_unused:UNUSED_PAD src0_sel:WORD_1
	v_pk_mul_f32 v[12:13], v[2:3], v[20:21]
	v_cvt_f32_f16_e32 v68, v37
	v_cvt_f32_f16_e32 v10, v32
	v_cvt_f32_f16_sdwa v11, v32 dst_sel:DWORD dst_unused:UNUSED_PAD src0_sel:WORD_1
	s_waitcnt vmcnt(1)
	v_pk_mul_f32 v[14:15], v[12:13], v[34:35] op_sel_hi:[1,0]
	v_cvt_f32_f16_e32 v12, v33
	v_cvt_f32_f16_sdwa v13, v33 dst_sel:DWORD dst_unused:UNUSED_PAD src0_sel:WORD_1
	v_cvt_f32_f16_sdwa v67, v29 dst_sel:DWORD dst_unused:UNUSED_PAD src0_sel:WORD_1
	v_cvt_f32_f16_e32 v66, v29
	v_xor_b32_e32 v22, 0x80000000, v50
	v_xor_b32_e32 v23, 0x80000000, v51
	v_xor_b32_e32 v24, 0x80000000, v68
	v_xor_b32_e32 v25, 0x80000000, v69
	v_pk_add_f32 v[50:51], v[50:51], -1.0 op_sel_hi:[1,0]
	v_pk_add_f32 v[68:69], v[68:69], -1.0 op_sel_hi:[1,0]
	v_mul_f32_e32 v10, 0xbfb8aa3b, v10
	v_mul_f32_e32 v11, 0xbfb8aa3b, v11
	v_mul_f32_e32 v12, 0xbfb8aa3b, v12
	v_mul_f32_e32 v13, 0xbfb8aa3b, v13
	v_pk_fma_f32 v[68:69], v[8:9], v[68:69], 1.0 op_sel_hi:[1,1,0]
	v_pk_fma_f32 v[50:51], v[6:7], v[50:51], 1.0 op_sel_hi:[1,1,0]
	v_exp_f32_e32 v10, v10
	v_exp_f32_e32 v11, v11
	v_cvt_f32_f16_sdwa v19, v30 dst_sel:DWORD dst_unused:UNUSED_PAD src0_sel:WORD_1
	v_cvt_f32_f16_e32 v18, v30
	v_exp_f32_e32 v12, v12
	v_exp_f32_e32 v13, v13
	v_pk_mul_f32 v[16:17], v[4:5], v[66:67]
	v_pk_mul_f32 v[68:69], v[68:69], v[66:67]
	v_pk_mul_f32 v[66:67], v[50:51], v[20:21]
	v_cvt_f32_f16_sdwa v21, v31 dst_sel:DWORD dst_unused:UNUSED_PAD src0_sel:WORD_1
	v_cvt_f32_f16_e32 v20, v31
	v_pk_mul_f32 v[16:17], v[16:17], v[34:35] op_sel_hi:[1,0]
	v_pk_mul_f32 v[22:23], v[14:15], v[22:23]
	v_pk_mul_f32 v[24:25], v[16:17], v[24:25]
	ds_write_b128 v55, v[10:13] offset:43008
	ds_write_b128 v55, v[14:17] offset:51200
	ds_write_b128 v55, v[22:25] offset:59392
	ds_write_b128 v60, v[18:21]
	v_cvt_f32_f16_sdwa v21, v42 dst_sel:DWORD dst_unused:UNUSED_PAD src0_sel:WORD_1
	v_cvt_f32_f16_e32 v20, v42
	v_cvt_f32_f16_e32 v10, v46
	v_cvt_f32_f16_sdwa v11, v46 dst_sel:DWORD dst_unused:UNUSED_PAD src0_sel:WORD_1
	ds_write_b128 v59, v[66:69]
	v_pk_mul_f32 v[12:13], v[2:3], v[20:21]
	v_cvt_f32_f16_sdwa v51, v48 dst_sel:DWORD dst_unused:UNUSED_PAD src0_sel:WORD_1
	v_pk_mul_f32 v[14:15], v[12:13], v[34:35] op_sel:[0,1]
	v_cvt_f32_f16_e32 v12, v47
	v_cvt_f32_f16_sdwa v13, v47 dst_sel:DWORD dst_unused:UNUSED_PAD src0_sel:WORD_1
	v_cvt_f32_f16_e32 v50, v48
	v_cvt_f32_f16_sdwa v69, v49 dst_sel:DWORD dst_unused:UNUSED_PAD src0_sel:WORD_1
	v_cvt_f32_f16_e32 v68, v49
	v_cvt_f32_f16_sdwa v67, v43 dst_sel:DWORD dst_unused:UNUSED_PAD src0_sel:WORD_1
	v_cvt_f32_f16_e32 v66, v43
	v_mul_f32_e32 v10, 0xbfb8aa3b, v10
	v_mul_f32_e32 v11, 0xbfb8aa3b, v11
	v_mul_f32_e32 v12, 0xbfb8aa3b, v12
	v_mul_f32_e32 v13, 0xbfb8aa3b, v13
	v_exp_f32_e32 v10, v10
	v_exp_f32_e32 v11, v11
	v_exp_f32_e32 v12, v12
	v_exp_f32_e32 v13, v13
	v_xor_b32_e32 v22, 0x80000000, v50
	v_xor_b32_e32 v23, 0x80000000, v51
	v_xor_b32_e32 v24, 0x80000000, v68
	v_xor_b32_e32 v25, 0x80000000, v69
	v_pk_add_f32 v[50:51], v[50:51], -1.0 op_sel_hi:[1,0]
	v_pk_add_f32 v[68:69], v[68:69], -1.0 op_sel_hi:[1,0]
	v_pk_mul_f32 v[16:17], v[4:5], v[66:67]
	v_pk_fma_f32 v[68:69], v[8:9], v[68:69], 1.0 op_sel_hi:[1,1,0]
	v_pk_fma_f32 v[50:51], v[6:7], v[50:51], 1.0 op_sel_hi:[1,1,0]
	s_cmpk_gt_u32 s25, 0x85
	v_cvt_f32_f16_sdwa v19, v44 dst_sel:DWORD dst_unused:UNUSED_PAD src0_sel:WORD_1
	v_cvt_f32_f16_e32 v18, v44
	v_pk_mul_f32 v[16:17], v[16:17], v[34:35] op_sel:[0,1]
	v_pk_mul_f32 v[68:69], v[68:69], v[66:67]
	v_pk_mul_f32 v[66:67], v[50:51], v[20:21]
	v_cvt_f32_f16_sdwa v21, v45 dst_sel:DWORD dst_unused:UNUSED_PAD src0_sel:WORD_1
	v_cvt_f32_f16_e32 v20, v45
	s_cselect_b64 s[20:21], -1, 0
	v_pk_mul_f32 v[24:25], v[16:17], v[24:25]
	v_pk_mul_f32 v[22:23], v[14:15], v[22:23]
	ds_write_b128 v55, v[10:13] offset:47104
	ds_write_b128 v55, v[14:17] offset:55296
	s_waitcnt vmcnt(0)
	v_cvt_f32_f16_sdwa v11, v65 dst_sel:DWORD dst_unused:UNUSED_PAD src0_sel:WORD_1
	v_cvt_f32_f16_e32 v10, v65
	s_and_b64 vcc, exec, s[20:21]
	ds_write_b128 v55, v[22:25] offset:63488
	ds_write_b128 v59, v[66:69] offset:4096
	ds_write_b128 v60, v[18:21] offset:4096
	ds_write2_b32 v61, v10, v11 offset1:32
	s_cbranch_vccnz .LBB0_1320
	s_lshl_b32 s2, s25, 5
	s_add_i32 s2, s2, 64
	s_and_b64 vcc, exec, s[6:7]
	v_add_u32_e32 v10, s2, v52
	s_cbranch_vccnz .LBB0_1309
	v_add3_u32 v11, v52, s24, 64
	v_cmp_lt_u32_e32 vcc, s29, v11
	s_and_saveexec_b64 s[22:23], vcc
	s_xor_b64 s[22:23], exec, s[22:23]
	v_add_u32_e32 v10, 0xffffffa0, v62
	s_andn2_saveexec_b64 s[22:23], s[22:23]
	v_sub_u32_e32 v10, 0xff, v10
	s_or_b64 exec, exec, s[22:23]

; __device__ __forceinline__ void phase_rwc(const int wvs, const Params& p, LAS unsigned char* lds, int layer, int wg0) {
;     ...
;     RW_LOAD(0) RW_DERIVE(0) RW_LOAD(1)
;     __syncthreads();
; #pragma unroll 2
;     for (int blk = 0; blk < NBLK; ++blk) {
;       if (blk + 1 < NBLK) RW_DERIVE((blk + 1) & 1)
;       if (blk + 2 < NBLK) RW_LOAD(blk + 2)
;       if (blk >= 1) RW_YOUT(blk - 1)
;       __syncthreads();
.LBB0_1330:
	s_cmpk_eq_i32 s24, 0x10c0
	s_waitcnt lgkmcnt(0)
	s_barrier
	s_cbranch_scc1 .LBB0_1332
	s_waitcnt vmcnt(10)
	v_cvt_f32_f16_sdwa v21, v28 dst_sel:DWORD dst_unused:UNUSED_PAD src0_sel:WORD_1
	v_cvt_f32_f16_e32 v20, v28
	s_waitcnt vmcnt(7)
	v_cvt_f32_f16_sdwa v51, v36 dst_sel:DWORD dst_unused:UNUSED_PAD src0_sel:WORD_1
	v_cvt_f32_f16_e32 v50, v36
	v_cvt_f32_f16_sdwa v71, v37 dst_sel:DWORD dst_unused:UNUSED_PAD src0_sel:WORD_1
	v_pk_mul_f32 v[12:13], v[2:3], v[20:21]
	v_cvt_f32_f16_e32 v70, v37
	v_cvt_f32_f16_e32 v10, v32
	v_cvt_f32_f16_sdwa v11, v32 dst_sel:DWORD dst_unused:UNUSED_PAD src0_sel:WORD_1
	s_waitcnt vmcnt(1)
	v_pk_mul_f32 v[14:15], v[12:13], v[34:35] op_sel_hi:[1,0]
	v_cvt_f32_f16_e32 v12, v33
	v_cvt_f32_f16_sdwa v13, v33 dst_sel:DWORD dst_unused:UNUSED_PAD src0_sel:WORD_1
	v_cvt_f32_f16_sdwa v69, v29 dst_sel:DWORD dst_unused:UNUSED_PAD src0_sel:WORD_1
	v_cvt_f32_f16_e32 v68, v29
	v_xor_b32_e32 v22, 0x80000000, v50
	v_xor_b32_e32 v23, 0x80000000, v51
	v_xor_b32_e32 v24, 0x80000000, v70
	v_xor_b32_e32 v25, 0x80000000, v71
	v_pk_add_f32 v[50:51], v[50:51], -1.0 op_sel_hi:[1,0]
	v_pk_add_f32 v[70:71], v[70:71], -1.0 op_sel_hi:[1,0]
	v_mul_f32_e32 v10, 0xbfb8aa3b, v10
	v_mul_f32_e32 v11, 0xbfb8aa3b, v11
	v_mul_f32_e32 v12, 0xbfb8aa3b, v12
	v_mul_f32_e32 v13, 0xbfb8aa3b, v13
	v_pk_fma_f32 v[70:71], v[8:9], v[70:71], 1.0 op_sel_hi:[1,1,0]
	v_pk_fma_f32 v[50:51], v[6:7], v[50:51], 1.0 op_sel_hi:[1,1,0]
	v_exp_f32_e32 v10, v10
	v_exp_f32_e32 v11, v11
	v_cvt_f32_f16_sdwa v19, v30 dst_sel:DWORD dst_unused:UNUSED_PAD src0_sel:WORD_1
	v_cvt_f32_f16_e32 v18, v30
	v_exp_f32_e32 v12, v12
	v_exp_f32_e32 v13, v13
	v_pk_mul_f32 v[16:17], v[4:5], v[68:69]
	v_pk_mul_f32 v[70:71], v[70:71], v[68:69]
	v_pk_mul_f32 v[68:69], v[50:51], v[20:21]
	v_cvt_f32_f16_sdwa v21, v31 dst_sel:DWORD dst_unused:UNUSED_PAD src0_sel:WORD_1
	v_cvt_f32_f16_e32 v20, v31
	v_pk_mul_f32 v[16:17], v[16:17], v[34:35] op_sel_hi:[1,0]
	v_pk_mul_f32 v[22:23], v[14:15], v[22:23]
	v_pk_mul_f32 v[24:25], v[16:17], v[24:25]
	ds_write_b128 v55, v[10:13]
	ds_write_b128 v55, v[14:17] offset:8192
	ds_write_b128 v55, v[22:25] offset:16384
	ds_write_b128 v55, v[18:21] offset:32768
	v_cvt_f32_f16_sdwa v21, v42 dst_sel:DWORD dst_unused:UNUSED_PAD src0_sel:WORD_1
	v_cvt_f32_f16_e32 v20, v42
	v_cvt_f32_f16_e32 v10, v46
	v_cvt_f32_f16_sdwa v11, v46 dst_sel:DWORD dst_unused:UNUSED_PAD src0_sel:WORD_1
	ds_write_b128 v55, v[68:71] offset:24576
	v_pk_mul_f32 v[12:13], v[2:3], v[20:21]
	v_cvt_f32_f16_sdwa v51, v48 dst_sel:DWORD dst_unused:UNUSED_PAD src0_sel:WORD_1
	v_pk_mul_f32 v[14:15], v[12:13], v[34:35] op_sel:[0,1]
	v_cvt_f32_f16_e32 v12, v47
	v_cvt_f32_f16_sdwa v13, v47 dst_sel:DWORD dst_unused:UNUSED_PAD src0_sel:WORD_1
	v_cvt_f32_f16_e32 v50, v48
	v_cvt_f32_f16_sdwa v71, v49 dst_sel:DWORD dst_unused:UNUSED_PAD src0_sel:WORD_1
	v_cvt_f32_f16_e32 v70, v49
	v_cvt_f32_f16_sdwa v69, v43 dst_sel:DWORD dst_unused:UNUSED_PAD src0_sel:WORD_1
	v_cvt_f32_f16_e32 v68, v43
	v_mul_f32_e32 v10, 0xbfb8aa3b, v10
	v_mul_f32_e32 v11, 0xbfb8aa3b, v11
	v_mul_f32_e32 v12, 0xbfb8aa3b, v12
	v_mul_f32_e32 v13, 0xbfb8aa3b, v13
	v_exp_f32_e32 v10, v10
	v_exp_f32_e32 v11, v11
	v_exp_f32_e32 v12, v12
	v_exp_f32_e32 v13, v13
	v_xor_b32_e32 v22, 0x80000000, v50
	v_xor_b32_e32 v23, 0x80000000, v51
	v_xor_b32_e32 v24, 0x80000000, v70
	v_xor_b32_e32 v25, 0x80000000, v71
	v_pk_add_f32 v[50:51], v[50:51], -1.0 op_sel_hi:[1,0]
	v_pk_add_f32 v[70:71], v[70:71], -1.0 op_sel_hi:[1,0]
	v_pk_mul_f32 v[16:17], v[4:5], v[68:69]
	v_pk_fma_f32 v[70:71], v[8:9], v[70:71], 1.0 op_sel_hi:[1,1,0]
	v_pk_fma_f32 v[50:51], v[6:7], v[50:51], 1.0 op_sel_hi:[1,1,0]
	v_cvt_f32_f16_sdwa v19, v44 dst_sel:DWORD dst_unused:UNUSED_PAD src0_sel:WORD_1
	v_cvt_f32_f16_e32 v18, v44
	v_pk_mul_f32 v[16:17], v[16:17], v[34:35] op_sel:[0,1]
	v_pk_mul_f32 v[70:71], v[70:71], v[68:69]
	v_pk_mul_f32 v[68:69], v[50:51], v[20:21]
	v_cvt_f32_f16_sdwa v21, v45 dst_sel:DWORD dst_unused:UNUSED_PAD src0_sel:WORD_1
	v_cvt_f32_f16_e32 v20, v45
	v_pk_mul_f32 v[24:25], v[16:17], v[24:25]
	v_pk_mul_f32 v[22:23], v[14:15], v[22:23]
	ds_write_b128 v55, v[10:13] offset:4096
	ds_write_b128 v55, v[14:17] offset:12288
	s_waitcnt vmcnt(0)
	v_cvt_f32_f16_sdwa v11, v65 dst_sel:DWORD dst_unused:UNUSED_PAD src0_sel:WORD_1
	v_cvt_f32_f16_e32 v10, v65
	ds_write_b128 v55, v[22:25] offset:20480
	ds_write_b128 v55, v[68:71] offset:28672
	ds_write_b128 v55, v[18:21] offset:36864
	ds_write2_b32 v56, v10, v11 offset1:32
